# indexer pass 0 rewritten by hand: per half tile both 16-key blocks share each q-fragment read (half the LDS q traffic), relu+fmac straight into key registers, 2-op sortable key, K fragments prefetched
# speedup vs baseline: 1.0143x; 1.0138x over previous
; #define LAS __attribute__((address_space(3)))
; __device__ __forceinline__ void sel_unit(LAS char* lds, int b, int u, const bf16_t* QI, const bf16_t* KIDX, const float* WIDX, unsigned long long* MASK) {
;     ...
;     __syncthreads();
;     const int nj = (c - wid + 8) >> 3;
;     u32x4 sc[8][4];
; #pragma unroll
;     for (int j = 0; j < 8; ++j) {
;         if (j < nj) {
;             int t = wid + 8 * j; asm volatile("" : "+s"(t));
; #pragma unroll
;             for (int kh = 0; kh < 2; ++kh) {
;             bf16x8 kf[2][2];
; #pragma unroll
;             for (int kb = 0; kb < 2; ++kb)
; #pragma unroll
;                 for (int ks = 0; ks < 2; ++ks) kf[kb][ks] = *(const bf16x8*)(KIDX + (rowbase + 64 * t + 32 * kh + 16 * kb + q16) * 64 + 32 * ks + 8 * kg);
; #pragma unroll
;             for (int kb = 0; kb < 2; ++kb) {
;                 f32x4 s = (f32x4){0.f, 0.f, 0.f, 0.f};
; #pragma unroll
;                 for (int hh = 0; hh < 8; ++hh) {
;                     f32x4 a = (f32x4){0.f, 0.f, 0.f, 0.f};
; #pragma unroll
;                     for (int ks = 0; ks < 2; ++ks) {
;                         const bf16x8 qv = *(const LAS bf16x8*)(lds + L_QI + q16 * 1024 + (((hh * 8 + 4 * ks + kg) ^ q16) << 4));
;                         a = __builtin_amdgcn_mfma_f32_16x16x32_bf16(kf[kb][ks], qv, a, 0, 0, 0);
;                     }
;                     const float wh = wl[hh * 16];
; #pragma unroll
;                     for (int i = 0; i < 4; ++i) s[i] += wh * fmaxf(a[i], 0.f);
;                 }
.LBB0_656:
	s_or_b64 exec, exec, s[2:3]
	s_ashr_i32 s46, s47, 6
	s_sub_i32 s2, s34, s46
	s_add_i32 s2, s2, 8
	s_ashr_i32 s4, s2, 3
	v_bfe_u32 v2, v2, 4, 2
	v_lshl_add_u32 v60, v59, 2, 0
	v_or_b32_e32 v18, s0, v59
	s_movk_i32 s0, 0x3fc
	s_cmp_gt_i32 s4, 0
	v_lshlrev_b32_e32 v0, 4, v2
	v_mad_u32_u24 v150, v59, s0, v60
	s_movk_i32 s0, 0xfc04
	s_cselect_b64 s[22:23], -1, 0
	v_mov_b32_e32 v19, s1
	v_lshl_add_u64 v[20:21], s[62:63], 0, v[0:1]
	v_mad_i32_i24 v0, v59, s0, v150
	s_and_b64 vcc, exec, s[22:23]
	v_xor_b32_e32 v182, v2, v59
	v_bitop3_b32 v183, v2, v59, 4 bitop3:0x36
	v_add_u32_e32 v137, 0x8800, v60
	v_bitop3_b32 v184, v2, v59, 8 bitop3:0x36
	v_bitop3_b32 v185, v2, v59, 12 bitop3:0x36
	v_bitop3_b32 v179, v2, v59, 16 bitop3:0x36
	v_bitop3_b32 v180, v2, v59, 20 bitop3:0x36
	v_bitop3_b32 v176, v2, v59, 24 bitop3:0x36
	v_bitop3_b32 v159, v2, v59, 28 bitop3:0x36
	v_bitop3_b32 v158, v2, v59, 32 bitop3:0x36
	v_bitop3_b32 v157, v2, v59, 36 bitop3:0x36
	v_bitop3_b32 v156, v2, v59, 40 bitop3:0x36
	v_bitop3_b32 v155, v2, v59, 44 bitop3:0x36
	v_bitop3_b32 v154, v2, v59, 48 bitop3:0x36
	v_bitop3_b32 v153, v2, v59, 52 bitop3:0x36
	v_bitop3_b32 v152, v2, v59, 56 bitop3:0x36
	v_bitop3_b32 v151, v2, v59, 60 bitop3:0x36
	v_lshl_add_u32 v182, v182, 4, v150
	v_lshl_add_u32 v183, v183, 4, v150
	v_lshl_add_u32 v184, v184, 4, v150
	v_lshl_add_u32 v185, v185, 4, v150
	v_lshl_add_u32 v179, v179, 4, v150
	v_lshl_add_u32 v180, v180, 4, v150
	v_lshl_add_u32 v176, v176, 4, v150
	v_lshl_add_u32 v159, v159, 4, v150
	v_lshl_add_u32 v158, v158, 4, v150
	v_lshl_add_u32 v157, v157, 4, v150
	v_lshl_add_u32 v156, v156, 4, v150
	v_lshl_add_u32 v155, v155, 4, v150
	v_lshl_add_u32 v154, v154, 4, v150
	v_lshl_add_u32 v153, v153, 4, v150
	v_lshl_add_u32 v152, v152, 4, v150
	v_lshl_add_u32 v151, v151, 4, v150
	s_waitcnt lgkmcnt(0)
	s_barrier
	s_cbranch_vccz .LBB0_658
	s_mov_b32 s0, s46
	s_lshl_b32 s0, s0, 6
	s_ashr_i32 s1, s0, 31
	v_lshl_add_u64 v[2:3], v[18:19], 0, s[0:1]
	v_lshlrev_b64 v[2:3], 7, v[2:3]
	v_lshl_add_u64 v[22:23], v[20:21], 0, v[2:3]
	v_bfrev_b32_e32 v8, 1
	global_load_dwordx4 v[26:29], v[22:23], off
	global_load_dwordx4 v[30:33], v[22:23], off offset:64
	global_load_dwordx4 v[34:37], v[22:23], off offset:2048
	global_load_dwordx4 v[38:41], v[22:23], off offset:2112
	ds_read_b128 v[230:233], v182
	ds_read_b128 v[234:237], v183
	ds_read_b32 v6, v137 offset:320
	s_waitcnt vmcnt(0)
	v_add_co_u32_e32 v22, vcc, s96, v22
	s_nop 1
	v_addc_co_u32_e32 v23, vcc, 0, v23, vcc
	global_load_dwordx4 v[42:45], v[22:23], off
	global_load_dwordx4 v[46:49], v[22:23], off offset:64
	global_load_dwordx4 v[50:53], v[22:23], off offset:2048
	global_load_dwordx4 v[2:5], v[22:23], off offset:2112
	s_waitcnt lgkmcnt(1)
	v_mfma_f32_16x16x32_bf16 v[246:249], v[26:29], v[230:233], 0
	v_mfma_f32_16x16x32_bf16 v[250:253], v[34:37], v[230:233], 0
	v_mfma_f32_16x16x32_bf16 v[246:249], v[30:33], v[234:237], v[246:249]
	v_mfma_f32_16x16x32_bf16 v[250:253], v[38:41], v[234:237], v[250:253]
	ds_read_b128 v[238:241], v184
	ds_read_b128 v[242:245], v185
	ds_read_b32 v7, v137 offset:384
	s_waitcnt lgkmcnt(1)
	v_mfma_f32_16x16x32_bf16 v[206:209], v[26:29], v[238:241], 0
	v_mfma_f32_16x16x32_bf16 v[210:213], v[34:37], v[238:241], 0
	v_mfma_f32_16x16x32_bf16 v[206:209], v[30:33], v[242:245], v[206:209]
	v_mfma_f32_16x16x32_bf16 v[210:213], v[38:41], v[242:245], v[210:213]
	ds_read_b128 v[230:233], v179
	ds_read_b128 v[234:237], v180
	ds_read_b32 v217, v137 offset:448
	v_max_f32_e32 v9, 0, v246
	v_max_f32_e32 v200, 0, v247
	v_max_f32_e32 v201, 0, v248
	v_max_f32_e32 v216, 0, v249
	v_mul_f32_e32 v62, v6, v9
	v_mul_f32_e32 v61, v6, v200
	v_mul_f32_e32 v64, v6, v201
	v_mul_f32_e32 v63, v6, v216
	v_max_f32_e32 v9, 0, v250
	v_max_f32_e32 v200, 0, v251
	v_max_f32_e32 v201, 0, v252
	v_max_f32_e32 v216, 0, v253
	v_mul_f32_e32 v66, v6, v9
	v_mul_f32_e32 v65, v6, v200
	v_mul_f32_e32 v68, v6, v201
	v_mul_f32_e32 v67, v6, v216
	s_waitcnt lgkmcnt(1)
	v_mfma_f32_16x16x32_bf16 v[246:249], v[26:29], v[230:233], 0
	v_mfma_f32_16x16x32_bf16 v[250:253], v[34:37], v[230:233], 0
	v_mfma_f32_16x16x32_bf16 v[246:249], v[30:33], v[234:237], v[246:249]
	v_mfma_f32_16x16x32_bf16 v[250:253], v[38:41], v[234:237], v[250:253]
	ds_read_b128 v[238:241], v176
	ds_read_b128 v[242:245], v159
	ds_read_b32 v6, v137 offset:512
	v_max_f32_e32 v9, 0, v206
	v_max_f32_e32 v200, 0, v207
	v_max_f32_e32 v201, 0, v208
	v_max_f32_e32 v216, 0, v209
	v_fmac_f32_e32 v62, v7, v9
	v_fmac_f32_e32 v61, v7, v200
	v_fmac_f32_e32 v64, v7, v201
	v_fmac_f32_e32 v63, v7, v216
	v_max_f32_e32 v9, 0, v210
	v_max_f32_e32 v200, 0, v211
	v_max_f32_e32 v201, 0, v212
	v_max_f32_e32 v216, 0, v213
	v_fmac_f32_e32 v66, v7, v9
	v_fmac_f32_e32 v65, v7, v200
	v_fmac_f32_e32 v68, v7, v201
	v_fmac_f32_e32 v67, v7, v216
	s_waitcnt lgkmcnt(1)
	v_mfma_f32_16x16x32_bf16 v[206:209], v[26:29], v[238:241], 0
	v_mfma_f32_16x16x32_bf16 v[210:213], v[34:37], v[238:241], 0
	v_mfma_f32_16x16x32_bf16 v[206:209], v[30:33], v[242:245], v[206:209]
	v_mfma_f32_16x16x32_bf16 v[210:213], v[38:41], v[242:245], v[210:213]
	ds_read_b128 v[230:233], v158
	ds_read_b128 v[234:237], v157
	ds_read_b32 v7, v137 offset:576
	v_max_f32_e32 v9, 0, v246
	v_max_f32_e32 v200, 0, v247
	v_max_f32_e32 v201, 0, v248
	v_max_f32_e32 v216, 0, v249
	v_fmac_f32_e32 v62, v217, v9
	v_fmac_f32_e32 v61, v217, v200
	v_fmac_f32_e32 v64, v217, v201
	v_fmac_f32_e32 v63, v217, v216
	v_max_f32_e32 v9, 0, v250
	v_max_f32_e32 v200, 0, v251
	v_max_f32_e32 v201, 0, v252
	v_max_f32_e32 v216, 0, v253
	v_fmac_f32_e32 v66, v217, v9
	v_fmac_f32_e32 v65, v217, v200
	v_fmac_f32_e32 v68, v217, v201
	v_fmac_f32_e32 v67, v217, v216
	s_waitcnt lgkmcnt(1)
; #define LAS __attribute__((address_space(3)))
; #define SEL_HADD(idx_) __hip_atomic_fetch_add(&hist[(idx_)], 1u, __ATOMIC_RELAXED, __HIP_MEMORY_SCOPE_WORKGROUP)
; __device__ __forceinline__ unsigned fkey(float f) { const unsigned u = __float_as_uint(f); return (u & 0x80000000u) ? ~u : (u | 0x80000000u); }
; __device__ __forceinline__ void sel_unit(LAS char* lds, int b, int u, const bf16_t* QI, const bf16_t* KIDX, const float* WIDX, unsigned long long* MASK) {
;     ...
;             for (int kb = 0; kb < 2; ++kb) {
;                 f32x4 s = (f32x4){0.f, 0.f, 0.f, 0.f};
; #pragma unroll
;                 for (int hh = 0; hh < 8; ++hh) {
;                     f32x4 a = (f32x4){0.f, 0.f, 0.f, 0.f};
; #pragma unroll
;                     for (int ks = 0; ks < 2; ++ks) {
;                         const bf16x8 qv = *(const LAS bf16x8*)(lds + L_QI + q16 * 1024 + (((hh * 8 + 4 * ks + kg) ^ q16) << 4));
;                         a = __builtin_amdgcn_mfma_f32_16x16x32_bf16(kf[kb][ks], qv, a, 0, 0, 0);
;                     }
;                     const float wh = wl[hh * 16];
; #pragma unroll
;                     for (int i = 0; i < 4; ++i) s[i] += wh * fmaxf(a[i], 0.f);
;                 }
;                 u32x4 kk; kk.x = fkey(s[0]); kk.y = fkey(s[1]); kk.z = fkey(s[2]); kk.w = fkey(s[3]);
;                 sc[j][2 * kh + kb] = kk;
; #pragma unroll
;                 for (int i = 0; i < 4; ++i) SEL_HADD((kk[i] >> 24) * 16 + q16);
;                 __builtin_amdgcn_sched_barrier(0);
	v_mfma_f32_16x16x32_bf16 v[246:249], v[26:29], v[230:233], 0
	v_mfma_f32_16x16x32_bf16 v[250:253], v[34:37], v[230:233], 0
	v_mfma_f32_16x16x32_bf16 v[246:249], v[30:33], v[234:237], v[246:249]
	v_mfma_f32_16x16x32_bf16 v[250:253], v[38:41], v[234:237], v[250:253]
	ds_read_b128 v[238:241], v156
	ds_read_b128 v[242:245], v155
	ds_read_b32 v217, v137 offset:640
	v_max_f32_e32 v9, 0, v206
	v_max_f32_e32 v200, 0, v207
	v_max_f32_e32 v201, 0, v208
	v_max_f32_e32 v216, 0, v209
	v_fmac_f32_e32 v62, v6, v9
	v_fmac_f32_e32 v61, v6, v200
	v_fmac_f32_e32 v64, v6, v201
	v_fmac_f32_e32 v63, v6, v216
	v_max_f32_e32 v9, 0, v210
	v_max_f32_e32 v200, 0, v211
	v_max_f32_e32 v201, 0, v212
	v_max_f32_e32 v216, 0, v213
	v_fmac_f32_e32 v66, v6, v9
	v_fmac_f32_e32 v65, v6, v200
	v_fmac_f32_e32 v68, v6, v201
	v_fmac_f32_e32 v67, v6, v216
	s_waitcnt lgkmcnt(1)
	v_mfma_f32_16x16x32_bf16 v[206:209], v[26:29], v[238:241], 0
	v_mfma_f32_16x16x32_bf16 v[210:213], v[34:37], v[238:241], 0
	v_mfma_f32_16x16x32_bf16 v[206:209], v[30:33], v[242:245], v[206:209]
	v_mfma_f32_16x16x32_bf16 v[210:213], v[38:41], v[242:245], v[210:213]
	ds_read_b128 v[230:233], v154
	ds_read_b128 v[234:237], v153
	ds_read_b32 v6, v137 offset:704
	v_max_f32_e32 v9, 0, v246
	v_max_f32_e32 v200, 0, v247
	v_max_f32_e32 v201, 0, v248
	v_max_f32_e32 v216, 0, v249
	v_fmac_f32_e32 v62, v7, v9
	v_fmac_f32_e32 v61, v7, v200
	v_fmac_f32_e32 v64, v7, v201
	v_fmac_f32_e32 v63, v7, v216
	v_max_f32_e32 v9, 0, v250
	v_max_f32_e32 v200, 0, v251
	v_max_f32_e32 v201, 0, v252
	v_max_f32_e32 v216, 0, v253
	v_fmac_f32_e32 v66, v7, v9
	v_fmac_f32_e32 v65, v7, v200
	v_fmac_f32_e32 v68, v7, v201
	v_fmac_f32_e32 v67, v7, v216
	s_waitcnt lgkmcnt(1)
	v_mfma_f32_16x16x32_bf16 v[246:249], v[26:29], v[230:233], 0
	v_mfma_f32_16x16x32_bf16 v[250:253], v[34:37], v[230:233], 0
	v_mfma_f32_16x16x32_bf16 v[246:249], v[30:33], v[234:237], v[246:249]
	v_mfma_f32_16x16x32_bf16 v[250:253], v[38:41], v[234:237], v[250:253]
	ds_read_b128 v[238:241], v152
	ds_read_b128 v[242:245], v151
	ds_read_b32 v7, v137 offset:768
	v_max_f32_e32 v9, 0, v206
	v_max_f32_e32 v200, 0, v207
	v_max_f32_e32 v201, 0, v208
	v_max_f32_e32 v216, 0, v209
	v_fmac_f32_e32 v62, v217, v9
	v_fmac_f32_e32 v61, v217, v200
	v_fmac_f32_e32 v64, v217, v201
	v_fmac_f32_e32 v63, v217, v216
	v_max_f32_e32 v9, 0, v210
	v_max_f32_e32 v200, 0, v211
	v_max_f32_e32 v201, 0, v212
	v_max_f32_e32 v216, 0, v213
	v_fmac_f32_e32 v66, v217, v9
	v_fmac_f32_e32 v65, v217, v200
	v_fmac_f32_e32 v68, v217, v201
	v_fmac_f32_e32 v67, v217, v216
	s_waitcnt lgkmcnt(1)
	v_mfma_f32_16x16x32_bf16 v[206:209], v[26:29], v[238:241], 0
	v_mfma_f32_16x16x32_bf16 v[210:213], v[34:37], v[238:241], 0
	v_mfma_f32_16x16x32_bf16 v[206:209], v[30:33], v[242:245], v[206:209]
	v_mfma_f32_16x16x32_bf16 v[210:213], v[38:41], v[242:245], v[210:213]
	v_max_f32_e32 v9, 0, v246
	v_max_f32_e32 v200, 0, v247
	v_max_f32_e32 v201, 0, v248
	v_max_f32_e32 v216, 0, v249
	v_fmac_f32_e32 v62, v6, v9
	v_fmac_f32_e32 v61, v6, v200
	v_fmac_f32_e32 v64, v6, v201
	v_fmac_f32_e32 v63, v6, v216
	v_max_f32_e32 v9, 0, v250
	v_max_f32_e32 v200, 0, v251
	v_max_f32_e32 v201, 0, v252
	v_max_f32_e32 v216, 0, v253
	v_fmac_f32_e32 v66, v6, v9
	v_fmac_f32_e32 v65, v6, v200
	v_fmac_f32_e32 v68, v6, v201
	v_fmac_f32_e32 v67, v6, v216
	s_waitcnt lgkmcnt(0)
	v_max_f32_e32 v9, 0, v206
	v_max_f32_e32 v200, 0, v207
	v_max_f32_e32 v201, 0, v208
	v_max_f32_e32 v216, 0, v209
	v_fmac_f32_e32 v62, v7, v9
	v_fmac_f32_e32 v61, v7, v200
	v_fmac_f32_e32 v64, v7, v201
	v_fmac_f32_e32 v63, v7, v216
	v_max_f32_e32 v9, 0, v210
	v_max_f32_e32 v200, 0, v211
	v_max_f32_e32 v201, 0, v212
	v_max_f32_e32 v216, 0, v213
	v_fmac_f32_e32 v66, v7, v9
	v_fmac_f32_e32 v65, v7, v200
	v_fmac_f32_e32 v68, v7, v201
	v_fmac_f32_e32 v67, v7, v216
	v_ashrrev_i32_e32 v9, 31, v62
	v_bitop3_b32 v62, v9, v62, v8 bitop3:0x36
	v_ashrrev_i32_e32 v200, 31, v61
	v_bitop3_b32 v61, v200, v61, v8 bitop3:0x36
	v_ashrrev_i32_e32 v201, 31, v64
	v_bitop3_b32 v64, v201, v64, v8 bitop3:0x36
	v_ashrrev_i32_e32 v216, 31, v63
	v_bitop3_b32 v63, v216, v63, v8 bitop3:0x36
	v_ashrrev_i32_e32 v9, 31, v66
	v_bitop3_b32 v66, v9, v66, v8 bitop3:0x36
	v_ashrrev_i32_e32 v200, 31, v65
	v_bitop3_b32 v65, v200, v65, v8 bitop3:0x36
	v_ashrrev_i32_e32 v201, 31, v68
	v_bitop3_b32 v68, v201, v68, v8 bitop3:0x36
	v_ashrrev_i32_e32 v216, 31, v67
	v_bitop3_b32 v67, v216, v67, v8 bitop3:0x36
	v_lshrrev_b32_e32 v9, 24, v62
	v_lshl_add_u32 v9, v9, 6, v0
	ds_add_u32 v9, v205 offset:16384
	v_lshrrev_b32_e32 v200, 24, v61
	v_lshl_add_u32 v200, v200, 6, v0
	ds_add_u32 v200, v205 offset:16384
	v_lshrrev_b32_e32 v201, 24, v64
	v_lshl_add_u32 v201, v201, 6, v0
	ds_add_u32 v201, v205 offset:16384
	v_lshrrev_b32_e32 v216, 24, v63
	v_lshl_add_u32 v216, v216, 6, v0
	ds_add_u32 v216, v205 offset:16384
	v_lshrrev_b32_e32 v9, 24, v66
	v_lshl_add_u32 v9, v9, 6, v0
	ds_add_u32 v9, v205 offset:16384
	v_lshrrev_b32_e32 v200, 24, v65
	v_lshl_add_u32 v200, v200, 6, v0
	ds_add_u32 v200, v205 offset:16384
	v_lshrrev_b32_e32 v201, 24, v68
	v_lshl_add_u32 v201, v201, 6, v0
	ds_add_u32 v201, v205 offset:16384
	v_lshrrev_b32_e32 v216, 24, v67
	v_lshl_add_u32 v216, v216, 6, v0
	ds_add_u32 v216, v205 offset:16384
	ds_read_b128 v[230:233], v182
	ds_read_b128 v[234:237], v183
	ds_read_b32 v6, v137 offset:320
	s_waitcnt vmcnt(0)
	s_cmp_lt_i32 s4, 2
	s_cbranch_scc1 .Lp0_nopf_0
	v_add_co_u32_e32 v22, vcc, 0xf000, v22
	s_nop 1
	v_addc_co_u32_e32 v23, vcc, 0, v23, vcc
	global_load_dwordx4 v[26:29], v[22:23], off
	global_load_dwordx4 v[30:33], v[22:23], off offset:64
	global_load_dwordx4 v[34:37], v[22:23], off offset:2048
	global_load_dwordx4 v[38:41], v[22:23], off offset:2112
; #define LAS __attribute__((address_space(3)))
; __device__ __forceinline__ void sel_unit(LAS char* lds, int b, int u, const bf16_t* QI, const bf16_t* KIDX, const float* WIDX, unsigned long long* MASK) {
;     ...
;             for (int kb = 0; kb < 2; ++kb) {
;                 f32x4 s = (f32x4){0.f, 0.f, 0.f, 0.f};
; #pragma unroll
;                 for (int hh = 0; hh < 8; ++hh) {
;                     f32x4 a = (f32x4){0.f, 0.f, 0.f, 0.f};
; #pragma unroll
;                     for (int ks = 0; ks < 2; ++ks) {
;                         const bf16x8 qv = *(const LAS bf16x8*)(lds + L_QI + q16 * 1024 + (((hh * 8 + 4 * ks + kg) ^ q16) << 4));
;                         a = __builtin_amdgcn_mfma_f32_16x16x32_bf16(kf[kb][ks], qv, a, 0, 0, 0);
;                     }
;                     const float wh = wl[hh * 16];
; #pragma unroll
;                     for (int i = 0; i < 4; ++i) s[i] += wh * fmaxf(a[i], 0.f);
;                 }
.Lp0_nopf_0:
	s_waitcnt lgkmcnt(1)
	v_mfma_f32_16x16x32_bf16 v[246:249], v[42:45], v[230:233], 0
	v_mfma_f32_16x16x32_bf16 v[250:253], v[50:53], v[230:233], 0
	v_mfma_f32_16x16x32_bf16 v[246:249], v[46:49], v[234:237], v[246:249]
	v_mfma_f32_16x16x32_bf16 v[250:253], v[2:5], v[234:237], v[250:253]
	ds_read_b128 v[238:241], v184
	ds_read_b128 v[242:245], v185
	ds_read_b32 v7, v137 offset:384
	s_waitcnt lgkmcnt(1)
	v_mfma_f32_16x16x32_bf16 v[206:209], v[42:45], v[238:241], 0
	v_mfma_f32_16x16x32_bf16 v[210:213], v[50:53], v[238:241], 0
	v_mfma_f32_16x16x32_bf16 v[206:209], v[46:49], v[242:245], v[206:209]
	v_mfma_f32_16x16x32_bf16 v[210:213], v[2:5], v[242:245], v[210:213]
	ds_read_b128 v[230:233], v179
	ds_read_b128 v[234:237], v180
	ds_read_b32 v217, v137 offset:448
	v_max_f32_e32 v9, 0, v246
	v_max_f32_e32 v200, 0, v247
	v_max_f32_e32 v201, 0, v248
	v_max_f32_e32 v216, 0, v249
	v_mul_f32_e32 v70, v6, v9
	v_mul_f32_e32 v69, v6, v200
	v_mul_f32_e32 v72, v6, v201
	v_mul_f32_e32 v71, v6, v216
	v_max_f32_e32 v9, 0, v250
	v_max_f32_e32 v200, 0, v251
	v_max_f32_e32 v201, 0, v252
	v_max_f32_e32 v216, 0, v253
	v_mul_f32_e32 v74, v6, v9
	v_mul_f32_e32 v73, v6, v200
	v_mul_f32_e32 v76, v6, v201
	v_mul_f32_e32 v75, v6, v216
	s_waitcnt lgkmcnt(1)
	v_mfma_f32_16x16x32_bf16 v[246:249], v[42:45], v[230:233], 0
	v_mfma_f32_16x16x32_bf16 v[250:253], v[50:53], v[230:233], 0
	v_mfma_f32_16x16x32_bf16 v[246:249], v[46:49], v[234:237], v[246:249]
	v_mfma_f32_16x16x32_bf16 v[250:253], v[2:5], v[234:237], v[250:253]
	ds_read_b128 v[238:241], v176
	ds_read_b128 v[242:245], v159
	ds_read_b32 v6, v137 offset:512
	v_max_f32_e32 v9, 0, v206
	v_max_f32_e32 v200, 0, v207
	v_max_f32_e32 v201, 0, v208
	v_max_f32_e32 v216, 0, v209
	v_fmac_f32_e32 v70, v7, v9
	v_fmac_f32_e32 v69, v7, v200
	v_fmac_f32_e32 v72, v7, v201
	v_fmac_f32_e32 v71, v7, v216
	v_max_f32_e32 v9, 0, v210
	v_max_f32_e32 v200, 0, v211
	v_max_f32_e32 v201, 0, v212
	v_max_f32_e32 v216, 0, v213
	v_fmac_f32_e32 v74, v7, v9
	v_fmac_f32_e32 v73, v7, v200
	v_fmac_f32_e32 v76, v7, v201
	v_fmac_f32_e32 v75, v7, v216
	s_waitcnt lgkmcnt(1)
	v_mfma_f32_16x16x32_bf16 v[206:209], v[42:45], v[238:241], 0
	v_mfma_f32_16x16x32_bf16 v[210:213], v[50:53], v[238:241], 0
	v_mfma_f32_16x16x32_bf16 v[206:209], v[46:49], v[242:245], v[206:209]
	v_mfma_f32_16x16x32_bf16 v[210:213], v[2:5], v[242:245], v[210:213]
	ds_read_b128 v[230:233], v158
	ds_read_b128 v[234:237], v157
	ds_read_b32 v7, v137 offset:576
	v_max_f32_e32 v9, 0, v246
	v_max_f32_e32 v200, 0, v247
	v_max_f32_e32 v201, 0, v248
	v_max_f32_e32 v216, 0, v249
	v_fmac_f32_e32 v70, v217, v9
	v_fmac_f32_e32 v69, v217, v200
	v_fmac_f32_e32 v72, v217, v201
	v_fmac_f32_e32 v71, v217, v216
	v_max_f32_e32 v9, 0, v250
	v_max_f32_e32 v200, 0, v251
	v_max_f32_e32 v201, 0, v252
	v_max_f32_e32 v216, 0, v253
	v_fmac_f32_e32 v74, v217, v9
	v_fmac_f32_e32 v73, v217, v200
	v_fmac_f32_e32 v76, v217, v201
	v_fmac_f32_e32 v75, v217, v216
	s_waitcnt lgkmcnt(1)
	v_mfma_f32_16x16x32_bf16 v[246:249], v[42:45], v[230:233], 0
	v_mfma_f32_16x16x32_bf16 v[250:253], v[50:53], v[230:233], 0
	v_mfma_f32_16x16x32_bf16 v[246:249], v[46:49], v[234:237], v[246:249]
	v_mfma_f32_16x16x32_bf16 v[250:253], v[2:5], v[234:237], v[250:253]
	ds_read_b128 v[238:241], v156
	ds_read_b128 v[242:245], v155
	ds_read_b32 v217, v137 offset:640
	v_max_f32_e32 v9, 0, v206
	v_max_f32_e32 v200, 0, v207
	v_max_f32_e32 v201, 0, v208
	v_max_f32_e32 v216, 0, v209
	v_fmac_f32_e32 v70, v6, v9
	v_fmac_f32_e32 v69, v6, v200
	v_fmac_f32_e32 v72, v6, v201
	v_fmac_f32_e32 v71, v6, v216
	v_max_f32_e32 v9, 0, v210
	v_max_f32_e32 v200, 0, v211
	v_max_f32_e32 v201, 0, v212
	v_max_f32_e32 v216, 0, v213
	v_fmac_f32_e32 v74, v6, v9
	v_fmac_f32_e32 v73, v6, v200
	v_fmac_f32_e32 v76, v6, v201
	v_fmac_f32_e32 v75, v6, v216
	s_waitcnt lgkmcnt(1)
	v_mfma_f32_16x16x32_bf16 v[206:209], v[42:45], v[238:241], 0
	v_mfma_f32_16x16x32_bf16 v[210:213], v[50:53], v[238:241], 0
	v_mfma_f32_16x16x32_bf16 v[206:209], v[46:49], v[242:245], v[206:209]
	v_mfma_f32_16x16x32_bf16 v[210:213], v[2:5], v[242:245], v[210:213]
	ds_read_b128 v[230:233], v154
	ds_read_b128 v[234:237], v153
	ds_read_b32 v6, v137 offset:704
	v_max_f32_e32 v9, 0, v246
	v_max_f32_e32 v200, 0, v247
	v_max_f32_e32 v201, 0, v248
	v_max_f32_e32 v216, 0, v249
	v_fmac_f32_e32 v70, v7, v9
	v_fmac_f32_e32 v69, v7, v200
	v_fmac_f32_e32 v72, v7, v201
	v_fmac_f32_e32 v71, v7, v216
	v_max_f32_e32 v9, 0, v250
	v_max_f32_e32 v200, 0, v251
	v_max_f32_e32 v201, 0, v252
	v_max_f32_e32 v216, 0, v253
	v_fmac_f32_e32 v74, v7, v9
	v_fmac_f32_e32 v73, v7, v200
	v_fmac_f32_e32 v76, v7, v201
	v_fmac_f32_e32 v75, v7, v216
	s_waitcnt lgkmcnt(1)
	v_mfma_f32_16x16x32_bf16 v[246:249], v[42:45], v[230:233], 0
	v_mfma_f32_16x16x32_bf16 v[250:253], v[50:53], v[230:233], 0
	v_mfma_f32_16x16x32_bf16 v[246:249], v[46:49], v[234:237], v[246:249]
	v_mfma_f32_16x16x32_bf16 v[250:253], v[2:5], v[234:237], v[250:253]
	ds_read_b128 v[238:241], v152
	ds_read_b128 v[242:245], v151
	ds_read_b32 v7, v137 offset:768
	v_max_f32_e32 v9, 0, v206
	v_max_f32_e32 v200, 0, v207
	v_max_f32_e32 v201, 0, v208
	v_max_f32_e32 v216, 0, v209
	v_fmac_f32_e32 v70, v217, v9
	v_fmac_f32_e32 v69, v217, v200
	v_fmac_f32_e32 v72, v217, v201
	v_fmac_f32_e32 v71, v217, v216
	v_max_f32_e32 v9, 0, v210
	v_max_f32_e32 v200, 0, v211
	v_max_f32_e32 v201, 0, v212
	v_max_f32_e32 v216, 0, v213
	v_fmac_f32_e32 v74, v217, v9
	v_fmac_f32_e32 v73, v217, v200
	v_fmac_f32_e32 v76, v217, v201
	v_fmac_f32_e32 v75, v217, v216
	s_waitcnt lgkmcnt(1)
; #define LAS __attribute__((address_space(3)))
; #define SEL_HADD(idx_) __hip_atomic_fetch_add(&hist[(idx_)], 1u, __ATOMIC_RELAXED, __HIP_MEMORY_SCOPE_WORKGROUP)
; __device__ __forceinline__ unsigned fkey(float f) { const unsigned u = __float_as_uint(f); return (u & 0x80000000u) ? ~u : (u | 0x80000000u); }
; __device__ __forceinline__ void sel_unit(LAS char* lds, int b, int u, const bf16_t* QI, const bf16_t* KIDX, const float* WIDX, unsigned long long* MASK) {
;     ...
;             for (int kb = 0; kb < 2; ++kb) {
;                 f32x4 s = (f32x4){0.f, 0.f, 0.f, 0.f};
; #pragma unroll
;                 for (int hh = 0; hh < 8; ++hh) {
;                     f32x4 a = (f32x4){0.f, 0.f, 0.f, 0.f};
; #pragma unroll
;                     for (int ks = 0; ks < 2; ++ks) {
;                         const bf16x8 qv = *(const LAS bf16x8*)(lds + L_QI + q16 * 1024 + (((hh * 8 + 4 * ks + kg) ^ q16) << 4));
;                         a = __builtin_amdgcn_mfma_f32_16x16x32_bf16(kf[kb][ks], qv, a, 0, 0, 0);
;                     }
;                     const float wh = wl[hh * 16];
; #pragma unroll
;                     for (int i = 0; i < 4; ++i) s[i] += wh * fmaxf(a[i], 0.f);
;                 }
;                 u32x4 kk; kk.x = fkey(s[0]); kk.y = fkey(s[1]); kk.z = fkey(s[2]); kk.w = fkey(s[3]);
;                 sc[j][2 * kh + kb] = kk;
; #pragma unroll
;                 for (int i = 0; i < 4; ++i) SEL_HADD((kk[i] >> 24) * 16 + q16);
;                 __builtin_amdgcn_sched_barrier(0);
	v_mfma_f32_16x16x32_bf16 v[206:209], v[42:45], v[238:241], 0
	v_mfma_f32_16x16x32_bf16 v[210:213], v[50:53], v[238:241], 0
	v_mfma_f32_16x16x32_bf16 v[206:209], v[46:49], v[242:245], v[206:209]
	v_mfma_f32_16x16x32_bf16 v[210:213], v[2:5], v[242:245], v[210:213]
	v_max_f32_e32 v9, 0, v246
	v_max_f32_e32 v200, 0, v247
	v_max_f32_e32 v201, 0, v248
	v_max_f32_e32 v216, 0, v249
	v_fmac_f32_e32 v70, v6, v9
	v_fmac_f32_e32 v69, v6, v200
	v_fmac_f32_e32 v72, v6, v201
	v_fmac_f32_e32 v71, v6, v216
	v_max_f32_e32 v9, 0, v250
	v_max_f32_e32 v200, 0, v251
	v_max_f32_e32 v201, 0, v252
	v_max_f32_e32 v216, 0, v253
	v_fmac_f32_e32 v74, v6, v9
	v_fmac_f32_e32 v73, v6, v200
	v_fmac_f32_e32 v76, v6, v201
	v_fmac_f32_e32 v75, v6, v216
	s_waitcnt lgkmcnt(0)
	v_max_f32_e32 v9, 0, v206
	v_max_f32_e32 v200, 0, v207
	v_max_f32_e32 v201, 0, v208
	v_max_f32_e32 v216, 0, v209
	v_fmac_f32_e32 v70, v7, v9
	v_fmac_f32_e32 v69, v7, v200
	v_fmac_f32_e32 v72, v7, v201
	v_fmac_f32_e32 v71, v7, v216
	v_max_f32_e32 v9, 0, v210
	v_max_f32_e32 v200, 0, v211
	v_max_f32_e32 v201, 0, v212
	v_max_f32_e32 v216, 0, v213
	v_fmac_f32_e32 v74, v7, v9
	v_fmac_f32_e32 v73, v7, v200
	v_fmac_f32_e32 v76, v7, v201
	v_fmac_f32_e32 v75, v7, v216
	v_ashrrev_i32_e32 v9, 31, v70
	v_bitop3_b32 v70, v9, v70, v8 bitop3:0x36
	v_ashrrev_i32_e32 v200, 31, v69
	v_bitop3_b32 v69, v200, v69, v8 bitop3:0x36
	v_ashrrev_i32_e32 v201, 31, v72
	v_bitop3_b32 v72, v201, v72, v8 bitop3:0x36
	v_ashrrev_i32_e32 v216, 31, v71
	v_bitop3_b32 v71, v216, v71, v8 bitop3:0x36
	v_ashrrev_i32_e32 v9, 31, v74
	v_bitop3_b32 v74, v9, v74, v8 bitop3:0x36
	v_ashrrev_i32_e32 v200, 31, v73
	v_bitop3_b32 v73, v200, v73, v8 bitop3:0x36
	v_ashrrev_i32_e32 v201, 31, v76
	v_bitop3_b32 v76, v201, v76, v8 bitop3:0x36
	v_ashrrev_i32_e32 v216, 31, v75
	v_bitop3_b32 v75, v216, v75, v8 bitop3:0x36
	v_lshrrev_b32_e32 v9, 24, v70
	v_lshl_add_u32 v9, v9, 6, v0
	ds_add_u32 v9, v205 offset:16384
	v_lshrrev_b32_e32 v200, 24, v69
	v_lshl_add_u32 v200, v200, 6, v0
	ds_add_u32 v200, v205 offset:16384
	v_lshrrev_b32_e32 v201, 24, v72
	v_lshl_add_u32 v201, v201, 6, v0
	ds_add_u32 v201, v205 offset:16384
	v_lshrrev_b32_e32 v216, 24, v71
	v_lshl_add_u32 v216, v216, 6, v0
	ds_add_u32 v216, v205 offset:16384
	v_lshrrev_b32_e32 v9, 24, v74
	v_lshl_add_u32 v9, v9, 6, v0
	ds_add_u32 v9, v205 offset:16384
	v_lshrrev_b32_e32 v200, 24, v73
	v_lshl_add_u32 v200, v200, 6, v0
	ds_add_u32 v200, v205 offset:16384
	v_lshrrev_b32_e32 v201, 24, v76
	v_lshl_add_u32 v201, v201, 6, v0
	ds_add_u32 v201, v205 offset:16384
	v_lshrrev_b32_e32 v216, 24, v75
	v_lshl_add_u32 v216, v216, 6, v0
	ds_add_u32 v216, v205 offset:16384
.LBB0_658:
	s_cmp_gt_i32 s4, 1
	s_cselect_b64 s[18:19], -1, 0
	s_cmp_lt_i32 s4, 2
	s_cbranch_scc1 .LBB0_660
	ds_read_b128 v[230:233], v182
	ds_read_b128 v[234:237], v183
	ds_read_b32 v6, v137 offset:320
	s_waitcnt vmcnt(0)
	v_add_co_u32_e32 v22, vcc, s96, v22
	s_nop 1
	v_addc_co_u32_e32 v23, vcc, 0, v23, vcc
	global_load_dwordx4 v[42:45], v[22:23], off
	global_load_dwordx4 v[46:49], v[22:23], off offset:64
	global_load_dwordx4 v[50:53], v[22:23], off offset:2048
	global_load_dwordx4 v[2:5], v[22:23], off offset:2112
	s_waitcnt lgkmcnt(1)
	v_mfma_f32_16x16x32_bf16 v[246:249], v[26:29], v[230:233], 0
	v_mfma_f32_16x16x32_bf16 v[250:253], v[34:37], v[230:233], 0
	v_mfma_f32_16x16x32_bf16 v[246:249], v[30:33], v[234:237], v[246:249]
	v_mfma_f32_16x16x32_bf16 v[250:253], v[38:41], v[234:237], v[250:253]
	ds_read_b128 v[238:241], v184
	ds_read_b128 v[242:245], v185
	ds_read_b32 v7, v137 offset:384
	s_waitcnt lgkmcnt(1)
	v_mfma_f32_16x16x32_bf16 v[206:209], v[26:29], v[238:241], 0
	v_mfma_f32_16x16x32_bf16 v[210:213], v[34:37], v[238:241], 0
	v_mfma_f32_16x16x32_bf16 v[206:209], v[30:33], v[242:245], v[206:209]
	v_mfma_f32_16x16x32_bf16 v[210:213], v[38:41], v[242:245], v[210:213]
	ds_read_b128 v[230:233], v179
	ds_read_b128 v[234:237], v180
	ds_read_b32 v217, v137 offset:448
	v_max_f32_e32 v9, 0, v246
	v_max_f32_e32 v200, 0, v247
	v_max_f32_e32 v201, 0, v248
	v_max_f32_e32 v216, 0, v249
	v_mul_f32_e32 v78, v6, v9
	v_mul_f32_e32 v77, v6, v200
	v_mul_f32_e32 v80, v6, v201
	v_mul_f32_e32 v79, v6, v216
	v_max_f32_e32 v9, 0, v250
	v_max_f32_e32 v200, 0, v251
	v_max_f32_e32 v201, 0, v252
	v_max_f32_e32 v216, 0, v253
	v_mul_f32_e32 v82, v6, v9
	v_mul_f32_e32 v81, v6, v200
	v_mul_f32_e32 v84, v6, v201
	v_mul_f32_e32 v83, v6, v216
	s_waitcnt lgkmcnt(1)
	v_mfma_f32_16x16x32_bf16 v[246:249], v[26:29], v[230:233], 0
	v_mfma_f32_16x16x32_bf16 v[250:253], v[34:37], v[230:233], 0
	v_mfma_f32_16x16x32_bf16 v[246:249], v[30:33], v[234:237], v[246:249]
	v_mfma_f32_16x16x32_bf16 v[250:253], v[38:41], v[234:237], v[250:253]
	ds_read_b128 v[238:241], v176
	ds_read_b128 v[242:245], v159
	ds_read_b32 v6, v137 offset:512
	v_max_f32_e32 v9, 0, v206
	v_max_f32_e32 v200, 0, v207
	v_max_f32_e32 v201, 0, v208
	v_max_f32_e32 v216, 0, v209
	v_fmac_f32_e32 v78, v7, v9
	v_fmac_f32_e32 v77, v7, v200
	v_fmac_f32_e32 v80, v7, v201
	v_fmac_f32_e32 v79, v7, v216
	v_max_f32_e32 v9, 0, v210
	v_max_f32_e32 v200, 0, v211
	v_max_f32_e32 v201, 0, v212
	v_max_f32_e32 v216, 0, v213
	v_fmac_f32_e32 v82, v7, v9
	v_fmac_f32_e32 v81, v7, v200
	v_fmac_f32_e32 v84, v7, v201
	v_fmac_f32_e32 v83, v7, v216
	s_waitcnt lgkmcnt(1)
; #define LAS __attribute__((address_space(3)))
; #define SEL_HADD(idx_) __hip_atomic_fetch_add(&hist[(idx_)], 1u, __ATOMIC_RELAXED, __HIP_MEMORY_SCOPE_WORKGROUP)
; __device__ __forceinline__ unsigned fkey(float f) { const unsigned u = __float_as_uint(f); return (u & 0x80000000u) ? ~u : (u | 0x80000000u); }
; __device__ __forceinline__ void sel_unit(LAS char* lds, int b, int u, const bf16_t* QI, const bf16_t* KIDX, const float* WIDX, unsigned long long* MASK) {
;     ...
;             for (int kb = 0; kb < 2; ++kb) {
;                 f32x4 s = (f32x4){0.f, 0.f, 0.f, 0.f};
; #pragma unroll
;                 for (int hh = 0; hh < 8; ++hh) {
;                     f32x4 a = (f32x4){0.f, 0.f, 0.f, 0.f};
; #pragma unroll
;                     for (int ks = 0; ks < 2; ++ks) {
;                         const bf16x8 qv = *(const LAS bf16x8*)(lds + L_QI + q16 * 1024 + (((hh * 8 + 4 * ks + kg) ^ q16) << 4));
;                         a = __builtin_amdgcn_mfma_f32_16x16x32_bf16(kf[kb][ks], qv, a, 0, 0, 0);
;                     }
;                     const float wh = wl[hh * 16];
; #pragma unroll
;                     for (int i = 0; i < 4; ++i) s[i] += wh * fmaxf(a[i], 0.f);
;                 }
;                 u32x4 kk; kk.x = fkey(s[0]); kk.y = fkey(s[1]); kk.z = fkey(s[2]); kk.w = fkey(s[3]);
;                 sc[j][2 * kh + kb] = kk;
; #pragma unroll
;                 for (int i = 0; i < 4; ++i) SEL_HADD((kk[i] >> 24) * 16 + q16);
;                 __builtin_amdgcn_sched_barrier(0);
	v_mfma_f32_16x16x32_bf16 v[206:209], v[26:29], v[238:241], 0
	v_mfma_f32_16x16x32_bf16 v[210:213], v[34:37], v[238:241], 0
	v_mfma_f32_16x16x32_bf16 v[206:209], v[30:33], v[242:245], v[206:209]
	v_mfma_f32_16x16x32_bf16 v[210:213], v[38:41], v[242:245], v[210:213]
	ds_read_b128 v[230:233], v158
	ds_read_b128 v[234:237], v157
	ds_read_b32 v7, v137 offset:576
	v_max_f32_e32 v9, 0, v246
	v_max_f32_e32 v200, 0, v247
	v_max_f32_e32 v201, 0, v248
	v_max_f32_e32 v216, 0, v249
	v_fmac_f32_e32 v78, v217, v9
	v_fmac_f32_e32 v77, v217, v200
	v_fmac_f32_e32 v80, v217, v201
	v_fmac_f32_e32 v79, v217, v216
	v_max_f32_e32 v9, 0, v250
	v_max_f32_e32 v200, 0, v251
	v_max_f32_e32 v201, 0, v252
	v_max_f32_e32 v216, 0, v253
	v_fmac_f32_e32 v82, v217, v9
	v_fmac_f32_e32 v81, v217, v200
	v_fmac_f32_e32 v84, v217, v201
	v_fmac_f32_e32 v83, v217, v216
	s_waitcnt lgkmcnt(1)
	v_mfma_f32_16x16x32_bf16 v[246:249], v[26:29], v[230:233], 0
	v_mfma_f32_16x16x32_bf16 v[250:253], v[34:37], v[230:233], 0
	v_mfma_f32_16x16x32_bf16 v[246:249], v[30:33], v[234:237], v[246:249]
	v_mfma_f32_16x16x32_bf16 v[250:253], v[38:41], v[234:237], v[250:253]
	ds_read_b128 v[238:241], v156
	ds_read_b128 v[242:245], v155
	ds_read_b32 v217, v137 offset:640
	v_max_f32_e32 v9, 0, v206
	v_max_f32_e32 v200, 0, v207
	v_max_f32_e32 v201, 0, v208
	v_max_f32_e32 v216, 0, v209
	v_fmac_f32_e32 v78, v6, v9
	v_fmac_f32_e32 v77, v6, v200
	v_fmac_f32_e32 v80, v6, v201
	v_fmac_f32_e32 v79, v6, v216
	v_max_f32_e32 v9, 0, v210
	v_max_f32_e32 v200, 0, v211
	v_max_f32_e32 v201, 0, v212
	v_max_f32_e32 v216, 0, v213
	v_fmac_f32_e32 v82, v6, v9
	v_fmac_f32_e32 v81, v6, v200
	v_fmac_f32_e32 v84, v6, v201
	v_fmac_f32_e32 v83, v6, v216
	s_waitcnt lgkmcnt(1)
	v_mfma_f32_16x16x32_bf16 v[206:209], v[26:29], v[238:241], 0
	v_mfma_f32_16x16x32_bf16 v[210:213], v[34:37], v[238:241], 0
	v_mfma_f32_16x16x32_bf16 v[206:209], v[30:33], v[242:245], v[206:209]
	v_mfma_f32_16x16x32_bf16 v[210:213], v[38:41], v[242:245], v[210:213]
	ds_read_b128 v[230:233], v154
	ds_read_b128 v[234:237], v153
	ds_read_b32 v6, v137 offset:704
	v_max_f32_e32 v9, 0, v246
	v_max_f32_e32 v200, 0, v247
	v_max_f32_e32 v201, 0, v248
	v_max_f32_e32 v216, 0, v249
	v_fmac_f32_e32 v78, v7, v9
	v_fmac_f32_e32 v77, v7, v200
	v_fmac_f32_e32 v80, v7, v201
	v_fmac_f32_e32 v79, v7, v216
	v_max_f32_e32 v9, 0, v250
	v_max_f32_e32 v200, 0, v251
	v_max_f32_e32 v201, 0, v252
	v_max_f32_e32 v216, 0, v253
	v_fmac_f32_e32 v82, v7, v9
	v_fmac_f32_e32 v81, v7, v200
	v_fmac_f32_e32 v84, v7, v201
	v_fmac_f32_e32 v83, v7, v216
	s_waitcnt lgkmcnt(1)
	v_mfma_f32_16x16x32_bf16 v[246:249], v[26:29], v[230:233], 0
	v_mfma_f32_16x16x32_bf16 v[250:253], v[34:37], v[230:233], 0
	v_mfma_f32_16x16x32_bf16 v[246:249], v[30:33], v[234:237], v[246:249]
	v_mfma_f32_16x16x32_bf16 v[250:253], v[38:41], v[234:237], v[250:253]
	ds_read_b128 v[238:241], v152
	ds_read_b128 v[242:245], v151
	ds_read_b32 v7, v137 offset:768
	v_max_f32_e32 v9, 0, v206
	v_max_f32_e32 v200, 0, v207
	v_max_f32_e32 v201, 0, v208
	v_max_f32_e32 v216, 0, v209
	v_fmac_f32_e32 v78, v217, v9
	v_fmac_f32_e32 v77, v217, v200
	v_fmac_f32_e32 v80, v217, v201
	v_fmac_f32_e32 v79, v217, v216
	v_max_f32_e32 v9, 0, v210
	v_max_f32_e32 v200, 0, v211
	v_max_f32_e32 v201, 0, v212
	v_max_f32_e32 v216, 0, v213
	v_fmac_f32_e32 v82, v217, v9
	v_fmac_f32_e32 v81, v217, v200
	v_fmac_f32_e32 v84, v217, v201
	v_fmac_f32_e32 v83, v217, v216
	s_waitcnt lgkmcnt(1)
	v_mfma_f32_16x16x32_bf16 v[206:209], v[26:29], v[238:241], 0
	v_mfma_f32_16x16x32_bf16 v[210:213], v[34:37], v[238:241], 0
	v_mfma_f32_16x16x32_bf16 v[206:209], v[30:33], v[242:245], v[206:209]
	v_mfma_f32_16x16x32_bf16 v[210:213], v[38:41], v[242:245], v[210:213]
	v_max_f32_e32 v9, 0, v246
	v_max_f32_e32 v200, 0, v247
	v_max_f32_e32 v201, 0, v248
	v_max_f32_e32 v216, 0, v249
	v_fmac_f32_e32 v78, v6, v9
	v_fmac_f32_e32 v77, v6, v200
	v_fmac_f32_e32 v80, v6, v201
	v_fmac_f32_e32 v79, v6, v216
	v_max_f32_e32 v9, 0, v250
	v_max_f32_e32 v200, 0, v251
	v_max_f32_e32 v201, 0, v252
	v_max_f32_e32 v216, 0, v253
	v_fmac_f32_e32 v82, v6, v9
	v_fmac_f32_e32 v81, v6, v200
	v_fmac_f32_e32 v84, v6, v201
	v_fmac_f32_e32 v83, v6, v216
	s_waitcnt lgkmcnt(0)
	v_max_f32_e32 v9, 0, v206
	v_max_f32_e32 v200, 0, v207
	v_max_f32_e32 v201, 0, v208
	v_max_f32_e32 v216, 0, v209
	v_fmac_f32_e32 v78, v7, v9
	v_fmac_f32_e32 v77, v7, v200
	v_fmac_f32_e32 v80, v7, v201
	v_fmac_f32_e32 v79, v7, v216
	v_max_f32_e32 v9, 0, v210
	v_max_f32_e32 v200, 0, v211
	v_max_f32_e32 v201, 0, v212
	v_max_f32_e32 v216, 0, v213
	v_fmac_f32_e32 v82, v7, v9
	v_fmac_f32_e32 v81, v7, v200
	v_fmac_f32_e32 v84, v7, v201
	v_fmac_f32_e32 v83, v7, v216
	v_ashrrev_i32_e32 v9, 31, v78
	v_bitop3_b32 v78, v9, v78, v8 bitop3:0x36
	v_ashrrev_i32_e32 v200, 31, v77
	v_bitop3_b32 v77, v200, v77, v8 bitop3:0x36
	v_ashrrev_i32_e32 v201, 31, v80
	v_bitop3_b32 v80, v201, v80, v8 bitop3:0x36
	v_ashrrev_i32_e32 v216, 31, v79
	v_bitop3_b32 v79, v216, v79, v8 bitop3:0x36
	v_ashrrev_i32_e32 v9, 31, v82
	v_bitop3_b32 v82, v9, v82, v8 bitop3:0x36
	v_ashrrev_i32_e32 v200, 31, v81
	v_bitop3_b32 v81, v200, v81, v8 bitop3:0x36
	v_ashrrev_i32_e32 v201, 31, v84
	v_bitop3_b32 v84, v201, v84, v8 bitop3:0x36
	v_ashrrev_i32_e32 v216, 31, v83
	v_bitop3_b32 v83, v216, v83, v8 bitop3:0x36
	v_lshrrev_b32_e32 v9, 24, v78
	v_lshl_add_u32 v9, v9, 6, v0
	ds_add_u32 v9, v205 offset:16384
	v_lshrrev_b32_e32 v200, 24, v77
	v_lshl_add_u32 v200, v200, 6, v0
	ds_add_u32 v200, v205 offset:16384
	v_lshrrev_b32_e32 v201, 24, v80
	v_lshl_add_u32 v201, v201, 6, v0
	ds_add_u32 v201, v205 offset:16384
	v_lshrrev_b32_e32 v216, 24, v79
	v_lshl_add_u32 v216, v216, 6, v0
	ds_add_u32 v216, v205 offset:16384
	v_lshrrev_b32_e32 v9, 24, v82
	v_lshl_add_u32 v9, v9, 6, v0
	ds_add_u32 v9, v205 offset:16384
	v_lshrrev_b32_e32 v200, 24, v81
	v_lshl_add_u32 v200, v200, 6, v0
	ds_add_u32 v200, v205 offset:16384
	v_lshrrev_b32_e32 v201, 24, v84
	v_lshl_add_u32 v201, v201, 6, v0
	ds_add_u32 v201, v205 offset:16384
	v_lshrrev_b32_e32 v216, 24, v83
	v_lshl_add_u32 v216, v216, 6, v0
	ds_add_u32 v216, v205 offset:16384
	ds_read_b128 v[230:233], v182
	ds_read_b128 v[234:237], v183
	ds_read_b32 v6, v137 offset:320
	s_waitcnt vmcnt(0)
	s_cmp_lt_i32 s4, 3
	s_cbranch_scc1 .Lp0_nopf_1
	v_add_co_u32_e32 v22, vcc, 0xf000, v22
	s_nop 1
	v_addc_co_u32_e32 v23, vcc, 0, v23, vcc
	global_load_dwordx4 v[26:29], v[22:23], off
	global_load_dwordx4 v[30:33], v[22:23], off offset:64
	global_load_dwordx4 v[34:37], v[22:23], off offset:2048
	global_load_dwordx4 v[38:41], v[22:23], off offset:2112
; #define LAS __attribute__((address_space(3)))
; __device__ __forceinline__ void sel_unit(LAS char* lds, int b, int u, const bf16_t* QI, const bf16_t* KIDX, const float* WIDX, unsigned long long* MASK) {
;     ...
;             for (int kb = 0; kb < 2; ++kb) {
;                 f32x4 s = (f32x4){0.f, 0.f, 0.f, 0.f};
; #pragma unroll
;                 for (int hh = 0; hh < 8; ++hh) {
;                     f32x4 a = (f32x4){0.f, 0.f, 0.f, 0.f};
; #pragma unroll
;                     for (int ks = 0; ks < 2; ++ks) {
;                         const bf16x8 qv = *(const LAS bf16x8*)(lds + L_QI + q16 * 1024 + (((hh * 8 + 4 * ks + kg) ^ q16) << 4));
;                         a = __builtin_amdgcn_mfma_f32_16x16x32_bf16(kf[kb][ks], qv, a, 0, 0, 0);
;                     }
;                     const float wh = wl[hh * 16];
; #pragma unroll
;                     for (int i = 0; i < 4; ++i) s[i] += wh * fmaxf(a[i], 0.f);
;                 }
.Lp0_nopf_1:
	s_waitcnt lgkmcnt(1)
	v_mfma_f32_16x16x32_bf16 v[246:249], v[42:45], v[230:233], 0
	v_mfma_f32_16x16x32_bf16 v[250:253], v[50:53], v[230:233], 0
	v_mfma_f32_16x16x32_bf16 v[246:249], v[46:49], v[234:237], v[246:249]
	v_mfma_f32_16x16x32_bf16 v[250:253], v[2:5], v[234:237], v[250:253]
	ds_read_b128 v[238:241], v184
	ds_read_b128 v[242:245], v185
	ds_read_b32 v7, v137 offset:384
	s_waitcnt lgkmcnt(1)
	v_mfma_f32_16x16x32_bf16 v[206:209], v[42:45], v[238:241], 0
	v_mfma_f32_16x16x32_bf16 v[210:213], v[50:53], v[238:241], 0
	v_mfma_f32_16x16x32_bf16 v[206:209], v[46:49], v[242:245], v[206:209]
	v_mfma_f32_16x16x32_bf16 v[210:213], v[2:5], v[242:245], v[210:213]
	ds_read_b128 v[230:233], v179
	ds_read_b128 v[234:237], v180
	ds_read_b32 v217, v137 offset:448
	v_max_f32_e32 v9, 0, v246
	v_max_f32_e32 v200, 0, v247
	v_max_f32_e32 v201, 0, v248
	v_max_f32_e32 v216, 0, v249
	v_mul_f32_e32 v86, v6, v9
	v_mul_f32_e32 v85, v6, v200
	v_mul_f32_e32 v88, v6, v201
	v_mul_f32_e32 v87, v6, v216
	v_max_f32_e32 v9, 0, v250
	v_max_f32_e32 v200, 0, v251
	v_max_f32_e32 v201, 0, v252
	v_max_f32_e32 v216, 0, v253
	v_mul_f32_e32 v90, v6, v9
	v_mul_f32_e32 v89, v6, v200
	v_mul_f32_e32 v92, v6, v201
	v_mul_f32_e32 v91, v6, v216
	s_waitcnt lgkmcnt(1)
	v_mfma_f32_16x16x32_bf16 v[246:249], v[42:45], v[230:233], 0
	v_mfma_f32_16x16x32_bf16 v[250:253], v[50:53], v[230:233], 0
	v_mfma_f32_16x16x32_bf16 v[246:249], v[46:49], v[234:237], v[246:249]
	v_mfma_f32_16x16x32_bf16 v[250:253], v[2:5], v[234:237], v[250:253]
	ds_read_b128 v[238:241], v176
	ds_read_b128 v[242:245], v159
	ds_read_b32 v6, v137 offset:512
	v_max_f32_e32 v9, 0, v206
	v_max_f32_e32 v200, 0, v207
	v_max_f32_e32 v201, 0, v208
	v_max_f32_e32 v216, 0, v209
	v_fmac_f32_e32 v86, v7, v9
	v_fmac_f32_e32 v85, v7, v200
	v_fmac_f32_e32 v88, v7, v201
	v_fmac_f32_e32 v87, v7, v216
	v_max_f32_e32 v9, 0, v210
	v_max_f32_e32 v200, 0, v211
	v_max_f32_e32 v201, 0, v212
	v_max_f32_e32 v216, 0, v213
	v_fmac_f32_e32 v90, v7, v9
	v_fmac_f32_e32 v89, v7, v200
	v_fmac_f32_e32 v92, v7, v201
	v_fmac_f32_e32 v91, v7, v216
	s_waitcnt lgkmcnt(1)
	v_mfma_f32_16x16x32_bf16 v[206:209], v[42:45], v[238:241], 0
	v_mfma_f32_16x16x32_bf16 v[210:213], v[50:53], v[238:241], 0
	v_mfma_f32_16x16x32_bf16 v[206:209], v[46:49], v[242:245], v[206:209]
	v_mfma_f32_16x16x32_bf16 v[210:213], v[2:5], v[242:245], v[210:213]
	ds_read_b128 v[230:233], v158
	ds_read_b128 v[234:237], v157
	ds_read_b32 v7, v137 offset:576
	v_max_f32_e32 v9, 0, v246
	v_max_f32_e32 v200, 0, v247
	v_max_f32_e32 v201, 0, v248
	v_max_f32_e32 v216, 0, v249
	v_fmac_f32_e32 v86, v217, v9
	v_fmac_f32_e32 v85, v217, v200
	v_fmac_f32_e32 v88, v217, v201
	v_fmac_f32_e32 v87, v217, v216
	v_max_f32_e32 v9, 0, v250
	v_max_f32_e32 v200, 0, v251
	v_max_f32_e32 v201, 0, v252
	v_max_f32_e32 v216, 0, v253
	v_fmac_f32_e32 v90, v217, v9
	v_fmac_f32_e32 v89, v217, v200
	v_fmac_f32_e32 v92, v217, v201
	v_fmac_f32_e32 v91, v217, v216
	s_waitcnt lgkmcnt(1)
	v_mfma_f32_16x16x32_bf16 v[246:249], v[42:45], v[230:233], 0
	v_mfma_f32_16x16x32_bf16 v[250:253], v[50:53], v[230:233], 0
	v_mfma_f32_16x16x32_bf16 v[246:249], v[46:49], v[234:237], v[246:249]
	v_mfma_f32_16x16x32_bf16 v[250:253], v[2:5], v[234:237], v[250:253]
	ds_read_b128 v[238:241], v156
	ds_read_b128 v[242:245], v155
	ds_read_b32 v217, v137 offset:640
	v_max_f32_e32 v9, 0, v206
	v_max_f32_e32 v200, 0, v207
	v_max_f32_e32 v201, 0, v208
	v_max_f32_e32 v216, 0, v209
	v_fmac_f32_e32 v86, v6, v9
	v_fmac_f32_e32 v85, v6, v200
	v_fmac_f32_e32 v88, v6, v201
	v_fmac_f32_e32 v87, v6, v216
	v_max_f32_e32 v9, 0, v210
	v_max_f32_e32 v200, 0, v211
	v_max_f32_e32 v201, 0, v212
	v_max_f32_e32 v216, 0, v213
	v_fmac_f32_e32 v90, v6, v9
	v_fmac_f32_e32 v89, v6, v200
	v_fmac_f32_e32 v92, v6, v201
	v_fmac_f32_e32 v91, v6, v216
	s_waitcnt lgkmcnt(1)
	v_mfma_f32_16x16x32_bf16 v[206:209], v[42:45], v[238:241], 0
	v_mfma_f32_16x16x32_bf16 v[210:213], v[50:53], v[238:241], 0
	v_mfma_f32_16x16x32_bf16 v[206:209], v[46:49], v[242:245], v[206:209]
	v_mfma_f32_16x16x32_bf16 v[210:213], v[2:5], v[242:245], v[210:213]
	ds_read_b128 v[230:233], v154
	ds_read_b128 v[234:237], v153
	ds_read_b32 v6, v137 offset:704
	v_max_f32_e32 v9, 0, v246
	v_max_f32_e32 v200, 0, v247
	v_max_f32_e32 v201, 0, v248
	v_max_f32_e32 v216, 0, v249
	v_fmac_f32_e32 v86, v7, v9
	v_fmac_f32_e32 v85, v7, v200
	v_fmac_f32_e32 v88, v7, v201
	v_fmac_f32_e32 v87, v7, v216
	v_max_f32_e32 v9, 0, v250
	v_max_f32_e32 v200, 0, v251
	v_max_f32_e32 v201, 0, v252
	v_max_f32_e32 v216, 0, v253
	v_fmac_f32_e32 v90, v7, v9
	v_fmac_f32_e32 v89, v7, v200
	v_fmac_f32_e32 v92, v7, v201
	v_fmac_f32_e32 v91, v7, v216
	s_waitcnt lgkmcnt(1)
	v_mfma_f32_16x16x32_bf16 v[246:249], v[42:45], v[230:233], 0
	v_mfma_f32_16x16x32_bf16 v[250:253], v[50:53], v[230:233], 0
	v_mfma_f32_16x16x32_bf16 v[246:249], v[46:49], v[234:237], v[246:249]
	v_mfma_f32_16x16x32_bf16 v[250:253], v[2:5], v[234:237], v[250:253]
	ds_read_b128 v[238:241], v152
	ds_read_b128 v[242:245], v151
	ds_read_b32 v7, v137 offset:768
	v_max_f32_e32 v9, 0, v206
	v_max_f32_e32 v200, 0, v207
	v_max_f32_e32 v201, 0, v208
	v_max_f32_e32 v216, 0, v209
	v_fmac_f32_e32 v86, v217, v9
	v_fmac_f32_e32 v85, v217, v200
	v_fmac_f32_e32 v88, v217, v201
	v_fmac_f32_e32 v87, v217, v216
	v_max_f32_e32 v9, 0, v210
	v_max_f32_e32 v200, 0, v211
	v_max_f32_e32 v201, 0, v212
	v_max_f32_e32 v216, 0, v213
	v_fmac_f32_e32 v90, v217, v9
	v_fmac_f32_e32 v89, v217, v200
	v_fmac_f32_e32 v92, v217, v201
	v_fmac_f32_e32 v91, v217, v216
	s_waitcnt lgkmcnt(1)
; #define LAS __attribute__((address_space(3)))
; #define SEL_HADD(idx_) __hip_atomic_fetch_add(&hist[(idx_)], 1u, __ATOMIC_RELAXED, __HIP_MEMORY_SCOPE_WORKGROUP)
; __device__ __forceinline__ unsigned fkey(float f) { const unsigned u = __float_as_uint(f); return (u & 0x80000000u) ? ~u : (u | 0x80000000u); }
; __device__ __forceinline__ void sel_unit(LAS char* lds, int b, int u, const bf16_t* QI, const bf16_t* KIDX, const float* WIDX, unsigned long long* MASK) {
;     ...
;             for (int kb = 0; kb < 2; ++kb) {
;                 f32x4 s = (f32x4){0.f, 0.f, 0.f, 0.f};
; #pragma unroll
;                 for (int hh = 0; hh < 8; ++hh) {
;                     f32x4 a = (f32x4){0.f, 0.f, 0.f, 0.f};
; #pragma unroll
;                     for (int ks = 0; ks < 2; ++ks) {
;                         const bf16x8 qv = *(const LAS bf16x8*)(lds + L_QI + q16 * 1024 + (((hh * 8 + 4 * ks + kg) ^ q16) << 4));
;                         a = __builtin_amdgcn_mfma_f32_16x16x32_bf16(kf[kb][ks], qv, a, 0, 0, 0);
;                     }
;                     const float wh = wl[hh * 16];
; #pragma unroll
;                     for (int i = 0; i < 4; ++i) s[i] += wh * fmaxf(a[i], 0.f);
;                 }
;                 u32x4 kk; kk.x = fkey(s[0]); kk.y = fkey(s[1]); kk.z = fkey(s[2]); kk.w = fkey(s[3]);
;                 sc[j][2 * kh + kb] = kk;
; #pragma unroll
;                 for (int i = 0; i < 4; ++i) SEL_HADD((kk[i] >> 24) * 16 + q16);
;                 __builtin_amdgcn_sched_barrier(0);
	v_mfma_f32_16x16x32_bf16 v[206:209], v[42:45], v[238:241], 0
	v_mfma_f32_16x16x32_bf16 v[210:213], v[50:53], v[238:241], 0
	v_mfma_f32_16x16x32_bf16 v[206:209], v[46:49], v[242:245], v[206:209]
	v_mfma_f32_16x16x32_bf16 v[210:213], v[2:5], v[242:245], v[210:213]
	v_max_f32_e32 v9, 0, v246
	v_max_f32_e32 v200, 0, v247
	v_max_f32_e32 v201, 0, v248
	v_max_f32_e32 v216, 0, v249
	v_fmac_f32_e32 v86, v6, v9
	v_fmac_f32_e32 v85, v6, v200
	v_fmac_f32_e32 v88, v6, v201
	v_fmac_f32_e32 v87, v6, v216
	v_max_f32_e32 v9, 0, v250
	v_max_f32_e32 v200, 0, v251
	v_max_f32_e32 v201, 0, v252
	v_max_f32_e32 v216, 0, v253
	v_fmac_f32_e32 v90, v6, v9
	v_fmac_f32_e32 v89, v6, v200
	v_fmac_f32_e32 v92, v6, v201
	v_fmac_f32_e32 v91, v6, v216
	s_waitcnt lgkmcnt(0)
	v_max_f32_e32 v9, 0, v206
	v_max_f32_e32 v200, 0, v207
	v_max_f32_e32 v201, 0, v208
	v_max_f32_e32 v216, 0, v209
	v_fmac_f32_e32 v86, v7, v9
	v_fmac_f32_e32 v85, v7, v200
	v_fmac_f32_e32 v88, v7, v201
	v_fmac_f32_e32 v87, v7, v216
	v_max_f32_e32 v9, 0, v210
	v_max_f32_e32 v200, 0, v211
	v_max_f32_e32 v201, 0, v212
	v_max_f32_e32 v216, 0, v213
	v_fmac_f32_e32 v90, v7, v9
	v_fmac_f32_e32 v89, v7, v200
	v_fmac_f32_e32 v92, v7, v201
	v_fmac_f32_e32 v91, v7, v216
	v_ashrrev_i32_e32 v9, 31, v86
	v_bitop3_b32 v86, v9, v86, v8 bitop3:0x36
	v_ashrrev_i32_e32 v200, 31, v85
	v_bitop3_b32 v85, v200, v85, v8 bitop3:0x36
	v_ashrrev_i32_e32 v201, 31, v88
	v_bitop3_b32 v88, v201, v88, v8 bitop3:0x36
	v_ashrrev_i32_e32 v216, 31, v87
	v_bitop3_b32 v87, v216, v87, v8 bitop3:0x36
	v_ashrrev_i32_e32 v9, 31, v90
	v_bitop3_b32 v90, v9, v90, v8 bitop3:0x36
	v_ashrrev_i32_e32 v200, 31, v89
	v_bitop3_b32 v89, v200, v89, v8 bitop3:0x36
	v_ashrrev_i32_e32 v201, 31, v92
	v_bitop3_b32 v92, v201, v92, v8 bitop3:0x36
	v_ashrrev_i32_e32 v216, 31, v91
	v_bitop3_b32 v91, v216, v91, v8 bitop3:0x36
	v_lshrrev_b32_e32 v9, 24, v86
	v_lshl_add_u32 v9, v9, 6, v0
	ds_add_u32 v9, v205 offset:16384
	v_lshrrev_b32_e32 v200, 24, v85
	v_lshl_add_u32 v200, v200, 6, v0
	ds_add_u32 v200, v205 offset:16384
	v_lshrrev_b32_e32 v201, 24, v88
	v_lshl_add_u32 v201, v201, 6, v0
	ds_add_u32 v201, v205 offset:16384
	v_lshrrev_b32_e32 v216, 24, v87
	v_lshl_add_u32 v216, v216, 6, v0
	ds_add_u32 v216, v205 offset:16384
	v_lshrrev_b32_e32 v9, 24, v90
	v_lshl_add_u32 v9, v9, 6, v0
	ds_add_u32 v9, v205 offset:16384
	v_lshrrev_b32_e32 v200, 24, v89
	v_lshl_add_u32 v200, v200, 6, v0
	ds_add_u32 v200, v205 offset:16384
	v_lshrrev_b32_e32 v201, 24, v92
	v_lshl_add_u32 v201, v201, 6, v0
	ds_add_u32 v201, v205 offset:16384
	v_lshrrev_b32_e32 v216, 24, v91
	v_lshl_add_u32 v216, v216, 6, v0
	ds_add_u32 v216, v205 offset:16384
.LBB0_660:
	s_cmp_gt_i32 s4, 2
	s_cselect_b64 s[54:55], -1, 0
	s_cmp_lt_i32 s4, 3
	s_cbranch_scc1 .LBB0_662
	ds_read_b128 v[230:233], v182
	ds_read_b128 v[234:237], v183
	ds_read_b32 v6, v137 offset:320
	s_waitcnt vmcnt(0)
	v_add_co_u32_e32 v22, vcc, s96, v22
	s_nop 1
	v_addc_co_u32_e32 v23, vcc, 0, v23, vcc
	global_load_dwordx4 v[42:45], v[22:23], off
	global_load_dwordx4 v[46:49], v[22:23], off offset:64
	global_load_dwordx4 v[50:53], v[22:23], off offset:2048
	global_load_dwordx4 v[2:5], v[22:23], off offset:2112
	s_waitcnt lgkmcnt(1)
	v_mfma_f32_16x16x32_bf16 v[246:249], v[26:29], v[230:233], 0
	v_mfma_f32_16x16x32_bf16 v[250:253], v[34:37], v[230:233], 0
	v_mfma_f32_16x16x32_bf16 v[246:249], v[30:33], v[234:237], v[246:249]
	v_mfma_f32_16x16x32_bf16 v[250:253], v[38:41], v[234:237], v[250:253]
	ds_read_b128 v[238:241], v184
	ds_read_b128 v[242:245], v185
	ds_read_b32 v7, v137 offset:384
	s_waitcnt lgkmcnt(1)
	v_mfma_f32_16x16x32_bf16 v[206:209], v[26:29], v[238:241], 0
	v_mfma_f32_16x16x32_bf16 v[210:213], v[34:37], v[238:241], 0
	v_mfma_f32_16x16x32_bf16 v[206:209], v[30:33], v[242:245], v[206:209]
	v_mfma_f32_16x16x32_bf16 v[210:213], v[38:41], v[242:245], v[210:213]
	ds_read_b128 v[230:233], v179
	ds_read_b128 v[234:237], v180
	ds_read_b32 v217, v137 offset:448
	v_max_f32_e32 v9, 0, v246
	v_max_f32_e32 v200, 0, v247
	v_max_f32_e32 v201, 0, v248
	v_max_f32_e32 v216, 0, v249
	v_mul_f32_e32 v94, v6, v9
	v_mul_f32_e32 v93, v6, v200
	v_mul_f32_e32 v96, v6, v201
	v_mul_f32_e32 v95, v6, v216
	v_max_f32_e32 v9, 0, v250
	v_max_f32_e32 v200, 0, v251
	v_max_f32_e32 v201, 0, v252
	v_max_f32_e32 v216, 0, v253
	v_mul_f32_e32 v98, v6, v9
	v_mul_f32_e32 v97, v6, v200
	v_mul_f32_e32 v100, v6, v201
	v_mul_f32_e32 v99, v6, v216
	s_waitcnt lgkmcnt(1)
	v_mfma_f32_16x16x32_bf16 v[246:249], v[26:29], v[230:233], 0
	v_mfma_f32_16x16x32_bf16 v[250:253], v[34:37], v[230:233], 0
	v_mfma_f32_16x16x32_bf16 v[246:249], v[30:33], v[234:237], v[246:249]
	v_mfma_f32_16x16x32_bf16 v[250:253], v[38:41], v[234:237], v[250:253]
	ds_read_b128 v[238:241], v176
	ds_read_b128 v[242:245], v159
	ds_read_b32 v6, v137 offset:512
	v_max_f32_e32 v9, 0, v206
	v_max_f32_e32 v200, 0, v207
	v_max_f32_e32 v201, 0, v208
	v_max_f32_e32 v216, 0, v209
	v_fmac_f32_e32 v94, v7, v9
	v_fmac_f32_e32 v93, v7, v200
	v_fmac_f32_e32 v96, v7, v201
	v_fmac_f32_e32 v95, v7, v216
	v_max_f32_e32 v9, 0, v210
	v_max_f32_e32 v200, 0, v211
	v_max_f32_e32 v201, 0, v212
	v_max_f32_e32 v216, 0, v213
	v_fmac_f32_e32 v98, v7, v9
	v_fmac_f32_e32 v97, v7, v200
	v_fmac_f32_e32 v100, v7, v201
	v_fmac_f32_e32 v99, v7, v216
	s_waitcnt lgkmcnt(1)
; #define LAS __attribute__((address_space(3)))
; #define SEL_HADD(idx_) __hip_atomic_fetch_add(&hist[(idx_)], 1u, __ATOMIC_RELAXED, __HIP_MEMORY_SCOPE_WORKGROUP)
; __device__ __forceinline__ unsigned fkey(float f) { const unsigned u = __float_as_uint(f); return (u & 0x80000000u) ? ~u : (u | 0x80000000u); }
; __device__ __forceinline__ void sel_unit(LAS char* lds, int b, int u, const bf16_t* QI, const bf16_t* KIDX, const float* WIDX, unsigned long long* MASK) {
;     ...
;             for (int kb = 0; kb < 2; ++kb) {
;                 f32x4 s = (f32x4){0.f, 0.f, 0.f, 0.f};
; #pragma unroll
;                 for (int hh = 0; hh < 8; ++hh) {
;                     f32x4 a = (f32x4){0.f, 0.f, 0.f, 0.f};
; #pragma unroll
;                     for (int ks = 0; ks < 2; ++ks) {
;                         const bf16x8 qv = *(const LAS bf16x8*)(lds + L_QI + q16 * 1024 + (((hh * 8 + 4 * ks + kg) ^ q16) << 4));
;                         a = __builtin_amdgcn_mfma_f32_16x16x32_bf16(kf[kb][ks], qv, a, 0, 0, 0);
;                     }
;                     const float wh = wl[hh * 16];
; #pragma unroll
;                     for (int i = 0; i < 4; ++i) s[i] += wh * fmaxf(a[i], 0.f);
;                 }
;                 u32x4 kk; kk.x = fkey(s[0]); kk.y = fkey(s[1]); kk.z = fkey(s[2]); kk.w = fkey(s[3]);
;                 sc[j][2 * kh + kb] = kk;
; #pragma unroll
;                 for (int i = 0; i < 4; ++i) SEL_HADD((kk[i] >> 24) * 16 + q16);
;                 __builtin_amdgcn_sched_barrier(0);
	v_mfma_f32_16x16x32_bf16 v[206:209], v[26:29], v[238:241], 0
	v_mfma_f32_16x16x32_bf16 v[210:213], v[34:37], v[238:241], 0
	v_mfma_f32_16x16x32_bf16 v[206:209], v[30:33], v[242:245], v[206:209]
	v_mfma_f32_16x16x32_bf16 v[210:213], v[38:41], v[242:245], v[210:213]
	ds_read_b128 v[230:233], v158
	ds_read_b128 v[234:237], v157
	ds_read_b32 v7, v137 offset:576
	v_max_f32_e32 v9, 0, v246
	v_max_f32_e32 v200, 0, v247
	v_max_f32_e32 v201, 0, v248
	v_max_f32_e32 v216, 0, v249
	v_fmac_f32_e32 v94, v217, v9
	v_fmac_f32_e32 v93, v217, v200
	v_fmac_f32_e32 v96, v217, v201
	v_fmac_f32_e32 v95, v217, v216
	v_max_f32_e32 v9, 0, v250
	v_max_f32_e32 v200, 0, v251
	v_max_f32_e32 v201, 0, v252
	v_max_f32_e32 v216, 0, v253
	v_fmac_f32_e32 v98, v217, v9
	v_fmac_f32_e32 v97, v217, v200
	v_fmac_f32_e32 v100, v217, v201
	v_fmac_f32_e32 v99, v217, v216
	s_waitcnt lgkmcnt(1)
	v_mfma_f32_16x16x32_bf16 v[246:249], v[26:29], v[230:233], 0
	v_mfma_f32_16x16x32_bf16 v[250:253], v[34:37], v[230:233], 0
	v_mfma_f32_16x16x32_bf16 v[246:249], v[30:33], v[234:237], v[246:249]
	v_mfma_f32_16x16x32_bf16 v[250:253], v[38:41], v[234:237], v[250:253]
	ds_read_b128 v[238:241], v156
	ds_read_b128 v[242:245], v155
	ds_read_b32 v217, v137 offset:640
	v_max_f32_e32 v9, 0, v206
	v_max_f32_e32 v200, 0, v207
	v_max_f32_e32 v201, 0, v208
	v_max_f32_e32 v216, 0, v209
	v_fmac_f32_e32 v94, v6, v9
	v_fmac_f32_e32 v93, v6, v200
	v_fmac_f32_e32 v96, v6, v201
	v_fmac_f32_e32 v95, v6, v216
	v_max_f32_e32 v9, 0, v210
	v_max_f32_e32 v200, 0, v211
	v_max_f32_e32 v201, 0, v212
	v_max_f32_e32 v216, 0, v213
	v_fmac_f32_e32 v98, v6, v9
	v_fmac_f32_e32 v97, v6, v200
	v_fmac_f32_e32 v100, v6, v201
	v_fmac_f32_e32 v99, v6, v216
	s_waitcnt lgkmcnt(1)
	v_mfma_f32_16x16x32_bf16 v[206:209], v[26:29], v[238:241], 0
	v_mfma_f32_16x16x32_bf16 v[210:213], v[34:37], v[238:241], 0
	v_mfma_f32_16x16x32_bf16 v[206:209], v[30:33], v[242:245], v[206:209]
	v_mfma_f32_16x16x32_bf16 v[210:213], v[38:41], v[242:245], v[210:213]
	ds_read_b128 v[230:233], v154
	ds_read_b128 v[234:237], v153
	ds_read_b32 v6, v137 offset:704
	v_max_f32_e32 v9, 0, v246
	v_max_f32_e32 v200, 0, v247
	v_max_f32_e32 v201, 0, v248
	v_max_f32_e32 v216, 0, v249
	v_fmac_f32_e32 v94, v7, v9
	v_fmac_f32_e32 v93, v7, v200
	v_fmac_f32_e32 v96, v7, v201
	v_fmac_f32_e32 v95, v7, v216
	v_max_f32_e32 v9, 0, v250
	v_max_f32_e32 v200, 0, v251
	v_max_f32_e32 v201, 0, v252
	v_max_f32_e32 v216, 0, v253
	v_fmac_f32_e32 v98, v7, v9
	v_fmac_f32_e32 v97, v7, v200
	v_fmac_f32_e32 v100, v7, v201
	v_fmac_f32_e32 v99, v7, v216
	s_waitcnt lgkmcnt(1)
	v_mfma_f32_16x16x32_bf16 v[246:249], v[26:29], v[230:233], 0
	v_mfma_f32_16x16x32_bf16 v[250:253], v[34:37], v[230:233], 0
	v_mfma_f32_16x16x32_bf16 v[246:249], v[30:33], v[234:237], v[246:249]
	v_mfma_f32_16x16x32_bf16 v[250:253], v[38:41], v[234:237], v[250:253]
	ds_read_b128 v[238:241], v152
	ds_read_b128 v[242:245], v151
	ds_read_b32 v7, v137 offset:768
	v_max_f32_e32 v9, 0, v206
	v_max_f32_e32 v200, 0, v207
	v_max_f32_e32 v201, 0, v208
	v_max_f32_e32 v216, 0, v209
	v_fmac_f32_e32 v94, v217, v9
	v_fmac_f32_e32 v93, v217, v200
	v_fmac_f32_e32 v96, v217, v201
	v_fmac_f32_e32 v95, v217, v216
	v_max_f32_e32 v9, 0, v210
	v_max_f32_e32 v200, 0, v211
	v_max_f32_e32 v201, 0, v212
	v_max_f32_e32 v216, 0, v213
	v_fmac_f32_e32 v98, v217, v9
	v_fmac_f32_e32 v97, v217, v200
	v_fmac_f32_e32 v100, v217, v201
	v_fmac_f32_e32 v99, v217, v216
	s_waitcnt lgkmcnt(1)
	v_mfma_f32_16x16x32_bf16 v[206:209], v[26:29], v[238:241], 0
	v_mfma_f32_16x16x32_bf16 v[210:213], v[34:37], v[238:241], 0
	v_mfma_f32_16x16x32_bf16 v[206:209], v[30:33], v[242:245], v[206:209]
	v_mfma_f32_16x16x32_bf16 v[210:213], v[38:41], v[242:245], v[210:213]
	v_max_f32_e32 v9, 0, v246
	v_max_f32_e32 v200, 0, v247
	v_max_f32_e32 v201, 0, v248
	v_max_f32_e32 v216, 0, v249
	v_fmac_f32_e32 v94, v6, v9
	v_fmac_f32_e32 v93, v6, v200
	v_fmac_f32_e32 v96, v6, v201
	v_fmac_f32_e32 v95, v6, v216
	v_max_f32_e32 v9, 0, v250
	v_max_f32_e32 v200, 0, v251
	v_max_f32_e32 v201, 0, v252
	v_max_f32_e32 v216, 0, v253
	v_fmac_f32_e32 v98, v6, v9
	v_fmac_f32_e32 v97, v6, v200
	v_fmac_f32_e32 v100, v6, v201
	v_fmac_f32_e32 v99, v6, v216
	s_waitcnt lgkmcnt(0)
	v_max_f32_e32 v9, 0, v206
	v_max_f32_e32 v200, 0, v207
	v_max_f32_e32 v201, 0, v208
	v_max_f32_e32 v216, 0, v209
	v_fmac_f32_e32 v94, v7, v9
	v_fmac_f32_e32 v93, v7, v200
	v_fmac_f32_e32 v96, v7, v201
	v_fmac_f32_e32 v95, v7, v216
	v_max_f32_e32 v9, 0, v210
	v_max_f32_e32 v200, 0, v211
	v_max_f32_e32 v201, 0, v212
	v_max_f32_e32 v216, 0, v213
	v_fmac_f32_e32 v98, v7, v9
	v_fmac_f32_e32 v97, v7, v200
	v_fmac_f32_e32 v100, v7, v201
	v_fmac_f32_e32 v99, v7, v216
	v_ashrrev_i32_e32 v9, 31, v94
	v_bitop3_b32 v94, v9, v94, v8 bitop3:0x36
	v_ashrrev_i32_e32 v200, 31, v93
	v_bitop3_b32 v93, v200, v93, v8 bitop3:0x36
	v_ashrrev_i32_e32 v201, 31, v96
	v_bitop3_b32 v96, v201, v96, v8 bitop3:0x36
	v_ashrrev_i32_e32 v216, 31, v95
	v_bitop3_b32 v95, v216, v95, v8 bitop3:0x36
	v_ashrrev_i32_e32 v9, 31, v98
	v_bitop3_b32 v98, v9, v98, v8 bitop3:0x36
	v_ashrrev_i32_e32 v200, 31, v97
	v_bitop3_b32 v97, v200, v97, v8 bitop3:0x36
	v_ashrrev_i32_e32 v201, 31, v100
	v_bitop3_b32 v100, v201, v100, v8 bitop3:0x36
	v_ashrrev_i32_e32 v216, 31, v99
	v_bitop3_b32 v99, v216, v99, v8 bitop3:0x36
	v_lshrrev_b32_e32 v9, 24, v94
	v_lshl_add_u32 v9, v9, 6, v0
	ds_add_u32 v9, v205 offset:16384
	v_lshrrev_b32_e32 v200, 24, v93
	v_lshl_add_u32 v200, v200, 6, v0
	ds_add_u32 v200, v205 offset:16384
	v_lshrrev_b32_e32 v201, 24, v96
	v_lshl_add_u32 v201, v201, 6, v0
	ds_add_u32 v201, v205 offset:16384
	v_lshrrev_b32_e32 v216, 24, v95
	v_lshl_add_u32 v216, v216, 6, v0
	ds_add_u32 v216, v205 offset:16384
	v_lshrrev_b32_e32 v9, 24, v98
	v_lshl_add_u32 v9, v9, 6, v0
	ds_add_u32 v9, v205 offset:16384
	v_lshrrev_b32_e32 v200, 24, v97
	v_lshl_add_u32 v200, v200, 6, v0
	ds_add_u32 v200, v205 offset:16384
	v_lshrrev_b32_e32 v201, 24, v100
	v_lshl_add_u32 v201, v201, 6, v0
	ds_add_u32 v201, v205 offset:16384
	v_lshrrev_b32_e32 v216, 24, v99
	v_lshl_add_u32 v216, v216, 6, v0
	ds_add_u32 v216, v205 offset:16384
	ds_read_b128 v[230:233], v182
	ds_read_b128 v[234:237], v183
	ds_read_b32 v6, v137 offset:320
	s_waitcnt vmcnt(0)
	s_cmp_lt_i32 s4, 4
	s_cbranch_scc1 .Lp0_nopf_2
	v_add_co_u32_e32 v22, vcc, 0xf000, v22
	s_nop 1
	v_addc_co_u32_e32 v23, vcc, 0, v23, vcc
	global_load_dwordx4 v[26:29], v[22:23], off
	global_load_dwordx4 v[30:33], v[22:23], off offset:64
	global_load_dwordx4 v[34:37], v[22:23], off offset:2048
	global_load_dwordx4 v[38:41], v[22:23], off offset:2112
; #define LAS __attribute__((address_space(3)))
; __device__ __forceinline__ void sel_unit(LAS char* lds, int b, int u, const bf16_t* QI, const bf16_t* KIDX, const float* WIDX, unsigned long long* MASK) {
;     ...
;             for (int kb = 0; kb < 2; ++kb) {
;                 f32x4 s = (f32x4){0.f, 0.f, 0.f, 0.f};
; #pragma unroll
;                 for (int hh = 0; hh < 8; ++hh) {
;                     f32x4 a = (f32x4){0.f, 0.f, 0.f, 0.f};
; #pragma unroll
;                     for (int ks = 0; ks < 2; ++ks) {
;                         const bf16x8 qv = *(const LAS bf16x8*)(lds + L_QI + q16 * 1024 + (((hh * 8 + 4 * ks + kg) ^ q16) << 4));
;                         a = __builtin_amdgcn_mfma_f32_16x16x32_bf16(kf[kb][ks], qv, a, 0, 0, 0);
;                     }
;                     const float wh = wl[hh * 16];
; #pragma unroll
;                     for (int i = 0; i < 4; ++i) s[i] += wh * fmaxf(a[i], 0.f);
;                 }
.Lp0_nopf_2:
	s_waitcnt lgkmcnt(1)
	v_mfma_f32_16x16x32_bf16 v[246:249], v[42:45], v[230:233], 0
	v_mfma_f32_16x16x32_bf16 v[250:253], v[50:53], v[230:233], 0
	v_mfma_f32_16x16x32_bf16 v[246:249], v[46:49], v[234:237], v[246:249]
	v_mfma_f32_16x16x32_bf16 v[250:253], v[2:5], v[234:237], v[250:253]
	ds_read_b128 v[238:241], v184
	ds_read_b128 v[242:245], v185
	ds_read_b32 v7, v137 offset:384
	s_waitcnt lgkmcnt(1)
	v_mfma_f32_16x16x32_bf16 v[206:209], v[42:45], v[238:241], 0
	v_mfma_f32_16x16x32_bf16 v[210:213], v[50:53], v[238:241], 0
	v_mfma_f32_16x16x32_bf16 v[206:209], v[46:49], v[242:245], v[206:209]
	v_mfma_f32_16x16x32_bf16 v[210:213], v[2:5], v[242:245], v[210:213]
	ds_read_b128 v[230:233], v179
	ds_read_b128 v[234:237], v180
	ds_read_b32 v217, v137 offset:448
	v_max_f32_e32 v9, 0, v246
	v_max_f32_e32 v200, 0, v247
	v_max_f32_e32 v201, 0, v248
	v_max_f32_e32 v216, 0, v249
	v_mul_f32_e32 v102, v6, v9
	v_mul_f32_e32 v101, v6, v200
	v_mul_f32_e32 v104, v6, v201
	v_mul_f32_e32 v103, v6, v216
	v_max_f32_e32 v9, 0, v250
	v_max_f32_e32 v200, 0, v251
	v_max_f32_e32 v201, 0, v252
	v_max_f32_e32 v216, 0, v253
	v_mul_f32_e32 v106, v6, v9
	v_mul_f32_e32 v105, v6, v200
	v_mul_f32_e32 v108, v6, v201
	v_mul_f32_e32 v107, v6, v216
	s_waitcnt lgkmcnt(1)
	v_mfma_f32_16x16x32_bf16 v[246:249], v[42:45], v[230:233], 0
	v_mfma_f32_16x16x32_bf16 v[250:253], v[50:53], v[230:233], 0
	v_mfma_f32_16x16x32_bf16 v[246:249], v[46:49], v[234:237], v[246:249]
	v_mfma_f32_16x16x32_bf16 v[250:253], v[2:5], v[234:237], v[250:253]
	ds_read_b128 v[238:241], v176
	ds_read_b128 v[242:245], v159
	ds_read_b32 v6, v137 offset:512
	v_max_f32_e32 v9, 0, v206
	v_max_f32_e32 v200, 0, v207
	v_max_f32_e32 v201, 0, v208
	v_max_f32_e32 v216, 0, v209
	v_fmac_f32_e32 v102, v7, v9
	v_fmac_f32_e32 v101, v7, v200
	v_fmac_f32_e32 v104, v7, v201
	v_fmac_f32_e32 v103, v7, v216
	v_max_f32_e32 v9, 0, v210
	v_max_f32_e32 v200, 0, v211
	v_max_f32_e32 v201, 0, v212
	v_max_f32_e32 v216, 0, v213
	v_fmac_f32_e32 v106, v7, v9
	v_fmac_f32_e32 v105, v7, v200
	v_fmac_f32_e32 v108, v7, v201
	v_fmac_f32_e32 v107, v7, v216
	s_waitcnt lgkmcnt(1)
	v_mfma_f32_16x16x32_bf16 v[206:209], v[42:45], v[238:241], 0
	v_mfma_f32_16x16x32_bf16 v[210:213], v[50:53], v[238:241], 0
	v_mfma_f32_16x16x32_bf16 v[206:209], v[46:49], v[242:245], v[206:209]
	v_mfma_f32_16x16x32_bf16 v[210:213], v[2:5], v[242:245], v[210:213]
	ds_read_b128 v[230:233], v158
	ds_read_b128 v[234:237], v157
	ds_read_b32 v7, v137 offset:576
	v_max_f32_e32 v9, 0, v246
	v_max_f32_e32 v200, 0, v247
	v_max_f32_e32 v201, 0, v248
	v_max_f32_e32 v216, 0, v249
	v_fmac_f32_e32 v102, v217, v9
	v_fmac_f32_e32 v101, v217, v200
	v_fmac_f32_e32 v104, v217, v201
	v_fmac_f32_e32 v103, v217, v216
	v_max_f32_e32 v9, 0, v250
	v_max_f32_e32 v200, 0, v251
	v_max_f32_e32 v201, 0, v252
	v_max_f32_e32 v216, 0, v253
	v_fmac_f32_e32 v106, v217, v9
	v_fmac_f32_e32 v105, v217, v200
	v_fmac_f32_e32 v108, v217, v201
	v_fmac_f32_e32 v107, v217, v216
	s_waitcnt lgkmcnt(1)
	v_mfma_f32_16x16x32_bf16 v[246:249], v[42:45], v[230:233], 0
	v_mfma_f32_16x16x32_bf16 v[250:253], v[50:53], v[230:233], 0
	v_mfma_f32_16x16x32_bf16 v[246:249], v[46:49], v[234:237], v[246:249]
	v_mfma_f32_16x16x32_bf16 v[250:253], v[2:5], v[234:237], v[250:253]
	ds_read_b128 v[238:241], v156
	ds_read_b128 v[242:245], v155
	ds_read_b32 v217, v137 offset:640
	v_max_f32_e32 v9, 0, v206
	v_max_f32_e32 v200, 0, v207
	v_max_f32_e32 v201, 0, v208
	v_max_f32_e32 v216, 0, v209
	v_fmac_f32_e32 v102, v6, v9
	v_fmac_f32_e32 v101, v6, v200
	v_fmac_f32_e32 v104, v6, v201
	v_fmac_f32_e32 v103, v6, v216
	v_max_f32_e32 v9, 0, v210
	v_max_f32_e32 v200, 0, v211
	v_max_f32_e32 v201, 0, v212
	v_max_f32_e32 v216, 0, v213
	v_fmac_f32_e32 v106, v6, v9
	v_fmac_f32_e32 v105, v6, v200
	v_fmac_f32_e32 v108, v6, v201
	v_fmac_f32_e32 v107, v6, v216
	s_waitcnt lgkmcnt(1)
	v_mfma_f32_16x16x32_bf16 v[206:209], v[42:45], v[238:241], 0
	v_mfma_f32_16x16x32_bf16 v[210:213], v[50:53], v[238:241], 0
	v_mfma_f32_16x16x32_bf16 v[206:209], v[46:49], v[242:245], v[206:209]
	v_mfma_f32_16x16x32_bf16 v[210:213], v[2:5], v[242:245], v[210:213]
	ds_read_b128 v[230:233], v154
	ds_read_b128 v[234:237], v153
	ds_read_b32 v6, v137 offset:704
	v_max_f32_e32 v9, 0, v246
	v_max_f32_e32 v200, 0, v247
	v_max_f32_e32 v201, 0, v248
	v_max_f32_e32 v216, 0, v249
	v_fmac_f32_e32 v102, v7, v9
	v_fmac_f32_e32 v101, v7, v200
	v_fmac_f32_e32 v104, v7, v201
	v_fmac_f32_e32 v103, v7, v216
	v_max_f32_e32 v9, 0, v250
	v_max_f32_e32 v200, 0, v251
	v_max_f32_e32 v201, 0, v252
	v_max_f32_e32 v216, 0, v253
	v_fmac_f32_e32 v106, v7, v9
	v_fmac_f32_e32 v105, v7, v200
	v_fmac_f32_e32 v108, v7, v201
	v_fmac_f32_e32 v107, v7, v216
	s_waitcnt lgkmcnt(1)
	v_mfma_f32_16x16x32_bf16 v[246:249], v[42:45], v[230:233], 0
	v_mfma_f32_16x16x32_bf16 v[250:253], v[50:53], v[230:233], 0
	v_mfma_f32_16x16x32_bf16 v[246:249], v[46:49], v[234:237], v[246:249]
	v_mfma_f32_16x16x32_bf16 v[250:253], v[2:5], v[234:237], v[250:253]
	ds_read_b128 v[238:241], v152
	ds_read_b128 v[242:245], v151
	ds_read_b32 v7, v137 offset:768
	v_max_f32_e32 v9, 0, v206
	v_max_f32_e32 v200, 0, v207
	v_max_f32_e32 v201, 0, v208
	v_max_f32_e32 v216, 0, v209
	v_fmac_f32_e32 v102, v217, v9
	v_fmac_f32_e32 v101, v217, v200
	v_fmac_f32_e32 v104, v217, v201
	v_fmac_f32_e32 v103, v217, v216
	v_max_f32_e32 v9, 0, v210
	v_max_f32_e32 v200, 0, v211
	v_max_f32_e32 v201, 0, v212
	v_max_f32_e32 v216, 0, v213
	v_fmac_f32_e32 v106, v217, v9
	v_fmac_f32_e32 v105, v217, v200
	v_fmac_f32_e32 v108, v217, v201
	v_fmac_f32_e32 v107, v217, v216
	s_waitcnt lgkmcnt(1)
; #define LAS __attribute__((address_space(3)))
; #define SEL_HADD(idx_) __hip_atomic_fetch_add(&hist[(idx_)], 1u, __ATOMIC_RELAXED, __HIP_MEMORY_SCOPE_WORKGROUP)
; __device__ __forceinline__ unsigned fkey(float f) { const unsigned u = __float_as_uint(f); return (u & 0x80000000u) ? ~u : (u | 0x80000000u); }
; __device__ __forceinline__ void sel_unit(LAS char* lds, int b, int u, const bf16_t* QI, const bf16_t* KIDX, const float* WIDX, unsigned long long* MASK) {
;     ...
;             for (int kb = 0; kb < 2; ++kb) {
;                 f32x4 s = (f32x4){0.f, 0.f, 0.f, 0.f};
; #pragma unroll
;                 for (int hh = 0; hh < 8; ++hh) {
;                     f32x4 a = (f32x4){0.f, 0.f, 0.f, 0.f};
; #pragma unroll
;                     for (int ks = 0; ks < 2; ++ks) {
;                         const bf16x8 qv = *(const LAS bf16x8*)(lds + L_QI + q16 * 1024 + (((hh * 8 + 4 * ks + kg) ^ q16) << 4));
;                         a = __builtin_amdgcn_mfma_f32_16x16x32_bf16(kf[kb][ks], qv, a, 0, 0, 0);
;                     }
;                     const float wh = wl[hh * 16];
; #pragma unroll
;                     for (int i = 0; i < 4; ++i) s[i] += wh * fmaxf(a[i], 0.f);
;                 }
;                 u32x4 kk; kk.x = fkey(s[0]); kk.y = fkey(s[1]); kk.z = fkey(s[2]); kk.w = fkey(s[3]);
;                 sc[j][2 * kh + kb] = kk;
; #pragma unroll
;                 for (int i = 0; i < 4; ++i) SEL_HADD((kk[i] >> 24) * 16 + q16);
;                 __builtin_amdgcn_sched_barrier(0);
	v_mfma_f32_16x16x32_bf16 v[206:209], v[42:45], v[238:241], 0
	v_mfma_f32_16x16x32_bf16 v[210:213], v[50:53], v[238:241], 0
	v_mfma_f32_16x16x32_bf16 v[206:209], v[46:49], v[242:245], v[206:209]
	v_mfma_f32_16x16x32_bf16 v[210:213], v[2:5], v[242:245], v[210:213]
	v_max_f32_e32 v9, 0, v246
	v_max_f32_e32 v200, 0, v247
	v_max_f32_e32 v201, 0, v248
	v_max_f32_e32 v216, 0, v249
	v_fmac_f32_e32 v102, v6, v9
	v_fmac_f32_e32 v101, v6, v200
	v_fmac_f32_e32 v104, v6, v201
	v_fmac_f32_e32 v103, v6, v216
	v_max_f32_e32 v9, 0, v250
	v_max_f32_e32 v200, 0, v251
	v_max_f32_e32 v201, 0, v252
	v_max_f32_e32 v216, 0, v253
	v_fmac_f32_e32 v106, v6, v9
	v_fmac_f32_e32 v105, v6, v200
	v_fmac_f32_e32 v108, v6, v201
	v_fmac_f32_e32 v107, v6, v216
	s_waitcnt lgkmcnt(0)
	v_max_f32_e32 v9, 0, v206
	v_max_f32_e32 v200, 0, v207
	v_max_f32_e32 v201, 0, v208
	v_max_f32_e32 v216, 0, v209
	v_fmac_f32_e32 v102, v7, v9
	v_fmac_f32_e32 v101, v7, v200
	v_fmac_f32_e32 v104, v7, v201
	v_fmac_f32_e32 v103, v7, v216
	v_max_f32_e32 v9, 0, v210
	v_max_f32_e32 v200, 0, v211
	v_max_f32_e32 v201, 0, v212
	v_max_f32_e32 v216, 0, v213
	v_fmac_f32_e32 v106, v7, v9
	v_fmac_f32_e32 v105, v7, v200
	v_fmac_f32_e32 v108, v7, v201
	v_fmac_f32_e32 v107, v7, v216
	v_ashrrev_i32_e32 v9, 31, v102
	v_bitop3_b32 v102, v9, v102, v8 bitop3:0x36
	v_ashrrev_i32_e32 v200, 31, v101
	v_bitop3_b32 v101, v200, v101, v8 bitop3:0x36
	v_ashrrev_i32_e32 v201, 31, v104
	v_bitop3_b32 v104, v201, v104, v8 bitop3:0x36
	v_ashrrev_i32_e32 v216, 31, v103
	v_bitop3_b32 v103, v216, v103, v8 bitop3:0x36
	v_ashrrev_i32_e32 v9, 31, v106
	v_bitop3_b32 v106, v9, v106, v8 bitop3:0x36
	v_ashrrev_i32_e32 v200, 31, v105
	v_bitop3_b32 v105, v200, v105, v8 bitop3:0x36
	v_ashrrev_i32_e32 v201, 31, v108
	v_bitop3_b32 v108, v201, v108, v8 bitop3:0x36
	v_ashrrev_i32_e32 v216, 31, v107
	v_bitop3_b32 v107, v216, v107, v8 bitop3:0x36
	v_lshrrev_b32_e32 v9, 24, v102
	v_lshl_add_u32 v9, v9, 6, v0
	ds_add_u32 v9, v205 offset:16384
	v_lshrrev_b32_e32 v200, 24, v101
	v_lshl_add_u32 v200, v200, 6, v0
	ds_add_u32 v200, v205 offset:16384
	v_lshrrev_b32_e32 v201, 24, v104
	v_lshl_add_u32 v201, v201, 6, v0
	ds_add_u32 v201, v205 offset:16384
	v_lshrrev_b32_e32 v216, 24, v103
	v_lshl_add_u32 v216, v216, 6, v0
	ds_add_u32 v216, v205 offset:16384
	v_lshrrev_b32_e32 v9, 24, v106
	v_lshl_add_u32 v9, v9, 6, v0
	ds_add_u32 v9, v205 offset:16384
	v_lshrrev_b32_e32 v200, 24, v105
	v_lshl_add_u32 v200, v200, 6, v0
	ds_add_u32 v200, v205 offset:16384
	v_lshrrev_b32_e32 v201, 24, v108
	v_lshl_add_u32 v201, v201, 6, v0
	ds_add_u32 v201, v205 offset:16384
	v_lshrrev_b32_e32 v216, 24, v107
	v_lshl_add_u32 v216, v216, 6, v0
	ds_add_u32 v216, v205 offset:16384
.LBB0_662:
	s_cmp_gt_i32 s4, 3
	s_cselect_b64 s[56:57], -1, 0
	s_cmp_lt_i32 s4, 4
	s_cbranch_scc1 .LBB0_664
	ds_read_b128 v[230:233], v182
	ds_read_b128 v[234:237], v183
	ds_read_b32 v6, v137 offset:320
	s_waitcnt vmcnt(0)
	v_add_co_u32_e32 v22, vcc, s96, v22
	s_nop 1
	v_addc_co_u32_e32 v23, vcc, 0, v23, vcc
	global_load_dwordx4 v[42:45], v[22:23], off
	global_load_dwordx4 v[46:49], v[22:23], off offset:64
	global_load_dwordx4 v[50:53], v[22:23], off offset:2048
	global_load_dwordx4 v[2:5], v[22:23], off offset:2112
	s_waitcnt lgkmcnt(1)
	v_mfma_f32_16x16x32_bf16 v[246:249], v[26:29], v[230:233], 0
	v_mfma_f32_16x16x32_bf16 v[250:253], v[34:37], v[230:233], 0
	v_mfma_f32_16x16x32_bf16 v[246:249], v[30:33], v[234:237], v[246:249]
	v_mfma_f32_16x16x32_bf16 v[250:253], v[38:41], v[234:237], v[250:253]
	ds_read_b128 v[238:241], v184
	ds_read_b128 v[242:245], v185
	ds_read_b32 v7, v137 offset:384
	s_waitcnt lgkmcnt(1)
	v_mfma_f32_16x16x32_bf16 v[206:209], v[26:29], v[238:241], 0
	v_mfma_f32_16x16x32_bf16 v[210:213], v[34:37], v[238:241], 0
	v_mfma_f32_16x16x32_bf16 v[206:209], v[30:33], v[242:245], v[206:209]
	v_mfma_f32_16x16x32_bf16 v[210:213], v[38:41], v[242:245], v[210:213]
	ds_read_b128 v[230:233], v179
	ds_read_b128 v[234:237], v180
	ds_read_b32 v217, v137 offset:448
	v_max_f32_e32 v9, 0, v246
	v_max_f32_e32 v200, 0, v247
	v_max_f32_e32 v201, 0, v248
	v_max_f32_e32 v216, 0, v249
	v_mul_f32_e32 v110, v6, v9
	v_mul_f32_e32 v109, v6, v200
	v_mul_f32_e32 v112, v6, v201
	v_mul_f32_e32 v111, v6, v216
	v_max_f32_e32 v9, 0, v250
	v_max_f32_e32 v200, 0, v251
	v_max_f32_e32 v201, 0, v252
	v_max_f32_e32 v216, 0, v253
	v_mul_f32_e32 v114, v6, v9
	v_mul_f32_e32 v113, v6, v200
	v_mul_f32_e32 v116, v6, v201
	v_mul_f32_e32 v115, v6, v216
	s_waitcnt lgkmcnt(1)
	v_mfma_f32_16x16x32_bf16 v[246:249], v[26:29], v[230:233], 0
	v_mfma_f32_16x16x32_bf16 v[250:253], v[34:37], v[230:233], 0
	v_mfma_f32_16x16x32_bf16 v[246:249], v[30:33], v[234:237], v[246:249]
	v_mfma_f32_16x16x32_bf16 v[250:253], v[38:41], v[234:237], v[250:253]
	ds_read_b128 v[238:241], v176
	ds_read_b128 v[242:245], v159
	ds_read_b32 v6, v137 offset:512
	v_max_f32_e32 v9, 0, v206
	v_max_f32_e32 v200, 0, v207
	v_max_f32_e32 v201, 0, v208
	v_max_f32_e32 v216, 0, v209
	v_fmac_f32_e32 v110, v7, v9
	v_fmac_f32_e32 v109, v7, v200
	v_fmac_f32_e32 v112, v7, v201
	v_fmac_f32_e32 v111, v7, v216
	v_max_f32_e32 v9, 0, v210
	v_max_f32_e32 v200, 0, v211
	v_max_f32_e32 v201, 0, v212
	v_max_f32_e32 v216, 0, v213
	v_fmac_f32_e32 v114, v7, v9
	v_fmac_f32_e32 v113, v7, v200
	v_fmac_f32_e32 v116, v7, v201
	v_fmac_f32_e32 v115, v7, v216
	s_waitcnt lgkmcnt(1)
; #define LAS __attribute__((address_space(3)))
; #define SEL_HADD(idx_) __hip_atomic_fetch_add(&hist[(idx_)], 1u, __ATOMIC_RELAXED, __HIP_MEMORY_SCOPE_WORKGROUP)
; __device__ __forceinline__ unsigned fkey(float f) { const unsigned u = __float_as_uint(f); return (u & 0x80000000u) ? ~u : (u | 0x80000000u); }
; __device__ __forceinline__ void sel_unit(LAS char* lds, int b, int u, const bf16_t* QI, const bf16_t* KIDX, const float* WIDX, unsigned long long* MASK) {
;     ...
;             for (int kb = 0; kb < 2; ++kb) {
;                 f32x4 s = (f32x4){0.f, 0.f, 0.f, 0.f};
; #pragma unroll
;                 for (int hh = 0; hh < 8; ++hh) {
;                     f32x4 a = (f32x4){0.f, 0.f, 0.f, 0.f};
; #pragma unroll
;                     for (int ks = 0; ks < 2; ++ks) {
;                         const bf16x8 qv = *(const LAS bf16x8*)(lds + L_QI + q16 * 1024 + (((hh * 8 + 4 * ks + kg) ^ q16) << 4));
;                         a = __builtin_amdgcn_mfma_f32_16x16x32_bf16(kf[kb][ks], qv, a, 0, 0, 0);
;                     }
;                     const float wh = wl[hh * 16];
; #pragma unroll
;                     for (int i = 0; i < 4; ++i) s[i] += wh * fmaxf(a[i], 0.f);
;                 }
;                 u32x4 kk; kk.x = fkey(s[0]); kk.y = fkey(s[1]); kk.z = fkey(s[2]); kk.w = fkey(s[3]);
;                 sc[j][2 * kh + kb] = kk;
; #pragma unroll
;                 for (int i = 0; i < 4; ++i) SEL_HADD((kk[i] >> 24) * 16 + q16);
;                 __builtin_amdgcn_sched_barrier(0);
	v_mfma_f32_16x16x32_bf16 v[206:209], v[26:29], v[238:241], 0
	v_mfma_f32_16x16x32_bf16 v[210:213], v[34:37], v[238:241], 0
	v_mfma_f32_16x16x32_bf16 v[206:209], v[30:33], v[242:245], v[206:209]
	v_mfma_f32_16x16x32_bf16 v[210:213], v[38:41], v[242:245], v[210:213]
	ds_read_b128 v[230:233], v158
	ds_read_b128 v[234:237], v157
	ds_read_b32 v7, v137 offset:576
	v_max_f32_e32 v9, 0, v246
	v_max_f32_e32 v200, 0, v247
	v_max_f32_e32 v201, 0, v248
	v_max_f32_e32 v216, 0, v249
	v_fmac_f32_e32 v110, v217, v9
	v_fmac_f32_e32 v109, v217, v200
	v_fmac_f32_e32 v112, v217, v201
	v_fmac_f32_e32 v111, v217, v216
	v_max_f32_e32 v9, 0, v250
	v_max_f32_e32 v200, 0, v251
	v_max_f32_e32 v201, 0, v252
	v_max_f32_e32 v216, 0, v253
	v_fmac_f32_e32 v114, v217, v9
	v_fmac_f32_e32 v113, v217, v200
	v_fmac_f32_e32 v116, v217, v201
	v_fmac_f32_e32 v115, v217, v216
	s_waitcnt lgkmcnt(1)
	v_mfma_f32_16x16x32_bf16 v[246:249], v[26:29], v[230:233], 0
	v_mfma_f32_16x16x32_bf16 v[250:253], v[34:37], v[230:233], 0
	v_mfma_f32_16x16x32_bf16 v[246:249], v[30:33], v[234:237], v[246:249]
	v_mfma_f32_16x16x32_bf16 v[250:253], v[38:41], v[234:237], v[250:253]
	ds_read_b128 v[238:241], v156
	ds_read_b128 v[242:245], v155
	ds_read_b32 v217, v137 offset:640
	v_max_f32_e32 v9, 0, v206
	v_max_f32_e32 v200, 0, v207
	v_max_f32_e32 v201, 0, v208
	v_max_f32_e32 v216, 0, v209
	v_fmac_f32_e32 v110, v6, v9
	v_fmac_f32_e32 v109, v6, v200
	v_fmac_f32_e32 v112, v6, v201
	v_fmac_f32_e32 v111, v6, v216
	v_max_f32_e32 v9, 0, v210
	v_max_f32_e32 v200, 0, v211
	v_max_f32_e32 v201, 0, v212
	v_max_f32_e32 v216, 0, v213
	v_fmac_f32_e32 v114, v6, v9
	v_fmac_f32_e32 v113, v6, v200
	v_fmac_f32_e32 v116, v6, v201
	v_fmac_f32_e32 v115, v6, v216
	s_waitcnt lgkmcnt(1)
	v_mfma_f32_16x16x32_bf16 v[206:209], v[26:29], v[238:241], 0
	v_mfma_f32_16x16x32_bf16 v[210:213], v[34:37], v[238:241], 0
	v_mfma_f32_16x16x32_bf16 v[206:209], v[30:33], v[242:245], v[206:209]
	v_mfma_f32_16x16x32_bf16 v[210:213], v[38:41], v[242:245], v[210:213]
	ds_read_b128 v[230:233], v154
	ds_read_b128 v[234:237], v153
	ds_read_b32 v6, v137 offset:704
	v_max_f32_e32 v9, 0, v246
	v_max_f32_e32 v200, 0, v247
	v_max_f32_e32 v201, 0, v248
	v_max_f32_e32 v216, 0, v249
	v_fmac_f32_e32 v110, v7, v9
	v_fmac_f32_e32 v109, v7, v200
	v_fmac_f32_e32 v112, v7, v201
	v_fmac_f32_e32 v111, v7, v216
	v_max_f32_e32 v9, 0, v250
	v_max_f32_e32 v200, 0, v251
	v_max_f32_e32 v201, 0, v252
	v_max_f32_e32 v216, 0, v253
	v_fmac_f32_e32 v114, v7, v9
	v_fmac_f32_e32 v113, v7, v200
	v_fmac_f32_e32 v116, v7, v201
	v_fmac_f32_e32 v115, v7, v216
	s_waitcnt lgkmcnt(1)
	v_mfma_f32_16x16x32_bf16 v[246:249], v[26:29], v[230:233], 0
	v_mfma_f32_16x16x32_bf16 v[250:253], v[34:37], v[230:233], 0
	v_mfma_f32_16x16x32_bf16 v[246:249], v[30:33], v[234:237], v[246:249]
	v_mfma_f32_16x16x32_bf16 v[250:253], v[38:41], v[234:237], v[250:253]
	ds_read_b128 v[238:241], v152
	ds_read_b128 v[242:245], v151
	ds_read_b32 v7, v137 offset:768
	v_max_f32_e32 v9, 0, v206
	v_max_f32_e32 v200, 0, v207
	v_max_f32_e32 v201, 0, v208
	v_max_f32_e32 v216, 0, v209
	v_fmac_f32_e32 v110, v217, v9
	v_fmac_f32_e32 v109, v217, v200
	v_fmac_f32_e32 v112, v217, v201
	v_fmac_f32_e32 v111, v217, v216
	v_max_f32_e32 v9, 0, v210
	v_max_f32_e32 v200, 0, v211
	v_max_f32_e32 v201, 0, v212
	v_max_f32_e32 v216, 0, v213
	v_fmac_f32_e32 v114, v217, v9
	v_fmac_f32_e32 v113, v217, v200
	v_fmac_f32_e32 v116, v217, v201
	v_fmac_f32_e32 v115, v217, v216
	s_waitcnt lgkmcnt(1)
	v_mfma_f32_16x16x32_bf16 v[206:209], v[26:29], v[238:241], 0
	v_mfma_f32_16x16x32_bf16 v[210:213], v[34:37], v[238:241], 0
	v_mfma_f32_16x16x32_bf16 v[206:209], v[30:33], v[242:245], v[206:209]
	v_mfma_f32_16x16x32_bf16 v[210:213], v[38:41], v[242:245], v[210:213]
	v_max_f32_e32 v9, 0, v246
	v_max_f32_e32 v200, 0, v247
	v_max_f32_e32 v201, 0, v248
	v_max_f32_e32 v216, 0, v249
	v_fmac_f32_e32 v110, v6, v9
	v_fmac_f32_e32 v109, v6, v200
	v_fmac_f32_e32 v112, v6, v201
	v_fmac_f32_e32 v111, v6, v216
	v_max_f32_e32 v9, 0, v250
	v_max_f32_e32 v200, 0, v251
	v_max_f32_e32 v201, 0, v252
	v_max_f32_e32 v216, 0, v253
	v_fmac_f32_e32 v114, v6, v9
	v_fmac_f32_e32 v113, v6, v200
	v_fmac_f32_e32 v116, v6, v201
	v_fmac_f32_e32 v115, v6, v216
	s_waitcnt lgkmcnt(0)
	v_max_f32_e32 v9, 0, v206
	v_max_f32_e32 v200, 0, v207
	v_max_f32_e32 v201, 0, v208
	v_max_f32_e32 v216, 0, v209
	v_fmac_f32_e32 v110, v7, v9
	v_fmac_f32_e32 v109, v7, v200
	v_fmac_f32_e32 v112, v7, v201
	v_fmac_f32_e32 v111, v7, v216
	v_max_f32_e32 v9, 0, v210
	v_max_f32_e32 v200, 0, v211
	v_max_f32_e32 v201, 0, v212
	v_max_f32_e32 v216, 0, v213
	v_fmac_f32_e32 v114, v7, v9
	v_fmac_f32_e32 v113, v7, v200
	v_fmac_f32_e32 v116, v7, v201
	v_fmac_f32_e32 v115, v7, v216
	v_ashrrev_i32_e32 v9, 31, v110
	v_bitop3_b32 v110, v9, v110, v8 bitop3:0x36
	v_ashrrev_i32_e32 v200, 31, v109
	v_bitop3_b32 v109, v200, v109, v8 bitop3:0x36
	v_ashrrev_i32_e32 v201, 31, v112
	v_bitop3_b32 v112, v201, v112, v8 bitop3:0x36
	v_ashrrev_i32_e32 v216, 31, v111
	v_bitop3_b32 v111, v216, v111, v8 bitop3:0x36
	v_ashrrev_i32_e32 v9, 31, v114
	v_bitop3_b32 v114, v9, v114, v8 bitop3:0x36
	v_ashrrev_i32_e32 v200, 31, v113
	v_bitop3_b32 v113, v200, v113, v8 bitop3:0x36
	v_ashrrev_i32_e32 v201, 31, v116
	v_bitop3_b32 v116, v201, v116, v8 bitop3:0x36
	v_ashrrev_i32_e32 v216, 31, v115
	v_bitop3_b32 v115, v216, v115, v8 bitop3:0x36
	v_lshrrev_b32_e32 v9, 24, v110
	v_lshl_add_u32 v9, v9, 6, v0
	ds_add_u32 v9, v205 offset:16384
	v_lshrrev_b32_e32 v200, 24, v109
	v_lshl_add_u32 v200, v200, 6, v0
	ds_add_u32 v200, v205 offset:16384
	v_lshrrev_b32_e32 v201, 24, v112
	v_lshl_add_u32 v201, v201, 6, v0
	ds_add_u32 v201, v205 offset:16384
	v_lshrrev_b32_e32 v216, 24, v111
	v_lshl_add_u32 v216, v216, 6, v0
	ds_add_u32 v216, v205 offset:16384
	v_lshrrev_b32_e32 v9, 24, v114
	v_lshl_add_u32 v9, v9, 6, v0
	ds_add_u32 v9, v205 offset:16384
	v_lshrrev_b32_e32 v200, 24, v113
	v_lshl_add_u32 v200, v200, 6, v0
	ds_add_u32 v200, v205 offset:16384
	v_lshrrev_b32_e32 v201, 24, v116
	v_lshl_add_u32 v201, v201, 6, v0
	ds_add_u32 v201, v205 offset:16384
	v_lshrrev_b32_e32 v216, 24, v115
	v_lshl_add_u32 v216, v216, 6, v0
	ds_add_u32 v216, v205 offset:16384
	ds_read_b128 v[230:233], v182
	ds_read_b128 v[234:237], v183
	ds_read_b32 v6, v137 offset:320
	s_waitcnt vmcnt(0)
	s_cmp_lt_i32 s4, 5
	s_cbranch_scc1 .Lp0_nopf_3
	v_add_co_u32_e32 v22, vcc, 0xf000, v22
	s_nop 1
	v_addc_co_u32_e32 v23, vcc, 0, v23, vcc
	global_load_dwordx4 v[26:29], v[22:23], off
	global_load_dwordx4 v[30:33], v[22:23], off offset:64
	global_load_dwordx4 v[34:37], v[22:23], off offset:2048
	global_load_dwordx4 v[38:41], v[22:23], off offset:2112
; #define LAS __attribute__((address_space(3)))
; __device__ __forceinline__ void sel_unit(LAS char* lds, int b, int u, const bf16_t* QI, const bf16_t* KIDX, const float* WIDX, unsigned long long* MASK) {
;     ...
;             for (int kb = 0; kb < 2; ++kb) {
;                 f32x4 s = (f32x4){0.f, 0.f, 0.f, 0.f};
; #pragma unroll
;                 for (int hh = 0; hh < 8; ++hh) {
;                     f32x4 a = (f32x4){0.f, 0.f, 0.f, 0.f};
; #pragma unroll
;                     for (int ks = 0; ks < 2; ++ks) {
;                         const bf16x8 qv = *(const LAS bf16x8*)(lds + L_QI + q16 * 1024 + (((hh * 8 + 4 * ks + kg) ^ q16) << 4));
;                         a = __builtin_amdgcn_mfma_f32_16x16x32_bf16(kf[kb][ks], qv, a, 0, 0, 0);
;                     }
;                     const float wh = wl[hh * 16];
; #pragma unroll
;                     for (int i = 0; i < 4; ++i) s[i] += wh * fmaxf(a[i], 0.f);
;                 }
.Lp0_nopf_3:
	s_waitcnt lgkmcnt(1)
	v_mfma_f32_16x16x32_bf16 v[246:249], v[42:45], v[230:233], 0
	v_mfma_f32_16x16x32_bf16 v[250:253], v[50:53], v[230:233], 0
	v_mfma_f32_16x16x32_bf16 v[246:249], v[46:49], v[234:237], v[246:249]
	v_mfma_f32_16x16x32_bf16 v[250:253], v[2:5], v[234:237], v[250:253]
	ds_read_b128 v[238:241], v184
	ds_read_b128 v[242:245], v185
	ds_read_b32 v7, v137 offset:384
	s_waitcnt lgkmcnt(1)
	v_mfma_f32_16x16x32_bf16 v[206:209], v[42:45], v[238:241], 0
	v_mfma_f32_16x16x32_bf16 v[210:213], v[50:53], v[238:241], 0
	v_mfma_f32_16x16x32_bf16 v[206:209], v[46:49], v[242:245], v[206:209]
	v_mfma_f32_16x16x32_bf16 v[210:213], v[2:5], v[242:245], v[210:213]
	ds_read_b128 v[230:233], v179
	ds_read_b128 v[234:237], v180
	ds_read_b32 v217, v137 offset:448
	v_max_f32_e32 v9, 0, v246
	v_max_f32_e32 v200, 0, v247
	v_max_f32_e32 v201, 0, v248
	v_max_f32_e32 v216, 0, v249
	v_mul_f32_e32 v118, v6, v9
	v_mul_f32_e32 v117, v6, v200
	v_mul_f32_e32 v120, v6, v201
	v_mul_f32_e32 v119, v6, v216
	v_max_f32_e32 v9, 0, v250
	v_max_f32_e32 v200, 0, v251
	v_max_f32_e32 v201, 0, v252
	v_max_f32_e32 v216, 0, v253
	v_mul_f32_e32 v122, v6, v9
	v_mul_f32_e32 v121, v6, v200
	v_mul_f32_e32 v124, v6, v201
	v_mul_f32_e32 v123, v6, v216
	s_waitcnt lgkmcnt(1)
	v_mfma_f32_16x16x32_bf16 v[246:249], v[42:45], v[230:233], 0
	v_mfma_f32_16x16x32_bf16 v[250:253], v[50:53], v[230:233], 0
	v_mfma_f32_16x16x32_bf16 v[246:249], v[46:49], v[234:237], v[246:249]
	v_mfma_f32_16x16x32_bf16 v[250:253], v[2:5], v[234:237], v[250:253]
	ds_read_b128 v[238:241], v176
	ds_read_b128 v[242:245], v159
	ds_read_b32 v6, v137 offset:512
	v_max_f32_e32 v9, 0, v206
	v_max_f32_e32 v200, 0, v207
	v_max_f32_e32 v201, 0, v208
	v_max_f32_e32 v216, 0, v209
	v_fmac_f32_e32 v118, v7, v9
	v_fmac_f32_e32 v117, v7, v200
	v_fmac_f32_e32 v120, v7, v201
	v_fmac_f32_e32 v119, v7, v216
	v_max_f32_e32 v9, 0, v210
	v_max_f32_e32 v200, 0, v211
	v_max_f32_e32 v201, 0, v212
	v_max_f32_e32 v216, 0, v213
	v_fmac_f32_e32 v122, v7, v9
	v_fmac_f32_e32 v121, v7, v200
	v_fmac_f32_e32 v124, v7, v201
	v_fmac_f32_e32 v123, v7, v216
	s_waitcnt lgkmcnt(1)
	v_mfma_f32_16x16x32_bf16 v[206:209], v[42:45], v[238:241], 0
	v_mfma_f32_16x16x32_bf16 v[210:213], v[50:53], v[238:241], 0
	v_mfma_f32_16x16x32_bf16 v[206:209], v[46:49], v[242:245], v[206:209]
	v_mfma_f32_16x16x32_bf16 v[210:213], v[2:5], v[242:245], v[210:213]
	ds_read_b128 v[230:233], v158
	ds_read_b128 v[234:237], v157
	ds_read_b32 v7, v137 offset:576
	v_max_f32_e32 v9, 0, v246
	v_max_f32_e32 v200, 0, v247
	v_max_f32_e32 v201, 0, v248
	v_max_f32_e32 v216, 0, v249
	v_fmac_f32_e32 v118, v217, v9
	v_fmac_f32_e32 v117, v217, v200
	v_fmac_f32_e32 v120, v217, v201
	v_fmac_f32_e32 v119, v217, v216
	v_max_f32_e32 v9, 0, v250
	v_max_f32_e32 v200, 0, v251
	v_max_f32_e32 v201, 0, v252
	v_max_f32_e32 v216, 0, v253
	v_fmac_f32_e32 v122, v217, v9
	v_fmac_f32_e32 v121, v217, v200
	v_fmac_f32_e32 v124, v217, v201
	v_fmac_f32_e32 v123, v217, v216
	s_waitcnt lgkmcnt(1)
	v_mfma_f32_16x16x32_bf16 v[246:249], v[42:45], v[230:233], 0
	v_mfma_f32_16x16x32_bf16 v[250:253], v[50:53], v[230:233], 0
	v_mfma_f32_16x16x32_bf16 v[246:249], v[46:49], v[234:237], v[246:249]
	v_mfma_f32_16x16x32_bf16 v[250:253], v[2:5], v[234:237], v[250:253]
	ds_read_b128 v[238:241], v156
	ds_read_b128 v[242:245], v155
	ds_read_b32 v217, v137 offset:640
	v_max_f32_e32 v9, 0, v206
	v_max_f32_e32 v200, 0, v207
	v_max_f32_e32 v201, 0, v208
	v_max_f32_e32 v216, 0, v209
	v_fmac_f32_e32 v118, v6, v9
	v_fmac_f32_e32 v117, v6, v200
	v_fmac_f32_e32 v120, v6, v201
	v_fmac_f32_e32 v119, v6, v216
	v_max_f32_e32 v9, 0, v210
	v_max_f32_e32 v200, 0, v211
	v_max_f32_e32 v201, 0, v212
	v_max_f32_e32 v216, 0, v213
	v_fmac_f32_e32 v122, v6, v9
	v_fmac_f32_e32 v121, v6, v200
	v_fmac_f32_e32 v124, v6, v201
	v_fmac_f32_e32 v123, v6, v216
	s_waitcnt lgkmcnt(1)
	v_mfma_f32_16x16x32_bf16 v[206:209], v[42:45], v[238:241], 0
	v_mfma_f32_16x16x32_bf16 v[210:213], v[50:53], v[238:241], 0
	v_mfma_f32_16x16x32_bf16 v[206:209], v[46:49], v[242:245], v[206:209]
	v_mfma_f32_16x16x32_bf16 v[210:213], v[2:5], v[242:245], v[210:213]
	ds_read_b128 v[230:233], v154
	ds_read_b128 v[234:237], v153
	ds_read_b32 v6, v137 offset:704
	v_max_f32_e32 v9, 0, v246
	v_max_f32_e32 v200, 0, v247
	v_max_f32_e32 v201, 0, v248
	v_max_f32_e32 v216, 0, v249
	v_fmac_f32_e32 v118, v7, v9
	v_fmac_f32_e32 v117, v7, v200
	v_fmac_f32_e32 v120, v7, v201
	v_fmac_f32_e32 v119, v7, v216
	v_max_f32_e32 v9, 0, v250
	v_max_f32_e32 v200, 0, v251
	v_max_f32_e32 v201, 0, v252
	v_max_f32_e32 v216, 0, v253
	v_fmac_f32_e32 v122, v7, v9
	v_fmac_f32_e32 v121, v7, v200
	v_fmac_f32_e32 v124, v7, v201
	v_fmac_f32_e32 v123, v7, v216
	s_waitcnt lgkmcnt(1)
	v_mfma_f32_16x16x32_bf16 v[246:249], v[42:45], v[230:233], 0
	v_mfma_f32_16x16x32_bf16 v[250:253], v[50:53], v[230:233], 0
	v_mfma_f32_16x16x32_bf16 v[246:249], v[46:49], v[234:237], v[246:249]
	v_mfma_f32_16x16x32_bf16 v[250:253], v[2:5], v[234:237], v[250:253]
	ds_read_b128 v[238:241], v152
	ds_read_b128 v[242:245], v151
	ds_read_b32 v7, v137 offset:768
	v_max_f32_e32 v9, 0, v206
	v_max_f32_e32 v200, 0, v207
	v_max_f32_e32 v201, 0, v208
	v_max_f32_e32 v216, 0, v209
	v_fmac_f32_e32 v118, v217, v9
	v_fmac_f32_e32 v117, v217, v200
	v_fmac_f32_e32 v120, v217, v201
	v_fmac_f32_e32 v119, v217, v216
	v_max_f32_e32 v9, 0, v210
	v_max_f32_e32 v200, 0, v211
	v_max_f32_e32 v201, 0, v212
	v_max_f32_e32 v216, 0, v213
	v_fmac_f32_e32 v122, v217, v9
	v_fmac_f32_e32 v121, v217, v200
	v_fmac_f32_e32 v124, v217, v201
	v_fmac_f32_e32 v123, v217, v216
	s_waitcnt lgkmcnt(1)
; #define LAS __attribute__((address_space(3)))
; #define SEL_HADD(idx_) __hip_atomic_fetch_add(&hist[(idx_)], 1u, __ATOMIC_RELAXED, __HIP_MEMORY_SCOPE_WORKGROUP)
; __device__ __forceinline__ unsigned fkey(float f) { const unsigned u = __float_as_uint(f); return (u & 0x80000000u) ? ~u : (u | 0x80000000u); }
; __device__ __forceinline__ void sel_unit(LAS char* lds, int b, int u, const bf16_t* QI, const bf16_t* KIDX, const float* WIDX, unsigned long long* MASK) {
;     ...
;             for (int kb = 0; kb < 2; ++kb) {
;                 f32x4 s = (f32x4){0.f, 0.f, 0.f, 0.f};
; #pragma unroll
;                 for (int hh = 0; hh < 8; ++hh) {
;                     f32x4 a = (f32x4){0.f, 0.f, 0.f, 0.f};
; #pragma unroll
;                     for (int ks = 0; ks < 2; ++ks) {
;                         const bf16x8 qv = *(const LAS bf16x8*)(lds + L_QI + q16 * 1024 + (((hh * 8 + 4 * ks + kg) ^ q16) << 4));
;                         a = __builtin_amdgcn_mfma_f32_16x16x32_bf16(kf[kb][ks], qv, a, 0, 0, 0);
;                     }
;                     const float wh = wl[hh * 16];
; #pragma unroll
;                     for (int i = 0; i < 4; ++i) s[i] += wh * fmaxf(a[i], 0.f);
;                 }
;                 u32x4 kk; kk.x = fkey(s[0]); kk.y = fkey(s[1]); kk.z = fkey(s[2]); kk.w = fkey(s[3]);
;                 sc[j][2 * kh + kb] = kk;
; #pragma unroll
;                 for (int i = 0; i < 4; ++i) SEL_HADD((kk[i] >> 24) * 16 + q16);
;                 __builtin_amdgcn_sched_barrier(0);
	v_mfma_f32_16x16x32_bf16 v[206:209], v[42:45], v[238:241], 0
	v_mfma_f32_16x16x32_bf16 v[210:213], v[50:53], v[238:241], 0
	v_mfma_f32_16x16x32_bf16 v[206:209], v[46:49], v[242:245], v[206:209]
	v_mfma_f32_16x16x32_bf16 v[210:213], v[2:5], v[242:245], v[210:213]
	v_max_f32_e32 v9, 0, v246
	v_max_f32_e32 v200, 0, v247
	v_max_f32_e32 v201, 0, v248
	v_max_f32_e32 v216, 0, v249
	v_fmac_f32_e32 v118, v6, v9
	v_fmac_f32_e32 v117, v6, v200
	v_fmac_f32_e32 v120, v6, v201
	v_fmac_f32_e32 v119, v6, v216
	v_max_f32_e32 v9, 0, v250
	v_max_f32_e32 v200, 0, v251
	v_max_f32_e32 v201, 0, v252
	v_max_f32_e32 v216, 0, v253
	v_fmac_f32_e32 v122, v6, v9
	v_fmac_f32_e32 v121, v6, v200
	v_fmac_f32_e32 v124, v6, v201
	v_fmac_f32_e32 v123, v6, v216
	s_waitcnt lgkmcnt(0)
	v_max_f32_e32 v9, 0, v206
	v_max_f32_e32 v200, 0, v207
	v_max_f32_e32 v201, 0, v208
	v_max_f32_e32 v216, 0, v209
	v_fmac_f32_e32 v118, v7, v9
	v_fmac_f32_e32 v117, v7, v200
	v_fmac_f32_e32 v120, v7, v201
	v_fmac_f32_e32 v119, v7, v216
	v_max_f32_e32 v9, 0, v210
	v_max_f32_e32 v200, 0, v211
	v_max_f32_e32 v201, 0, v212
	v_max_f32_e32 v216, 0, v213
	v_fmac_f32_e32 v122, v7, v9
	v_fmac_f32_e32 v121, v7, v200
	v_fmac_f32_e32 v124, v7, v201
	v_fmac_f32_e32 v123, v7, v216
	v_ashrrev_i32_e32 v9, 31, v118
	v_bitop3_b32 v118, v9, v118, v8 bitop3:0x36
	v_ashrrev_i32_e32 v200, 31, v117
	v_bitop3_b32 v117, v200, v117, v8 bitop3:0x36
	v_ashrrev_i32_e32 v201, 31, v120
	v_bitop3_b32 v120, v201, v120, v8 bitop3:0x36
	v_ashrrev_i32_e32 v216, 31, v119
	v_bitop3_b32 v119, v216, v119, v8 bitop3:0x36
	v_ashrrev_i32_e32 v9, 31, v122
	v_bitop3_b32 v122, v9, v122, v8 bitop3:0x36
	v_ashrrev_i32_e32 v200, 31, v121
	v_bitop3_b32 v121, v200, v121, v8 bitop3:0x36
	v_ashrrev_i32_e32 v201, 31, v124
	v_bitop3_b32 v124, v201, v124, v8 bitop3:0x36
	v_ashrrev_i32_e32 v216, 31, v123
	v_bitop3_b32 v123, v216, v123, v8 bitop3:0x36
	v_lshrrev_b32_e32 v9, 24, v118
	v_lshl_add_u32 v9, v9, 6, v0
	ds_add_u32 v9, v205 offset:16384
	v_lshrrev_b32_e32 v200, 24, v117
	v_lshl_add_u32 v200, v200, 6, v0
	ds_add_u32 v200, v205 offset:16384
	v_lshrrev_b32_e32 v201, 24, v120
	v_lshl_add_u32 v201, v201, 6, v0
	ds_add_u32 v201, v205 offset:16384
	v_lshrrev_b32_e32 v216, 24, v119
	v_lshl_add_u32 v216, v216, 6, v0
	ds_add_u32 v216, v205 offset:16384
	v_lshrrev_b32_e32 v9, 24, v122
	v_lshl_add_u32 v9, v9, 6, v0
	ds_add_u32 v9, v205 offset:16384
	v_lshrrev_b32_e32 v200, 24, v121
	v_lshl_add_u32 v200, v200, 6, v0
	ds_add_u32 v200, v205 offset:16384
	v_lshrrev_b32_e32 v201, 24, v124
	v_lshl_add_u32 v201, v201, 6, v0
	ds_add_u32 v201, v205 offset:16384
	v_lshrrev_b32_e32 v216, 24, v123
	v_lshl_add_u32 v216, v216, 6, v0
	ds_add_u32 v216, v205 offset:16384
.LBB0_664:
	s_cmp_gt_i32 s4, 4
	s_cselect_b64 s[24:25], -1, 0
	s_cmp_lt_i32 s4, 5
	s_cbranch_scc1 .LBB0_666
	ds_read_b128 v[230:233], v182
	ds_read_b128 v[234:237], v183
	ds_read_b32 v6, v137 offset:320
	s_waitcnt vmcnt(0)
	v_add_co_u32_e32 v22, vcc, s96, v22
	s_nop 1
	v_addc_co_u32_e32 v23, vcc, 0, v23, vcc
	global_load_dwordx4 v[42:45], v[22:23], off
	global_load_dwordx4 v[46:49], v[22:23], off offset:64
	global_load_dwordx4 v[50:53], v[22:23], off offset:2048
	global_load_dwordx4 v[2:5], v[22:23], off offset:2112
	s_waitcnt lgkmcnt(1)
	v_mfma_f32_16x16x32_bf16 v[246:249], v[26:29], v[230:233], 0
	v_mfma_f32_16x16x32_bf16 v[250:253], v[34:37], v[230:233], 0
	v_mfma_f32_16x16x32_bf16 v[246:249], v[30:33], v[234:237], v[246:249]
	v_mfma_f32_16x16x32_bf16 v[250:253], v[38:41], v[234:237], v[250:253]
	ds_read_b128 v[238:241], v184
	ds_read_b128 v[242:245], v185
	ds_read_b32 v7, v137 offset:384
	s_waitcnt lgkmcnt(1)
	v_mfma_f32_16x16x32_bf16 v[206:209], v[26:29], v[238:241], 0
	v_mfma_f32_16x16x32_bf16 v[210:213], v[34:37], v[238:241], 0
	v_mfma_f32_16x16x32_bf16 v[206:209], v[30:33], v[242:245], v[206:209]
	v_mfma_f32_16x16x32_bf16 v[210:213], v[38:41], v[242:245], v[210:213]
	ds_read_b128 v[230:233], v179
	ds_read_b128 v[234:237], v180
	ds_read_b32 v217, v137 offset:448
	v_max_f32_e32 v9, 0, v246
	v_max_f32_e32 v200, 0, v247
	v_max_f32_e32 v201, 0, v248
	v_max_f32_e32 v216, 0, v249
	v_mul_f32_e32 v126, v6, v9
	v_mul_f32_e32 v125, v6, v200
	v_mul_f32_e32 v128, v6, v201
	v_mul_f32_e32 v127, v6, v216
	v_max_f32_e32 v9, 0, v250
	v_max_f32_e32 v200, 0, v251
	v_max_f32_e32 v201, 0, v252
	v_max_f32_e32 v216, 0, v253
	v_mul_f32_e32 v130, v6, v9
	v_mul_f32_e32 v129, v6, v200
	v_mul_f32_e32 v132, v6, v201
	v_mul_f32_e32 v131, v6, v216
	s_waitcnt lgkmcnt(1)
	v_mfma_f32_16x16x32_bf16 v[246:249], v[26:29], v[230:233], 0
	v_mfma_f32_16x16x32_bf16 v[250:253], v[34:37], v[230:233], 0
	v_mfma_f32_16x16x32_bf16 v[246:249], v[30:33], v[234:237], v[246:249]
	v_mfma_f32_16x16x32_bf16 v[250:253], v[38:41], v[234:237], v[250:253]
	ds_read_b128 v[238:241], v176
	ds_read_b128 v[242:245], v159
	ds_read_b32 v6, v137 offset:512
	v_max_f32_e32 v9, 0, v206
	v_max_f32_e32 v200, 0, v207
	v_max_f32_e32 v201, 0, v208
	v_max_f32_e32 v216, 0, v209
	v_fmac_f32_e32 v126, v7, v9
	v_fmac_f32_e32 v125, v7, v200
	v_fmac_f32_e32 v128, v7, v201
	v_fmac_f32_e32 v127, v7, v216
	v_max_f32_e32 v9, 0, v210
	v_max_f32_e32 v200, 0, v211
	v_max_f32_e32 v201, 0, v212
	v_max_f32_e32 v216, 0, v213
	v_fmac_f32_e32 v130, v7, v9
	v_fmac_f32_e32 v129, v7, v200
	v_fmac_f32_e32 v132, v7, v201
	v_fmac_f32_e32 v131, v7, v216
	s_waitcnt lgkmcnt(1)
; #define LAS __attribute__((address_space(3)))
; #define SEL_HADD(idx_) __hip_atomic_fetch_add(&hist[(idx_)], 1u, __ATOMIC_RELAXED, __HIP_MEMORY_SCOPE_WORKGROUP)
; __device__ __forceinline__ unsigned fkey(float f) { const unsigned u = __float_as_uint(f); return (u & 0x80000000u) ? ~u : (u | 0x80000000u); }
; __device__ __forceinline__ void sel_unit(LAS char* lds, int b, int u, const bf16_t* QI, const bf16_t* KIDX, const float* WIDX, unsigned long long* MASK) {
;     ...
;             for (int kb = 0; kb < 2; ++kb) {
;                 f32x4 s = (f32x4){0.f, 0.f, 0.f, 0.f};
; #pragma unroll
;                 for (int hh = 0; hh < 8; ++hh) {
;                     f32x4 a = (f32x4){0.f, 0.f, 0.f, 0.f};
; #pragma unroll
;                     for (int ks = 0; ks < 2; ++ks) {
;                         const bf16x8 qv = *(const LAS bf16x8*)(lds + L_QI + q16 * 1024 + (((hh * 8 + 4 * ks + kg) ^ q16) << 4));
;                         a = __builtin_amdgcn_mfma_f32_16x16x32_bf16(kf[kb][ks], qv, a, 0, 0, 0);
;                     }
;                     const float wh = wl[hh * 16];
; #pragma unroll
;                     for (int i = 0; i < 4; ++i) s[i] += wh * fmaxf(a[i], 0.f);
;                 }
;                 u32x4 kk; kk.x = fkey(s[0]); kk.y = fkey(s[1]); kk.z = fkey(s[2]); kk.w = fkey(s[3]);
;                 sc[j][2 * kh + kb] = kk;
; #pragma unroll
;                 for (int i = 0; i < 4; ++i) SEL_HADD((kk[i] >> 24) * 16 + q16);
;                 __builtin_amdgcn_sched_barrier(0);
	v_mfma_f32_16x16x32_bf16 v[206:209], v[26:29], v[238:241], 0
	v_mfma_f32_16x16x32_bf16 v[210:213], v[34:37], v[238:241], 0
	v_mfma_f32_16x16x32_bf16 v[206:209], v[30:33], v[242:245], v[206:209]
	v_mfma_f32_16x16x32_bf16 v[210:213], v[38:41], v[242:245], v[210:213]
	ds_read_b128 v[230:233], v158
	ds_read_b128 v[234:237], v157
	ds_read_b32 v7, v137 offset:576
	v_max_f32_e32 v9, 0, v246
	v_max_f32_e32 v200, 0, v247
	v_max_f32_e32 v201, 0, v248
	v_max_f32_e32 v216, 0, v249
	v_fmac_f32_e32 v126, v217, v9
	v_fmac_f32_e32 v125, v217, v200
	v_fmac_f32_e32 v128, v217, v201
	v_fmac_f32_e32 v127, v217, v216
	v_max_f32_e32 v9, 0, v250
	v_max_f32_e32 v200, 0, v251
	v_max_f32_e32 v201, 0, v252
	v_max_f32_e32 v216, 0, v253
	v_fmac_f32_e32 v130, v217, v9
	v_fmac_f32_e32 v129, v217, v200
	v_fmac_f32_e32 v132, v217, v201
	v_fmac_f32_e32 v131, v217, v216
	s_waitcnt lgkmcnt(1)
	v_mfma_f32_16x16x32_bf16 v[246:249], v[26:29], v[230:233], 0
	v_mfma_f32_16x16x32_bf16 v[250:253], v[34:37], v[230:233], 0
	v_mfma_f32_16x16x32_bf16 v[246:249], v[30:33], v[234:237], v[246:249]
	v_mfma_f32_16x16x32_bf16 v[250:253], v[38:41], v[234:237], v[250:253]
	ds_read_b128 v[238:241], v156
	ds_read_b128 v[242:245], v155
	ds_read_b32 v217, v137 offset:640
	v_max_f32_e32 v9, 0, v206
	v_max_f32_e32 v200, 0, v207
	v_max_f32_e32 v201, 0, v208
	v_max_f32_e32 v216, 0, v209
	v_fmac_f32_e32 v126, v6, v9
	v_fmac_f32_e32 v125, v6, v200
	v_fmac_f32_e32 v128, v6, v201
	v_fmac_f32_e32 v127, v6, v216
	v_max_f32_e32 v9, 0, v210
	v_max_f32_e32 v200, 0, v211
	v_max_f32_e32 v201, 0, v212
	v_max_f32_e32 v216, 0, v213
	v_fmac_f32_e32 v130, v6, v9
	v_fmac_f32_e32 v129, v6, v200
	v_fmac_f32_e32 v132, v6, v201
	v_fmac_f32_e32 v131, v6, v216
	s_waitcnt lgkmcnt(1)
	v_mfma_f32_16x16x32_bf16 v[206:209], v[26:29], v[238:241], 0
	v_mfma_f32_16x16x32_bf16 v[210:213], v[34:37], v[238:241], 0
	v_mfma_f32_16x16x32_bf16 v[206:209], v[30:33], v[242:245], v[206:209]
	v_mfma_f32_16x16x32_bf16 v[210:213], v[38:41], v[242:245], v[210:213]
	ds_read_b128 v[230:233], v154
	ds_read_b128 v[234:237], v153
	ds_read_b32 v6, v137 offset:704
	v_max_f32_e32 v9, 0, v246
	v_max_f32_e32 v200, 0, v247
	v_max_f32_e32 v201, 0, v248
	v_max_f32_e32 v216, 0, v249
	v_fmac_f32_e32 v126, v7, v9
	v_fmac_f32_e32 v125, v7, v200
	v_fmac_f32_e32 v128, v7, v201
	v_fmac_f32_e32 v127, v7, v216
	v_max_f32_e32 v9, 0, v250
	v_max_f32_e32 v200, 0, v251
	v_max_f32_e32 v201, 0, v252
	v_max_f32_e32 v216, 0, v253
	v_fmac_f32_e32 v130, v7, v9
	v_fmac_f32_e32 v129, v7, v200
	v_fmac_f32_e32 v132, v7, v201
	v_fmac_f32_e32 v131, v7, v216
	s_waitcnt lgkmcnt(1)
	v_mfma_f32_16x16x32_bf16 v[246:249], v[26:29], v[230:233], 0
	v_mfma_f32_16x16x32_bf16 v[250:253], v[34:37], v[230:233], 0
	v_mfma_f32_16x16x32_bf16 v[246:249], v[30:33], v[234:237], v[246:249]
	v_mfma_f32_16x16x32_bf16 v[250:253], v[38:41], v[234:237], v[250:253]
	ds_read_b128 v[238:241], v152
	ds_read_b128 v[242:245], v151
	ds_read_b32 v7, v137 offset:768
	v_max_f32_e32 v9, 0, v206
	v_max_f32_e32 v200, 0, v207
	v_max_f32_e32 v201, 0, v208
	v_max_f32_e32 v216, 0, v209
	v_fmac_f32_e32 v126, v217, v9
	v_fmac_f32_e32 v125, v217, v200
	v_fmac_f32_e32 v128, v217, v201
	v_fmac_f32_e32 v127, v217, v216
	v_max_f32_e32 v9, 0, v210
	v_max_f32_e32 v200, 0, v211
	v_max_f32_e32 v201, 0, v212
	v_max_f32_e32 v216, 0, v213
	v_fmac_f32_e32 v130, v217, v9
	v_fmac_f32_e32 v129, v217, v200
	v_fmac_f32_e32 v132, v217, v201
	v_fmac_f32_e32 v131, v217, v216
	s_waitcnt lgkmcnt(1)
	v_mfma_f32_16x16x32_bf16 v[206:209], v[26:29], v[238:241], 0
	v_mfma_f32_16x16x32_bf16 v[210:213], v[34:37], v[238:241], 0
	v_mfma_f32_16x16x32_bf16 v[206:209], v[30:33], v[242:245], v[206:209]
	v_mfma_f32_16x16x32_bf16 v[210:213], v[38:41], v[242:245], v[210:213]
	v_max_f32_e32 v9, 0, v246
	v_max_f32_e32 v200, 0, v247
	v_max_f32_e32 v201, 0, v248
	v_max_f32_e32 v216, 0, v249
	v_fmac_f32_e32 v126, v6, v9
	v_fmac_f32_e32 v125, v6, v200
	v_fmac_f32_e32 v128, v6, v201
	v_fmac_f32_e32 v127, v6, v216
	v_max_f32_e32 v9, 0, v250
	v_max_f32_e32 v200, 0, v251
	v_max_f32_e32 v201, 0, v252
	v_max_f32_e32 v216, 0, v253
	v_fmac_f32_e32 v130, v6, v9
	v_fmac_f32_e32 v129, v6, v200
	v_fmac_f32_e32 v132, v6, v201
	v_fmac_f32_e32 v131, v6, v216
	s_waitcnt lgkmcnt(0)
	v_max_f32_e32 v9, 0, v206
	v_max_f32_e32 v200, 0, v207
	v_max_f32_e32 v201, 0, v208
	v_max_f32_e32 v216, 0, v209
	v_fmac_f32_e32 v126, v7, v9
	v_fmac_f32_e32 v125, v7, v200
	v_fmac_f32_e32 v128, v7, v201
	v_fmac_f32_e32 v127, v7, v216
	v_max_f32_e32 v9, 0, v210
	v_max_f32_e32 v200, 0, v211
	v_max_f32_e32 v201, 0, v212
	v_max_f32_e32 v216, 0, v213
	v_fmac_f32_e32 v130, v7, v9
	v_fmac_f32_e32 v129, v7, v200
	v_fmac_f32_e32 v132, v7, v201
	v_fmac_f32_e32 v131, v7, v216
	v_ashrrev_i32_e32 v9, 31, v126
	v_bitop3_b32 v126, v9, v126, v8 bitop3:0x36
	v_ashrrev_i32_e32 v200, 31, v125
	v_bitop3_b32 v125, v200, v125, v8 bitop3:0x36
	v_ashrrev_i32_e32 v201, 31, v128
	v_bitop3_b32 v128, v201, v128, v8 bitop3:0x36
	v_ashrrev_i32_e32 v216, 31, v127
	v_bitop3_b32 v127, v216, v127, v8 bitop3:0x36
	v_ashrrev_i32_e32 v9, 31, v130
	v_bitop3_b32 v130, v9, v130, v8 bitop3:0x36
	v_ashrrev_i32_e32 v200, 31, v129
	v_bitop3_b32 v129, v200, v129, v8 bitop3:0x36
	v_ashrrev_i32_e32 v201, 31, v132
	v_bitop3_b32 v132, v201, v132, v8 bitop3:0x36
	v_ashrrev_i32_e32 v216, 31, v131
	v_bitop3_b32 v131, v216, v131, v8 bitop3:0x36
	v_lshrrev_b32_e32 v9, 24, v126
	v_lshl_add_u32 v9, v9, 6, v0
	ds_add_u32 v9, v205 offset:16384
	v_lshrrev_b32_e32 v200, 24, v125
	v_lshl_add_u32 v200, v200, 6, v0
	ds_add_u32 v200, v205 offset:16384
	v_lshrrev_b32_e32 v201, 24, v128
	v_lshl_add_u32 v201, v201, 6, v0
	ds_add_u32 v201, v205 offset:16384
	v_lshrrev_b32_e32 v216, 24, v127
	v_lshl_add_u32 v216, v216, 6, v0
	ds_add_u32 v216, v205 offset:16384
	v_lshrrev_b32_e32 v9, 24, v130
	v_lshl_add_u32 v9, v9, 6, v0
	ds_add_u32 v9, v205 offset:16384
	v_lshrrev_b32_e32 v200, 24, v129
	v_lshl_add_u32 v200, v200, 6, v0
	ds_add_u32 v200, v205 offset:16384
	v_lshrrev_b32_e32 v201, 24, v132
	v_lshl_add_u32 v201, v201, 6, v0
	ds_add_u32 v201, v205 offset:16384
	v_lshrrev_b32_e32 v216, 24, v131
	v_lshl_add_u32 v216, v216, 6, v0
	ds_add_u32 v216, v205 offset:16384
	ds_read_b128 v[230:233], v182
	ds_read_b128 v[234:237], v183
	ds_read_b32 v6, v137 offset:320
	s_waitcnt vmcnt(0)
	s_cmp_lt_i32 s4, 6
	s_cbranch_scc1 .Lp0_nopf_4
	v_add_co_u32_e32 v22, vcc, 0xf000, v22
	s_nop 1
	v_addc_co_u32_e32 v23, vcc, 0, v23, vcc
	global_load_dwordx4 v[26:29], v[22:23], off
	global_load_dwordx4 v[30:33], v[22:23], off offset:64
	global_load_dwordx4 v[34:37], v[22:23], off offset:2048
	global_load_dwordx4 v[38:41], v[22:23], off offset:2112
; #define LAS __attribute__((address_space(3)))
; __device__ __forceinline__ unsigned fkey(float f) { const unsigned u = __float_as_uint(f); return (u & 0x80000000u) ? ~u : (u | 0x80000000u); }
; #define SEL_HADD(idx_) __hip_atomic_fetch_add(&hist[(idx_)], 1u, __ATOMIC_RELAXED, __HIP_MEMORY_SCOPE_WORKGROUP)
; __device__ __forceinline__ void sel_unit(LAS char* lds, int b, int u, const bf16_t* QI, const bf16_t* KIDX, const float* WIDX, unsigned long long* MASK) {
;     ...
;             for (int kh = 0; kh < 2; ++kh) {
;             bf16x8 kf[2][2];
; #pragma unroll
;             for (int kb = 0; kb < 2; ++kb)
; #pragma unroll
;                 for (int ks = 0; ks < 2; ++ks) kf[kb][ks] = *(const bf16x8*)(KIDX + (rowbase + 64 * t + 32 * kh + 16 * kb + q16) * 64 + 32 * ks + 8 * kg);
; #pragma unroll
;             for (int kb = 0; kb < 2; ++kb) {
;                 f32x4 s = (f32x4){0.f, 0.f, 0.f, 0.f};
; #pragma unroll
;                 for (int hh = 0; hh < 8; ++hh) {
;                     f32x4 a = (f32x4){0.f, 0.f, 0.f, 0.f};
; #pragma unroll
;                     for (int ks = 0; ks < 2; ++ks) {
;                         const bf16x8 qv = *(const LAS bf16x8*)(lds + L_QI + q16 * 1024 + (((hh * 8 + 4 * ks + kg) ^ q16) << 4));
;                         a = __builtin_amdgcn_mfma_f32_16x16x32_bf16(kf[kb][ks], qv, a, 0, 0, 0);
;                     }
;                     const float wh = wl[hh * 16];
; #pragma unroll
;                     for (int i = 0; i < 4; ++i) s[i] += wh * fmaxf(a[i], 0.f);
;                 }
;                 u32x4 kk; kk.x = fkey(s[0]); kk.y = fkey(s[1]); kk.z = fkey(s[2]); kk.w = fkey(s[3]);
;                 sc[j][2 * kh + kb] = kk;
; #pragma unroll
;                 for (int i = 0; i < 4; ++i) SEL_HADD((kk[i] >> 24) * 16 + q16);
.Lp0_nopf_4:
	s_waitcnt lgkmcnt(1)
	v_mfma_f32_16x16x32_bf16 v[246:249], v[42:45], v[230:233], 0
	v_mfma_f32_16x16x32_bf16 v[250:253], v[50:53], v[230:233], 0
	v_mfma_f32_16x16x32_bf16 v[246:249], v[46:49], v[234:237], v[246:249]
	v_mfma_f32_16x16x32_bf16 v[250:253], v[2:5], v[234:237], v[250:253]
	ds_read_b128 v[238:241], v184
	ds_read_b128 v[242:245], v185
	ds_read_b32 v7, v137 offset:384
	s_waitcnt lgkmcnt(1)
	v_mfma_f32_16x16x32_bf16 v[206:209], v[42:45], v[238:241], 0
	v_mfma_f32_16x16x32_bf16 v[210:213], v[50:53], v[238:241], 0
	v_mfma_f32_16x16x32_bf16 v[206:209], v[46:49], v[242:245], v[206:209]
	v_mfma_f32_16x16x32_bf16 v[210:213], v[2:5], v[242:245], v[210:213]
	ds_read_b128 v[230:233], v179
	ds_read_b128 v[234:237], v180
	ds_read_b32 v217, v137 offset:448
	v_max_f32_e32 v9, 0, v246
	v_max_f32_e32 v200, 0, v247
	v_max_f32_e32 v201, 0, v248
	v_max_f32_e32 v216, 0, v249
	v_mul_f32_e32 v134, v6, v9
	v_mul_f32_e32 v133, v6, v200
	v_mul_f32_e32 v136, v6, v201
	v_mul_f32_e32 v135, v6, v216
	v_max_f32_e32 v9, 0, v250
	v_max_f32_e32 v200, 0, v251
	v_max_f32_e32 v201, 0, v252
	v_max_f32_e32 v216, 0, v253
	v_mul_f32_e32 v139, v6, v9
	v_mul_f32_e32 v138, v6, v200
	v_mul_f32_e32 v141, v6, v201
	v_mul_f32_e32 v140, v6, v216
	s_waitcnt lgkmcnt(1)
	v_mfma_f32_16x16x32_bf16 v[246:249], v[42:45], v[230:233], 0
	v_mfma_f32_16x16x32_bf16 v[250:253], v[50:53], v[230:233], 0
	v_mfma_f32_16x16x32_bf16 v[246:249], v[46:49], v[234:237], v[246:249]
	v_mfma_f32_16x16x32_bf16 v[250:253], v[2:5], v[234:237], v[250:253]
	ds_read_b128 v[238:241], v176
	ds_read_b128 v[242:245], v159
	ds_read_b32 v6, v137 offset:512
	v_max_f32_e32 v9, 0, v206
	v_max_f32_e32 v200, 0, v207
	v_max_f32_e32 v201, 0, v208
	v_max_f32_e32 v216, 0, v209
	v_fmac_f32_e32 v134, v7, v9
	v_fmac_f32_e32 v133, v7, v200
	v_fmac_f32_e32 v136, v7, v201
	v_fmac_f32_e32 v135, v7, v216
	v_max_f32_e32 v9, 0, v210
	v_max_f32_e32 v200, 0, v211
	v_max_f32_e32 v201, 0, v212
	v_max_f32_e32 v216, 0, v213
	v_fmac_f32_e32 v139, v7, v9
	v_fmac_f32_e32 v138, v7, v200
	v_fmac_f32_e32 v141, v7, v201
	v_fmac_f32_e32 v140, v7, v216
	s_waitcnt lgkmcnt(1)
	v_mfma_f32_16x16x32_bf16 v[206:209], v[42:45], v[238:241], 0
	v_mfma_f32_16x16x32_bf16 v[210:213], v[50:53], v[238:241], 0
	v_mfma_f32_16x16x32_bf16 v[206:209], v[46:49], v[242:245], v[206:209]
	v_mfma_f32_16x16x32_bf16 v[210:213], v[2:5], v[242:245], v[210:213]
	ds_read_b128 v[230:233], v158
	ds_read_b128 v[234:237], v157
	ds_read_b32 v7, v137 offset:576
	v_max_f32_e32 v9, 0, v246
	v_max_f32_e32 v200, 0, v247
	v_max_f32_e32 v201, 0, v248
	v_max_f32_e32 v216, 0, v249
	v_fmac_f32_e32 v134, v217, v9
	v_fmac_f32_e32 v133, v217, v200
	v_fmac_f32_e32 v136, v217, v201
	v_fmac_f32_e32 v135, v217, v216
	v_max_f32_e32 v9, 0, v250
	v_max_f32_e32 v200, 0, v251
	v_max_f32_e32 v201, 0, v252
	v_max_f32_e32 v216, 0, v253
	v_fmac_f32_e32 v139, v217, v9
	v_fmac_f32_e32 v138, v217, v200
	v_fmac_f32_e32 v141, v217, v201
	v_fmac_f32_e32 v140, v217, v216
	s_waitcnt lgkmcnt(1)
	v_mfma_f32_16x16x32_bf16 v[246:249], v[42:45], v[230:233], 0
	v_mfma_f32_16x16x32_bf16 v[250:253], v[50:53], v[230:233], 0
	v_mfma_f32_16x16x32_bf16 v[246:249], v[46:49], v[234:237], v[246:249]
	v_mfma_f32_16x16x32_bf16 v[250:253], v[2:5], v[234:237], v[250:253]
	ds_read_b128 v[238:241], v156
	ds_read_b128 v[242:245], v155
	ds_read_b32 v217, v137 offset:640
	v_max_f32_e32 v9, 0, v206
	v_max_f32_e32 v200, 0, v207
	v_max_f32_e32 v201, 0, v208
	v_max_f32_e32 v216, 0, v209
	v_fmac_f32_e32 v134, v6, v9
	v_fmac_f32_e32 v133, v6, v200
	v_fmac_f32_e32 v136, v6, v201
	v_fmac_f32_e32 v135, v6, v216
	v_max_f32_e32 v9, 0, v210
	v_max_f32_e32 v200, 0, v211
	v_max_f32_e32 v201, 0, v212
	v_max_f32_e32 v216, 0, v213
	v_fmac_f32_e32 v139, v6, v9
	v_fmac_f32_e32 v138, v6, v200
	v_fmac_f32_e32 v141, v6, v201
	v_fmac_f32_e32 v140, v6, v216
	s_waitcnt lgkmcnt(1)
	v_mfma_f32_16x16x32_bf16 v[206:209], v[42:45], v[238:241], 0
	v_mfma_f32_16x16x32_bf16 v[210:213], v[50:53], v[238:241], 0
	v_mfma_f32_16x16x32_bf16 v[206:209], v[46:49], v[242:245], v[206:209]
	v_mfma_f32_16x16x32_bf16 v[210:213], v[2:5], v[242:245], v[210:213]
	ds_read_b128 v[230:233], v154
	ds_read_b128 v[234:237], v153
	ds_read_b32 v6, v137 offset:704
	v_max_f32_e32 v9, 0, v246
	v_max_f32_e32 v200, 0, v247
	v_max_f32_e32 v201, 0, v248
	v_max_f32_e32 v216, 0, v249
	v_fmac_f32_e32 v134, v7, v9
	v_fmac_f32_e32 v133, v7, v200
	v_fmac_f32_e32 v136, v7, v201
	v_fmac_f32_e32 v135, v7, v216
	v_max_f32_e32 v9, 0, v250
	v_max_f32_e32 v200, 0, v251
	v_max_f32_e32 v201, 0, v252
	v_max_f32_e32 v216, 0, v253
	v_fmac_f32_e32 v139, v7, v9
	v_fmac_f32_e32 v138, v7, v200
	v_fmac_f32_e32 v141, v7, v201
	v_fmac_f32_e32 v140, v7, v216
	s_waitcnt lgkmcnt(1)
	v_mfma_f32_16x16x32_bf16 v[246:249], v[42:45], v[230:233], 0
	v_mfma_f32_16x16x32_bf16 v[250:253], v[50:53], v[230:233], 0
	v_mfma_f32_16x16x32_bf16 v[246:249], v[46:49], v[234:237], v[246:249]
	v_mfma_f32_16x16x32_bf16 v[250:253], v[2:5], v[234:237], v[250:253]
	ds_read_b128 v[238:241], v152
	ds_read_b128 v[242:245], v151
	ds_read_b32 v7, v137 offset:768
	v_max_f32_e32 v9, 0, v206
	v_max_f32_e32 v200, 0, v207
	v_max_f32_e32 v201, 0, v208
	v_max_f32_e32 v216, 0, v209
	v_fmac_f32_e32 v134, v217, v9
	v_fmac_f32_e32 v133, v217, v200
	v_fmac_f32_e32 v136, v217, v201
	v_fmac_f32_e32 v135, v217, v216
	v_max_f32_e32 v9, 0, v210
	v_max_f32_e32 v200, 0, v211
	v_max_f32_e32 v201, 0, v212
	v_max_f32_e32 v216, 0, v213
	v_fmac_f32_e32 v139, v217, v9
	v_fmac_f32_e32 v138, v217, v200
	v_fmac_f32_e32 v141, v217, v201
	v_fmac_f32_e32 v140, v217, v216
	s_waitcnt lgkmcnt(1)
; #define LAS __attribute__((address_space(3)))
; #define SEL_HADD(idx_) __hip_atomic_fetch_add(&hist[(idx_)], 1u, __ATOMIC_RELAXED, __HIP_MEMORY_SCOPE_WORKGROUP)
; __device__ __forceinline__ unsigned fkey(float f) { const unsigned u = __float_as_uint(f); return (u & 0x80000000u) ? ~u : (u | 0x80000000u); }
; __device__ __forceinline__ void sel_unit(LAS char* lds, int b, int u, const bf16_t* QI, const bf16_t* KIDX, const float* WIDX, unsigned long long* MASK) {
;     ...
;             for (int kb = 0; kb < 2; ++kb) {
;                 f32x4 s = (f32x4){0.f, 0.f, 0.f, 0.f};
; #pragma unroll
;                 for (int hh = 0; hh < 8; ++hh) {
;                     f32x4 a = (f32x4){0.f, 0.f, 0.f, 0.f};
; #pragma unroll
;                     for (int ks = 0; ks < 2; ++ks) {
;                         const bf16x8 qv = *(const LAS bf16x8*)(lds + L_QI + q16 * 1024 + (((hh * 8 + 4 * ks + kg) ^ q16) << 4));
;                         a = __builtin_amdgcn_mfma_f32_16x16x32_bf16(kf[kb][ks], qv, a, 0, 0, 0);
;                     }
;                     const float wh = wl[hh * 16];
; #pragma unroll
;                     for (int i = 0; i < 4; ++i) s[i] += wh * fmaxf(a[i], 0.f);
;                 }
;                 u32x4 kk; kk.x = fkey(s[0]); kk.y = fkey(s[1]); kk.z = fkey(s[2]); kk.w = fkey(s[3]);
;                 sc[j][2 * kh + kb] = kk;
; #pragma unroll
;                 for (int i = 0; i < 4; ++i) SEL_HADD((kk[i] >> 24) * 16 + q16);
	v_mfma_f32_16x16x32_bf16 v[206:209], v[42:45], v[238:241], 0
	v_mfma_f32_16x16x32_bf16 v[210:213], v[50:53], v[238:241], 0
	v_mfma_f32_16x16x32_bf16 v[206:209], v[46:49], v[242:245], v[206:209]
	v_mfma_f32_16x16x32_bf16 v[210:213], v[2:5], v[242:245], v[210:213]
	v_max_f32_e32 v9, 0, v246
	v_max_f32_e32 v200, 0, v247
	v_max_f32_e32 v201, 0, v248
	v_max_f32_e32 v216, 0, v249
	v_fmac_f32_e32 v134, v6, v9
	v_fmac_f32_e32 v133, v6, v200
	v_fmac_f32_e32 v136, v6, v201
	v_fmac_f32_e32 v135, v6, v216
	v_max_f32_e32 v9, 0, v250
	v_max_f32_e32 v200, 0, v251
	v_max_f32_e32 v201, 0, v252
	v_max_f32_e32 v216, 0, v253
	v_fmac_f32_e32 v139, v6, v9
	v_fmac_f32_e32 v138, v6, v200
	v_fmac_f32_e32 v141, v6, v201
	v_fmac_f32_e32 v140, v6, v216
	s_waitcnt lgkmcnt(0)
	v_max_f32_e32 v9, 0, v206
	v_max_f32_e32 v200, 0, v207
	v_max_f32_e32 v201, 0, v208
	v_max_f32_e32 v216, 0, v209
	v_fmac_f32_e32 v134, v7, v9
	v_fmac_f32_e32 v133, v7, v200
	v_fmac_f32_e32 v136, v7, v201
	v_fmac_f32_e32 v135, v7, v216
	v_max_f32_e32 v9, 0, v210
	v_max_f32_e32 v200, 0, v211
	v_max_f32_e32 v201, 0, v212
	v_max_f32_e32 v216, 0, v213
	v_fmac_f32_e32 v139, v7, v9
	v_fmac_f32_e32 v138, v7, v200
	v_fmac_f32_e32 v141, v7, v201
	v_fmac_f32_e32 v140, v7, v216
	v_ashrrev_i32_e32 v9, 31, v134
	v_bitop3_b32 v134, v9, v134, v8 bitop3:0x36
	v_ashrrev_i32_e32 v200, 31, v133
	v_bitop3_b32 v133, v200, v133, v8 bitop3:0x36
	v_ashrrev_i32_e32 v201, 31, v136
	v_bitop3_b32 v136, v201, v136, v8 bitop3:0x36
	v_ashrrev_i32_e32 v216, 31, v135
	v_bitop3_b32 v135, v216, v135, v8 bitop3:0x36
	v_ashrrev_i32_e32 v9, 31, v139
	v_bitop3_b32 v139, v9, v139, v8 bitop3:0x36
	v_ashrrev_i32_e32 v200, 31, v138
	v_bitop3_b32 v138, v200, v138, v8 bitop3:0x36
	v_ashrrev_i32_e32 v201, 31, v141
	v_bitop3_b32 v141, v201, v141, v8 bitop3:0x36
	v_ashrrev_i32_e32 v216, 31, v140
	v_bitop3_b32 v140, v216, v140, v8 bitop3:0x36
	v_lshrrev_b32_e32 v9, 24, v134
	v_lshl_add_u32 v9, v9, 6, v0
	ds_add_u32 v9, v205 offset:16384
	v_lshrrev_b32_e32 v200, 24, v133
	v_lshl_add_u32 v200, v200, 6, v0
	ds_add_u32 v200, v205 offset:16384
	v_lshrrev_b32_e32 v201, 24, v136
	v_lshl_add_u32 v201, v201, 6, v0
	ds_add_u32 v201, v205 offset:16384
	v_lshrrev_b32_e32 v216, 24, v135
	v_lshl_add_u32 v216, v216, 6, v0
	ds_add_u32 v216, v205 offset:16384
	v_lshrrev_b32_e32 v9, 24, v139
	v_lshl_add_u32 v9, v9, 6, v0
	ds_add_u32 v9, v205 offset:16384
	v_lshrrev_b32_e32 v200, 24, v138
	v_lshl_add_u32 v200, v200, 6, v0
	ds_add_u32 v200, v205 offset:16384
	v_lshrrev_b32_e32 v201, 24, v141
	v_lshl_add_u32 v201, v201, 6, v0
	ds_add_u32 v201, v205 offset:16384
	v_lshrrev_b32_e32 v216, 24, v140
	v_lshl_add_u32 v216, v216, 6, v0
	ds_add_u32 v216, v205 offset:16384
.LBB0_666:
	s_cmp_gt_i32 s4, 5
	s_cselect_b64 s[48:49], -1, 0
	s_cmp_lt_i32 s4, 6
	s_cbranch_scc1 .LBB0_668
	ds_read_b128 v[230:233], v182
	ds_read_b128 v[234:237], v183
	ds_read_b32 v6, v137 offset:320
	s_waitcnt vmcnt(0)
	v_add_co_u32_e32 v22, vcc, s96, v22
	s_nop 1
	v_addc_co_u32_e32 v23, vcc, 0, v23, vcc
	global_load_dwordx4 v[42:45], v[22:23], off
	global_load_dwordx4 v[46:49], v[22:23], off offset:64
	global_load_dwordx4 v[50:53], v[22:23], off offset:2048
	global_load_dwordx4 v[2:5], v[22:23], off offset:2112
	s_waitcnt lgkmcnt(1)
	v_mfma_f32_16x16x32_bf16 v[246:249], v[26:29], v[230:233], 0
	v_mfma_f32_16x16x32_bf16 v[250:253], v[34:37], v[230:233], 0
	v_mfma_f32_16x16x32_bf16 v[246:249], v[30:33], v[234:237], v[246:249]
	v_mfma_f32_16x16x32_bf16 v[250:253], v[38:41], v[234:237], v[250:253]
	ds_read_b128 v[238:241], v184
	ds_read_b128 v[242:245], v185
	ds_read_b32 v7, v137 offset:384
	s_waitcnt lgkmcnt(1)
	v_mfma_f32_16x16x32_bf16 v[206:209], v[26:29], v[238:241], 0
	v_mfma_f32_16x16x32_bf16 v[210:213], v[34:37], v[238:241], 0
	v_mfma_f32_16x16x32_bf16 v[206:209], v[30:33], v[242:245], v[206:209]
	v_mfma_f32_16x16x32_bf16 v[210:213], v[38:41], v[242:245], v[210:213]
	ds_read_b128 v[230:233], v179
	ds_read_b128 v[234:237], v180
	ds_read_b32 v217, v137 offset:448
	v_max_f32_e32 v9, 0, v246
	v_max_f32_e32 v200, 0, v247
	v_max_f32_e32 v201, 0, v248
	v_max_f32_e32 v216, 0, v249
	v_mul_f32_e32 v143, v6, v9
	v_mul_f32_e32 v142, v6, v200
	v_mul_f32_e32 v145, v6, v201
	v_mul_f32_e32 v144, v6, v216
	v_max_f32_e32 v9, 0, v250
	v_max_f32_e32 v200, 0, v251
	v_max_f32_e32 v201, 0, v252
	v_max_f32_e32 v216, 0, v253
	v_mul_f32_e32 v147, v6, v9
	v_mul_f32_e32 v146, v6, v200
	v_mul_f32_e32 v149, v6, v201
	v_mul_f32_e32 v148, v6, v216
	s_waitcnt lgkmcnt(1)
	v_mfma_f32_16x16x32_bf16 v[246:249], v[26:29], v[230:233], 0
	v_mfma_f32_16x16x32_bf16 v[250:253], v[34:37], v[230:233], 0
	v_mfma_f32_16x16x32_bf16 v[246:249], v[30:33], v[234:237], v[246:249]
	v_mfma_f32_16x16x32_bf16 v[250:253], v[38:41], v[234:237], v[250:253]
	ds_read_b128 v[238:241], v176
	ds_read_b128 v[242:245], v159
	ds_read_b32 v6, v137 offset:512
	v_max_f32_e32 v9, 0, v206
	v_max_f32_e32 v200, 0, v207
	v_max_f32_e32 v201, 0, v208
	v_max_f32_e32 v216, 0, v209
	v_fmac_f32_e32 v143, v7, v9
	v_fmac_f32_e32 v142, v7, v200
	v_fmac_f32_e32 v145, v7, v201
	v_fmac_f32_e32 v144, v7, v216
	v_max_f32_e32 v9, 0, v210
	v_max_f32_e32 v200, 0, v211
	v_max_f32_e32 v201, 0, v212
	v_max_f32_e32 v216, 0, v213
	v_fmac_f32_e32 v147, v7, v9
	v_fmac_f32_e32 v146, v7, v200
	v_fmac_f32_e32 v149, v7, v201
	v_fmac_f32_e32 v148, v7, v216
	s_waitcnt lgkmcnt(1)
; #define LAS __attribute__((address_space(3)))
; #define SEL_HADD(idx_) __hip_atomic_fetch_add(&hist[(idx_)], 1u, __ATOMIC_RELAXED, __HIP_MEMORY_SCOPE_WORKGROUP)
; __device__ __forceinline__ unsigned fkey(float f) { const unsigned u = __float_as_uint(f); return (u & 0x80000000u) ? ~u : (u | 0x80000000u); }
; __device__ __forceinline__ void sel_unit(LAS char* lds, int b, int u, const bf16_t* QI, const bf16_t* KIDX, const float* WIDX, unsigned long long* MASK) {
;     ...
;             for (int kb = 0; kb < 2; ++kb) {
;                 f32x4 s = (f32x4){0.f, 0.f, 0.f, 0.f};
; #pragma unroll
;                 for (int hh = 0; hh < 8; ++hh) {
;                     f32x4 a = (f32x4){0.f, 0.f, 0.f, 0.f};
; #pragma unroll
;                     for (int ks = 0; ks < 2; ++ks) {
;                         const bf16x8 qv = *(const LAS bf16x8*)(lds + L_QI + q16 * 1024 + (((hh * 8 + 4 * ks + kg) ^ q16) << 4));
;                         a = __builtin_amdgcn_mfma_f32_16x16x32_bf16(kf[kb][ks], qv, a, 0, 0, 0);
;                     }
;                     const float wh = wl[hh * 16];
; #pragma unroll
;                     for (int i = 0; i < 4; ++i) s[i] += wh * fmaxf(a[i], 0.f);
;                 }
;                 u32x4 kk; kk.x = fkey(s[0]); kk.y = fkey(s[1]); kk.z = fkey(s[2]); kk.w = fkey(s[3]);
;                 sc[j][2 * kh + kb] = kk;
; #pragma unroll
;                 for (int i = 0; i < 4; ++i) SEL_HADD((kk[i] >> 24) * 16 + q16);
	v_mfma_f32_16x16x32_bf16 v[206:209], v[26:29], v[238:241], 0
	v_mfma_f32_16x16x32_bf16 v[210:213], v[34:37], v[238:241], 0
	v_mfma_f32_16x16x32_bf16 v[206:209], v[30:33], v[242:245], v[206:209]
	v_mfma_f32_16x16x32_bf16 v[210:213], v[38:41], v[242:245], v[210:213]
	ds_read_b128 v[230:233], v158
	ds_read_b128 v[234:237], v157
	ds_read_b32 v7, v137 offset:576
	v_max_f32_e32 v9, 0, v246
	v_max_f32_e32 v200, 0, v247
	v_max_f32_e32 v201, 0, v248
	v_max_f32_e32 v216, 0, v249
	v_fmac_f32_e32 v143, v217, v9
	v_fmac_f32_e32 v142, v217, v200
	v_fmac_f32_e32 v145, v217, v201
	v_fmac_f32_e32 v144, v217, v216
	v_max_f32_e32 v9, 0, v250
	v_max_f32_e32 v200, 0, v251
	v_max_f32_e32 v201, 0, v252
	v_max_f32_e32 v216, 0, v253
	v_fmac_f32_e32 v147, v217, v9
	v_fmac_f32_e32 v146, v217, v200
	v_fmac_f32_e32 v149, v217, v201
	v_fmac_f32_e32 v148, v217, v216
	s_waitcnt lgkmcnt(1)
	v_mfma_f32_16x16x32_bf16 v[246:249], v[26:29], v[230:233], 0
	v_mfma_f32_16x16x32_bf16 v[250:253], v[34:37], v[230:233], 0
	v_mfma_f32_16x16x32_bf16 v[246:249], v[30:33], v[234:237], v[246:249]
	v_mfma_f32_16x16x32_bf16 v[250:253], v[38:41], v[234:237], v[250:253]
	ds_read_b128 v[238:241], v156
	ds_read_b128 v[242:245], v155
	ds_read_b32 v217, v137 offset:640
	v_max_f32_e32 v9, 0, v206
	v_max_f32_e32 v200, 0, v207
	v_max_f32_e32 v201, 0, v208
	v_max_f32_e32 v216, 0, v209
	v_fmac_f32_e32 v143, v6, v9
	v_fmac_f32_e32 v142, v6, v200
	v_fmac_f32_e32 v145, v6, v201
	v_fmac_f32_e32 v144, v6, v216
	v_max_f32_e32 v9, 0, v210
	v_max_f32_e32 v200, 0, v211
	v_max_f32_e32 v201, 0, v212
	v_max_f32_e32 v216, 0, v213
	v_fmac_f32_e32 v147, v6, v9
	v_fmac_f32_e32 v146, v6, v200
	v_fmac_f32_e32 v149, v6, v201
	v_fmac_f32_e32 v148, v6, v216
	s_waitcnt lgkmcnt(1)
	v_mfma_f32_16x16x32_bf16 v[206:209], v[26:29], v[238:241], 0
	v_mfma_f32_16x16x32_bf16 v[210:213], v[34:37], v[238:241], 0
	v_mfma_f32_16x16x32_bf16 v[206:209], v[30:33], v[242:245], v[206:209]
	v_mfma_f32_16x16x32_bf16 v[210:213], v[38:41], v[242:245], v[210:213]
	ds_read_b128 v[230:233], v154
	ds_read_b128 v[234:237], v153
	ds_read_b32 v6, v137 offset:704
	v_max_f32_e32 v9, 0, v246
	v_max_f32_e32 v200, 0, v247
	v_max_f32_e32 v201, 0, v248
	v_max_f32_e32 v216, 0, v249
	v_fmac_f32_e32 v143, v7, v9
	v_fmac_f32_e32 v142, v7, v200
	v_fmac_f32_e32 v145, v7, v201
	v_fmac_f32_e32 v144, v7, v216
	v_max_f32_e32 v9, 0, v250
	v_max_f32_e32 v200, 0, v251
	v_max_f32_e32 v201, 0, v252
	v_max_f32_e32 v216, 0, v253
	v_fmac_f32_e32 v147, v7, v9
	v_fmac_f32_e32 v146, v7, v200
	v_fmac_f32_e32 v149, v7, v201
	v_fmac_f32_e32 v148, v7, v216
	s_waitcnt lgkmcnt(1)
	v_mfma_f32_16x16x32_bf16 v[246:249], v[26:29], v[230:233], 0
	v_mfma_f32_16x16x32_bf16 v[250:253], v[34:37], v[230:233], 0
	v_mfma_f32_16x16x32_bf16 v[246:249], v[30:33], v[234:237], v[246:249]
	v_mfma_f32_16x16x32_bf16 v[250:253], v[38:41], v[234:237], v[250:253]
	ds_read_b128 v[238:241], v152
	ds_read_b128 v[242:245], v151
	ds_read_b32 v7, v137 offset:768
	v_max_f32_e32 v9, 0, v206
	v_max_f32_e32 v200, 0, v207
	v_max_f32_e32 v201, 0, v208
	v_max_f32_e32 v216, 0, v209
	v_fmac_f32_e32 v143, v217, v9
	v_fmac_f32_e32 v142, v217, v200
	v_fmac_f32_e32 v145, v217, v201
	v_fmac_f32_e32 v144, v217, v216
	v_max_f32_e32 v9, 0, v210
	v_max_f32_e32 v200, 0, v211
	v_max_f32_e32 v201, 0, v212
	v_max_f32_e32 v216, 0, v213
	v_fmac_f32_e32 v147, v217, v9
	v_fmac_f32_e32 v146, v217, v200
	v_fmac_f32_e32 v149, v217, v201
	v_fmac_f32_e32 v148, v217, v216
	s_waitcnt lgkmcnt(1)
	v_mfma_f32_16x16x32_bf16 v[206:209], v[26:29], v[238:241], 0
	v_mfma_f32_16x16x32_bf16 v[210:213], v[34:37], v[238:241], 0
	v_mfma_f32_16x16x32_bf16 v[206:209], v[30:33], v[242:245], v[206:209]
	v_mfma_f32_16x16x32_bf16 v[210:213], v[38:41], v[242:245], v[210:213]
	v_max_f32_e32 v9, 0, v246
	v_max_f32_e32 v200, 0, v247
	v_max_f32_e32 v201, 0, v248
	v_max_f32_e32 v216, 0, v249
	v_fmac_f32_e32 v143, v6, v9
	v_fmac_f32_e32 v142, v6, v200
	v_fmac_f32_e32 v145, v6, v201
	v_fmac_f32_e32 v144, v6, v216
	v_max_f32_e32 v9, 0, v250
	v_max_f32_e32 v200, 0, v251
	v_max_f32_e32 v201, 0, v252
	v_max_f32_e32 v216, 0, v253
	v_fmac_f32_e32 v147, v6, v9
	v_fmac_f32_e32 v146, v6, v200
	v_fmac_f32_e32 v149, v6, v201
	v_fmac_f32_e32 v148, v6, v216
	s_waitcnt lgkmcnt(0)
	v_max_f32_e32 v9, 0, v206
	v_max_f32_e32 v200, 0, v207
	v_max_f32_e32 v201, 0, v208
	v_max_f32_e32 v216, 0, v209
	v_fmac_f32_e32 v143, v7, v9
	v_fmac_f32_e32 v142, v7, v200
	v_fmac_f32_e32 v145, v7, v201
	v_fmac_f32_e32 v144, v7, v216
	v_max_f32_e32 v9, 0, v210
	v_max_f32_e32 v200, 0, v211
	v_max_f32_e32 v201, 0, v212
	v_max_f32_e32 v216, 0, v213
	v_fmac_f32_e32 v147, v7, v9
	v_fmac_f32_e32 v146, v7, v200
	v_fmac_f32_e32 v149, v7, v201
	v_fmac_f32_e32 v148, v7, v216
	v_ashrrev_i32_e32 v9, 31, v143
	v_bitop3_b32 v143, v9, v143, v8 bitop3:0x36
	v_ashrrev_i32_e32 v200, 31, v142
	v_bitop3_b32 v142, v200, v142, v8 bitop3:0x36
	v_ashrrev_i32_e32 v201, 31, v145
	v_bitop3_b32 v145, v201, v145, v8 bitop3:0x36
	v_ashrrev_i32_e32 v216, 31, v144
	v_bitop3_b32 v144, v216, v144, v8 bitop3:0x36
	v_ashrrev_i32_e32 v9, 31, v147
	v_bitop3_b32 v147, v9, v147, v8 bitop3:0x36
	v_ashrrev_i32_e32 v200, 31, v146
	v_bitop3_b32 v146, v200, v146, v8 bitop3:0x36
	v_ashrrev_i32_e32 v201, 31, v149
	v_bitop3_b32 v149, v201, v149, v8 bitop3:0x36
	v_ashrrev_i32_e32 v216, 31, v148
	v_bitop3_b32 v148, v216, v148, v8 bitop3:0x36
	v_lshrrev_b32_e32 v9, 24, v143
	v_lshl_add_u32 v9, v9, 6, v0
	ds_add_u32 v9, v205 offset:16384
	v_lshrrev_b32_e32 v200, 24, v142
	v_lshl_add_u32 v200, v200, 6, v0
	ds_add_u32 v200, v205 offset:16384
	v_lshrrev_b32_e32 v201, 24, v145
	v_lshl_add_u32 v201, v201, 6, v0
	ds_add_u32 v201, v205 offset:16384
	v_lshrrev_b32_e32 v216, 24, v144
	v_lshl_add_u32 v216, v216, 6, v0
	ds_add_u32 v216, v205 offset:16384
	v_lshrrev_b32_e32 v9, 24, v147
	v_lshl_add_u32 v9, v9, 6, v0
	ds_add_u32 v9, v205 offset:16384
	v_lshrrev_b32_e32 v200, 24, v146
	v_lshl_add_u32 v200, v200, 6, v0
	ds_add_u32 v200, v205 offset:16384
	v_lshrrev_b32_e32 v201, 24, v149
	v_lshl_add_u32 v201, v201, 6, v0
	ds_add_u32 v201, v205 offset:16384
	v_lshrrev_b32_e32 v216, 24, v148
	v_lshl_add_u32 v216, v216, 6, v0
	ds_add_u32 v216, v205 offset:16384
	ds_read_b128 v[230:233], v182
	ds_read_b128 v[234:237], v183
	ds_read_b32 v6, v137 offset:320
	s_waitcnt vmcnt(0)
	s_cmp_lt_i32 s4, 7
	s_cbranch_scc1 .Lp0_nopf_5
	v_add_co_u32_e32 v22, vcc, 0xf000, v22
	s_nop 1
	v_addc_co_u32_e32 v23, vcc, 0, v23, vcc
	global_load_dwordx4 v[26:29], v[22:23], off
	global_load_dwordx4 v[30:33], v[22:23], off offset:64
	global_load_dwordx4 v[34:37], v[22:23], off offset:2048
	global_load_dwordx4 v[38:41], v[22:23], off offset:2112
; #define LAS __attribute__((address_space(3)))
; __device__ __forceinline__ unsigned fkey(float f) { const unsigned u = __float_as_uint(f); return (u & 0x80000000u) ? ~u : (u | 0x80000000u); }
; #define SEL_HADD(idx_) __hip_atomic_fetch_add(&hist[(idx_)], 1u, __ATOMIC_RELAXED, __HIP_MEMORY_SCOPE_WORKGROUP)
; __device__ __forceinline__ void sel_unit(LAS char* lds, int b, int u, const bf16_t* QI, const bf16_t* KIDX, const float* WIDX, unsigned long long* MASK) {
;     ...
;             for (int kh = 0; kh < 2; ++kh) {
;             bf16x8 kf[2][2];
; #pragma unroll
;             for (int kb = 0; kb < 2; ++kb)
; #pragma unroll
;                 for (int ks = 0; ks < 2; ++ks) kf[kb][ks] = *(const bf16x8*)(KIDX + (rowbase + 64 * t + 32 * kh + 16 * kb + q16) * 64 + 32 * ks + 8 * kg);
; #pragma unroll
;             for (int kb = 0; kb < 2; ++kb) {
;                 f32x4 s = (f32x4){0.f, 0.f, 0.f, 0.f};
; #pragma unroll
;                 for (int hh = 0; hh < 8; ++hh) {
;                     f32x4 a = (f32x4){0.f, 0.f, 0.f, 0.f};
; #pragma unroll
;                     for (int ks = 0; ks < 2; ++ks) {
;                         const bf16x8 qv = *(const LAS bf16x8*)(lds + L_QI + q16 * 1024 + (((hh * 8 + 4 * ks + kg) ^ q16) << 4));
;                         a = __builtin_amdgcn_mfma_f32_16x16x32_bf16(kf[kb][ks], qv, a, 0, 0, 0);
;                     }
;                     const float wh = wl[hh * 16];
; #pragma unroll
;                     for (int i = 0; i < 4; ++i) s[i] += wh * fmaxf(a[i], 0.f);
;                 }
;                 u32x4 kk; kk.x = fkey(s[0]); kk.y = fkey(s[1]); kk.z = fkey(s[2]); kk.w = fkey(s[3]);
;                 sc[j][2 * kh + kb] = kk;
; #pragma unroll
;                 for (int i = 0; i < 4; ++i) SEL_HADD((kk[i] >> 24) * 16 + q16);
.Lp0_nopf_5:
	s_waitcnt lgkmcnt(1)
	v_mfma_f32_16x16x32_bf16 v[246:249], v[42:45], v[230:233], 0
	v_mfma_f32_16x16x32_bf16 v[250:253], v[50:53], v[230:233], 0
	v_mfma_f32_16x16x32_bf16 v[246:249], v[46:49], v[234:237], v[246:249]
	v_mfma_f32_16x16x32_bf16 v[250:253], v[2:5], v[234:237], v[250:253]
	ds_read_b128 v[238:241], v184
	ds_read_b128 v[242:245], v185
	ds_read_b32 v7, v137 offset:384
	s_waitcnt lgkmcnt(1)
	v_mfma_f32_16x16x32_bf16 v[206:209], v[42:45], v[238:241], 0
	v_mfma_f32_16x16x32_bf16 v[210:213], v[50:53], v[238:241], 0
	v_mfma_f32_16x16x32_bf16 v[206:209], v[46:49], v[242:245], v[206:209]
	v_mfma_f32_16x16x32_bf16 v[210:213], v[2:5], v[242:245], v[210:213]
	ds_read_b128 v[230:233], v179
	ds_read_b128 v[234:237], v180
	ds_read_b32 v217, v137 offset:448
	v_max_f32_e32 v9, 0, v246
	v_max_f32_e32 v200, 0, v247
	v_max_f32_e32 v201, 0, v248
	v_max_f32_e32 v216, 0, v249
	v_mul_f32_e32 v178, v6, v9
	v_mul_f32_e32 v177, v6, v200
	v_mul_f32_e32 v186, v6, v201
	v_mul_f32_e32 v181, v6, v216
	v_max_f32_e32 v9, 0, v250
	v_max_f32_e32 v200, 0, v251
	v_max_f32_e32 v201, 0, v252
	v_max_f32_e32 v216, 0, v253
	v_mul_f32_e32 v188, v6, v9
	v_mul_f32_e32 v187, v6, v200
	v_mul_f32_e32 v190, v6, v201
	v_mul_f32_e32 v189, v6, v216
	s_waitcnt lgkmcnt(1)
	v_mfma_f32_16x16x32_bf16 v[246:249], v[42:45], v[230:233], 0
	v_mfma_f32_16x16x32_bf16 v[250:253], v[50:53], v[230:233], 0
	v_mfma_f32_16x16x32_bf16 v[246:249], v[46:49], v[234:237], v[246:249]
	v_mfma_f32_16x16x32_bf16 v[250:253], v[2:5], v[234:237], v[250:253]
	ds_read_b128 v[238:241], v176
	ds_read_b128 v[242:245], v159
	ds_read_b32 v6, v137 offset:512
	v_max_f32_e32 v9, 0, v206
	v_max_f32_e32 v200, 0, v207
	v_max_f32_e32 v201, 0, v208
	v_max_f32_e32 v216, 0, v209
	v_fmac_f32_e32 v178, v7, v9
	v_fmac_f32_e32 v177, v7, v200
	v_fmac_f32_e32 v186, v7, v201
	v_fmac_f32_e32 v181, v7, v216
	v_max_f32_e32 v9, 0, v210
	v_max_f32_e32 v200, 0, v211
	v_max_f32_e32 v201, 0, v212
	v_max_f32_e32 v216, 0, v213
	v_fmac_f32_e32 v188, v7, v9
	v_fmac_f32_e32 v187, v7, v200
	v_fmac_f32_e32 v190, v7, v201
	v_fmac_f32_e32 v189, v7, v216
	s_waitcnt lgkmcnt(1)
	v_mfma_f32_16x16x32_bf16 v[206:209], v[42:45], v[238:241], 0
	v_mfma_f32_16x16x32_bf16 v[210:213], v[50:53], v[238:241], 0
	v_mfma_f32_16x16x32_bf16 v[206:209], v[46:49], v[242:245], v[206:209]
	v_mfma_f32_16x16x32_bf16 v[210:213], v[2:5], v[242:245], v[210:213]
	ds_read_b128 v[230:233], v158
	ds_read_b128 v[234:237], v157
	ds_read_b32 v7, v137 offset:576
	v_max_f32_e32 v9, 0, v246
	v_max_f32_e32 v200, 0, v247
	v_max_f32_e32 v201, 0, v248
	v_max_f32_e32 v216, 0, v249
	v_fmac_f32_e32 v178, v217, v9
	v_fmac_f32_e32 v177, v217, v200
	v_fmac_f32_e32 v186, v217, v201
	v_fmac_f32_e32 v181, v217, v216
	v_max_f32_e32 v9, 0, v250
	v_max_f32_e32 v200, 0, v251
	v_max_f32_e32 v201, 0, v252
	v_max_f32_e32 v216, 0, v253
	v_fmac_f32_e32 v188, v217, v9
	v_fmac_f32_e32 v187, v217, v200
	v_fmac_f32_e32 v190, v217, v201
	v_fmac_f32_e32 v189, v217, v216
	s_waitcnt lgkmcnt(1)
	v_mfma_f32_16x16x32_bf16 v[246:249], v[42:45], v[230:233], 0
	v_mfma_f32_16x16x32_bf16 v[250:253], v[50:53], v[230:233], 0
	v_mfma_f32_16x16x32_bf16 v[246:249], v[46:49], v[234:237], v[246:249]
	v_mfma_f32_16x16x32_bf16 v[250:253], v[2:5], v[234:237], v[250:253]
	ds_read_b128 v[238:241], v156
	ds_read_b128 v[242:245], v155
	ds_read_b32 v217, v137 offset:640
	v_max_f32_e32 v9, 0, v206
	v_max_f32_e32 v200, 0, v207
	v_max_f32_e32 v201, 0, v208
	v_max_f32_e32 v216, 0, v209
	v_fmac_f32_e32 v178, v6, v9
	v_fmac_f32_e32 v177, v6, v200
	v_fmac_f32_e32 v186, v6, v201
	v_fmac_f32_e32 v181, v6, v216
	v_max_f32_e32 v9, 0, v210
	v_max_f32_e32 v200, 0, v211
	v_max_f32_e32 v201, 0, v212
	v_max_f32_e32 v216, 0, v213
	v_fmac_f32_e32 v188, v6, v9
	v_fmac_f32_e32 v187, v6, v200
	v_fmac_f32_e32 v190, v6, v201
	v_fmac_f32_e32 v189, v6, v216
	s_waitcnt lgkmcnt(1)
	v_mfma_f32_16x16x32_bf16 v[206:209], v[42:45], v[238:241], 0
	v_mfma_f32_16x16x32_bf16 v[210:213], v[50:53], v[238:241], 0
	v_mfma_f32_16x16x32_bf16 v[206:209], v[46:49], v[242:245], v[206:209]
	v_mfma_f32_16x16x32_bf16 v[210:213], v[2:5], v[242:245], v[210:213]
	ds_read_b128 v[230:233], v154
	ds_read_b128 v[234:237], v153
	ds_read_b32 v6, v137 offset:704
	v_max_f32_e32 v9, 0, v246
	v_max_f32_e32 v200, 0, v247
	v_max_f32_e32 v201, 0, v248
	v_max_f32_e32 v216, 0, v249
	v_fmac_f32_e32 v178, v7, v9
	v_fmac_f32_e32 v177, v7, v200
	v_fmac_f32_e32 v186, v7, v201
	v_fmac_f32_e32 v181, v7, v216
	v_max_f32_e32 v9, 0, v250
	v_max_f32_e32 v200, 0, v251
	v_max_f32_e32 v201, 0, v252
	v_max_f32_e32 v216, 0, v253
	v_fmac_f32_e32 v188, v7, v9
	v_fmac_f32_e32 v187, v7, v200
	v_fmac_f32_e32 v190, v7, v201
	v_fmac_f32_e32 v189, v7, v216
	s_waitcnt lgkmcnt(1)
	v_mfma_f32_16x16x32_bf16 v[246:249], v[42:45], v[230:233], 0
	v_mfma_f32_16x16x32_bf16 v[250:253], v[50:53], v[230:233], 0
	v_mfma_f32_16x16x32_bf16 v[246:249], v[46:49], v[234:237], v[246:249]
	v_mfma_f32_16x16x32_bf16 v[250:253], v[2:5], v[234:237], v[250:253]
	ds_read_b128 v[238:241], v152
	ds_read_b128 v[242:245], v151
	ds_read_b32 v7, v137 offset:768
	v_max_f32_e32 v9, 0, v206
	v_max_f32_e32 v200, 0, v207
	v_max_f32_e32 v201, 0, v208
	v_max_f32_e32 v216, 0, v209
	v_fmac_f32_e32 v178, v217, v9
	v_fmac_f32_e32 v177, v217, v200
	v_fmac_f32_e32 v186, v217, v201
	v_fmac_f32_e32 v181, v217, v216
	v_max_f32_e32 v9, 0, v210
	v_max_f32_e32 v200, 0, v211
	v_max_f32_e32 v201, 0, v212
	v_max_f32_e32 v216, 0, v213
	v_fmac_f32_e32 v188, v217, v9
	v_fmac_f32_e32 v187, v217, v200
	v_fmac_f32_e32 v190, v217, v201
	v_fmac_f32_e32 v189, v217, v216
	s_waitcnt lgkmcnt(1)
; #define LAS __attribute__((address_space(3)))
; #define SEL_HADD(idx_) __hip_atomic_fetch_add(&hist[(idx_)], 1u, __ATOMIC_RELAXED, __HIP_MEMORY_SCOPE_WORKGROUP)
; __device__ __forceinline__ unsigned fkey(float f) { const unsigned u = __float_as_uint(f); return (u & 0x80000000u) ? ~u : (u | 0x80000000u); }
; __device__ __forceinline__ void sel_unit(LAS char* lds, int b, int u, const bf16_t* QI, const bf16_t* KIDX, const float* WIDX, unsigned long long* MASK) {
;     ...
;             for (int kb = 0; kb < 2; ++kb) {
;                 f32x4 s = (f32x4){0.f, 0.f, 0.f, 0.f};
; #pragma unroll
;                 for (int hh = 0; hh < 8; ++hh) {
;                     f32x4 a = (f32x4){0.f, 0.f, 0.f, 0.f};
; #pragma unroll
;                     for (int ks = 0; ks < 2; ++ks) {
;                         const bf16x8 qv = *(const LAS bf16x8*)(lds + L_QI + q16 * 1024 + (((hh * 8 + 4 * ks + kg) ^ q16) << 4));
;                         a = __builtin_amdgcn_mfma_f32_16x16x32_bf16(kf[kb][ks], qv, a, 0, 0, 0);
;                     }
;                     const float wh = wl[hh * 16];
; #pragma unroll
;                     for (int i = 0; i < 4; ++i) s[i] += wh * fmaxf(a[i], 0.f);
;                 }
;                 u32x4 kk; kk.x = fkey(s[0]); kk.y = fkey(s[1]); kk.z = fkey(s[2]); kk.w = fkey(s[3]);
;                 sc[j][2 * kh + kb] = kk;
; #pragma unroll
;                 for (int i = 0; i < 4; ++i) SEL_HADD((kk[i] >> 24) * 16 + q16);
	v_mfma_f32_16x16x32_bf16 v[206:209], v[42:45], v[238:241], 0
	v_mfma_f32_16x16x32_bf16 v[210:213], v[50:53], v[238:241], 0
	v_mfma_f32_16x16x32_bf16 v[206:209], v[46:49], v[242:245], v[206:209]
	v_mfma_f32_16x16x32_bf16 v[210:213], v[2:5], v[242:245], v[210:213]
	v_max_f32_e32 v9, 0, v246
	v_max_f32_e32 v200, 0, v247
	v_max_f32_e32 v201, 0, v248
	v_max_f32_e32 v216, 0, v249
	v_fmac_f32_e32 v178, v6, v9
	v_fmac_f32_e32 v177, v6, v200
	v_fmac_f32_e32 v186, v6, v201
	v_fmac_f32_e32 v181, v6, v216
	v_max_f32_e32 v9, 0, v250
	v_max_f32_e32 v200, 0, v251
	v_max_f32_e32 v201, 0, v252
	v_max_f32_e32 v216, 0, v253
	v_fmac_f32_e32 v188, v6, v9
	v_fmac_f32_e32 v187, v6, v200
	v_fmac_f32_e32 v190, v6, v201
	v_fmac_f32_e32 v189, v6, v216
	s_waitcnt lgkmcnt(0)
	v_max_f32_e32 v9, 0, v206
	v_max_f32_e32 v200, 0, v207
	v_max_f32_e32 v201, 0, v208
	v_max_f32_e32 v216, 0, v209
	v_fmac_f32_e32 v178, v7, v9
	v_fmac_f32_e32 v177, v7, v200
	v_fmac_f32_e32 v186, v7, v201
	v_fmac_f32_e32 v181, v7, v216
	v_max_f32_e32 v9, 0, v210
	v_max_f32_e32 v200, 0, v211
	v_max_f32_e32 v201, 0, v212
	v_max_f32_e32 v216, 0, v213
	v_fmac_f32_e32 v188, v7, v9
	v_fmac_f32_e32 v187, v7, v200
	v_fmac_f32_e32 v190, v7, v201
	v_fmac_f32_e32 v189, v7, v216
	v_ashrrev_i32_e32 v9, 31, v178
	v_bitop3_b32 v178, v9, v178, v8 bitop3:0x36
	v_ashrrev_i32_e32 v200, 31, v177
	v_bitop3_b32 v177, v200, v177, v8 bitop3:0x36
	v_ashrrev_i32_e32 v201, 31, v186
	v_bitop3_b32 v186, v201, v186, v8 bitop3:0x36
	v_ashrrev_i32_e32 v216, 31, v181
	v_bitop3_b32 v181, v216, v181, v8 bitop3:0x36
	v_ashrrev_i32_e32 v9, 31, v188
	v_bitop3_b32 v188, v9, v188, v8 bitop3:0x36
	v_ashrrev_i32_e32 v200, 31, v187
	v_bitop3_b32 v187, v200, v187, v8 bitop3:0x36
	v_ashrrev_i32_e32 v201, 31, v190
	v_bitop3_b32 v190, v201, v190, v8 bitop3:0x36
	v_ashrrev_i32_e32 v216, 31, v189
	v_bitop3_b32 v189, v216, v189, v8 bitop3:0x36
	v_lshrrev_b32_e32 v9, 24, v178
	v_lshl_add_u32 v9, v9, 6, v0
	ds_add_u32 v9, v205 offset:16384
	v_lshrrev_b32_e32 v200, 24, v177
	v_lshl_add_u32 v200, v200, 6, v0
	ds_add_u32 v200, v205 offset:16384
	v_lshrrev_b32_e32 v201, 24, v186
	v_lshl_add_u32 v201, v201, 6, v0
	ds_add_u32 v201, v205 offset:16384
	v_lshrrev_b32_e32 v216, 24, v181
	v_lshl_add_u32 v216, v216, 6, v0
	ds_add_u32 v216, v205 offset:16384
	v_lshrrev_b32_e32 v9, 24, v188
	v_lshl_add_u32 v9, v9, 6, v0
	ds_add_u32 v9, v205 offset:16384
	v_lshrrev_b32_e32 v200, 24, v187
	v_lshl_add_u32 v200, v200, 6, v0
	ds_add_u32 v200, v205 offset:16384
	v_lshrrev_b32_e32 v201, 24, v190
	v_lshl_add_u32 v201, v201, 6, v0
	ds_add_u32 v201, v205 offset:16384
	v_lshrrev_b32_e32 v216, 24, v189
	v_lshl_add_u32 v216, v216, 6, v0
	ds_add_u32 v216, v205 offset:16384
.LBB0_668:
	s_cmp_gt_i32 s4, 6
	s_cselect_b64 s[0:1], -1, 0
	s_cmp_lt_i32 s4, 7
	s_cbranch_scc1 .LBB0_670
	ds_read_b128 v[230:233], v182
	ds_read_b128 v[234:237], v183
	ds_read_b32 v6, v137 offset:320
	s_waitcnt vmcnt(0)
	v_add_co_u32_e32 v22, vcc, s96, v22
	s_nop 1
	v_addc_co_u32_e32 v23, vcc, 0, v23, vcc
	global_load_dwordx4 v[42:45], v[22:23], off
	global_load_dwordx4 v[46:49], v[22:23], off offset:64
	global_load_dwordx4 v[50:53], v[22:23], off offset:2048
	global_load_dwordx4 v[2:5], v[22:23], off offset:2112
	s_waitcnt lgkmcnt(1)
	v_mfma_f32_16x16x32_bf16 v[246:249], v[26:29], v[230:233], 0
	v_mfma_f32_16x16x32_bf16 v[250:253], v[34:37], v[230:233], 0
	v_mfma_f32_16x16x32_bf16 v[246:249], v[30:33], v[234:237], v[246:249]
	v_mfma_f32_16x16x32_bf16 v[250:253], v[38:41], v[234:237], v[250:253]
	ds_read_b128 v[238:241], v184
	ds_read_b128 v[242:245], v185
	ds_read_b32 v7, v137 offset:384
	s_waitcnt lgkmcnt(1)
	v_mfma_f32_16x16x32_bf16 v[206:209], v[26:29], v[238:241], 0
	v_mfma_f32_16x16x32_bf16 v[210:213], v[34:37], v[238:241], 0
	v_mfma_f32_16x16x32_bf16 v[206:209], v[30:33], v[242:245], v[206:209]
	v_mfma_f32_16x16x32_bf16 v[210:213], v[38:41], v[242:245], v[210:213]
	ds_read_b128 v[230:233], v179
	ds_read_b128 v[234:237], v180
	ds_read_b32 v217, v137 offset:448
	v_max_f32_e32 v9, 0, v246
	v_max_f32_e32 v200, 0, v247
	v_max_f32_e32 v201, 0, v248
	v_max_f32_e32 v216, 0, v249
	v_mul_f32_e32 v192, v6, v9
	v_mul_f32_e32 v191, v6, v200
	v_mul_f32_e32 v194, v6, v201
	v_mul_f32_e32 v193, v6, v216
	v_max_f32_e32 v9, 0, v250
	v_max_f32_e32 v200, 0, v251
	v_max_f32_e32 v201, 0, v252
	v_max_f32_e32 v216, 0, v253
	v_mul_f32_e32 v196, v6, v9
	v_mul_f32_e32 v195, v6, v200
	v_mul_f32_e32 v198, v6, v201
	v_mul_f32_e32 v197, v6, v216
	s_waitcnt lgkmcnt(1)
	v_mfma_f32_16x16x32_bf16 v[246:249], v[26:29], v[230:233], 0
	v_mfma_f32_16x16x32_bf16 v[250:253], v[34:37], v[230:233], 0
	v_mfma_f32_16x16x32_bf16 v[246:249], v[30:33], v[234:237], v[246:249]
	v_mfma_f32_16x16x32_bf16 v[250:253], v[38:41], v[234:237], v[250:253]
	ds_read_b128 v[238:241], v176
	ds_read_b128 v[242:245], v159
	ds_read_b32 v6, v137 offset:512
	v_max_f32_e32 v9, 0, v206
	v_max_f32_e32 v200, 0, v207
	v_max_f32_e32 v201, 0, v208
	v_max_f32_e32 v216, 0, v209
	v_fmac_f32_e32 v192, v7, v9
	v_fmac_f32_e32 v191, v7, v200
	v_fmac_f32_e32 v194, v7, v201
	v_fmac_f32_e32 v193, v7, v216
	v_max_f32_e32 v9, 0, v210
	v_max_f32_e32 v200, 0, v211
	v_max_f32_e32 v201, 0, v212
	v_max_f32_e32 v216, 0, v213
	v_fmac_f32_e32 v196, v7, v9
	v_fmac_f32_e32 v195, v7, v200
	v_fmac_f32_e32 v198, v7, v201
	v_fmac_f32_e32 v197, v7, v216
	s_waitcnt lgkmcnt(1)
; #define LAS __attribute__((address_space(3)))
; #define SEL_HADD(idx_) __hip_atomic_fetch_add(&hist[(idx_)], 1u, __ATOMIC_RELAXED, __HIP_MEMORY_SCOPE_WORKGROUP)
; __device__ __forceinline__ unsigned fkey(float f) { const unsigned u = __float_as_uint(f); return (u & 0x80000000u) ? ~u : (u | 0x80000000u); }
; __device__ __forceinline__ void sel_unit(LAS char* lds, int b, int u, const bf16_t* QI, const bf16_t* KIDX, const float* WIDX, unsigned long long* MASK) {
;     ...
;             for (int kb = 0; kb < 2; ++kb) {
;                 f32x4 s = (f32x4){0.f, 0.f, 0.f, 0.f};
; #pragma unroll
;                 for (int hh = 0; hh < 8; ++hh) {
;                     f32x4 a = (f32x4){0.f, 0.f, 0.f, 0.f};
; #pragma unroll
;                     for (int ks = 0; ks < 2; ++ks) {
;                         const bf16x8 qv = *(const LAS bf16x8*)(lds + L_QI + q16 * 1024 + (((hh * 8 + 4 * ks + kg) ^ q16) << 4));
;                         a = __builtin_amdgcn_mfma_f32_16x16x32_bf16(kf[kb][ks], qv, a, 0, 0, 0);
;                     }
;                     const float wh = wl[hh * 16];
; #pragma unroll
;                     for (int i = 0; i < 4; ++i) s[i] += wh * fmaxf(a[i], 0.f);
;                 }
;                 u32x4 kk; kk.x = fkey(s[0]); kk.y = fkey(s[1]); kk.z = fkey(s[2]); kk.w = fkey(s[3]);
;                 sc[j][2 * kh + kb] = kk;
; #pragma unroll
;                 for (int i = 0; i < 4; ++i) SEL_HADD((kk[i] >> 24) * 16 + q16);
	v_mfma_f32_16x16x32_bf16 v[206:209], v[26:29], v[238:241], 0
	v_mfma_f32_16x16x32_bf16 v[210:213], v[34:37], v[238:241], 0
	v_mfma_f32_16x16x32_bf16 v[206:209], v[30:33], v[242:245], v[206:209]
	v_mfma_f32_16x16x32_bf16 v[210:213], v[38:41], v[242:245], v[210:213]
	ds_read_b128 v[230:233], v158
	ds_read_b128 v[234:237], v157
	ds_read_b32 v7, v137 offset:576
	v_max_f32_e32 v9, 0, v246
	v_max_f32_e32 v200, 0, v247
	v_max_f32_e32 v201, 0, v248
	v_max_f32_e32 v216, 0, v249
	v_fmac_f32_e32 v192, v217, v9
	v_fmac_f32_e32 v191, v217, v200
	v_fmac_f32_e32 v194, v217, v201
	v_fmac_f32_e32 v193, v217, v216
	v_max_f32_e32 v9, 0, v250
	v_max_f32_e32 v200, 0, v251
	v_max_f32_e32 v201, 0, v252
	v_max_f32_e32 v216, 0, v253
	v_fmac_f32_e32 v196, v217, v9
	v_fmac_f32_e32 v195, v217, v200
	v_fmac_f32_e32 v198, v217, v201
	v_fmac_f32_e32 v197, v217, v216
	s_waitcnt lgkmcnt(1)
	v_mfma_f32_16x16x32_bf16 v[246:249], v[26:29], v[230:233], 0
	v_mfma_f32_16x16x32_bf16 v[250:253], v[34:37], v[230:233], 0
	v_mfma_f32_16x16x32_bf16 v[246:249], v[30:33], v[234:237], v[246:249]
	v_mfma_f32_16x16x32_bf16 v[250:253], v[38:41], v[234:237], v[250:253]
	ds_read_b128 v[238:241], v156
	ds_read_b128 v[242:245], v155
	ds_read_b32 v217, v137 offset:640
	v_max_f32_e32 v9, 0, v206
	v_max_f32_e32 v200, 0, v207
	v_max_f32_e32 v201, 0, v208
	v_max_f32_e32 v216, 0, v209
	v_fmac_f32_e32 v192, v6, v9
	v_fmac_f32_e32 v191, v6, v200
	v_fmac_f32_e32 v194, v6, v201
	v_fmac_f32_e32 v193, v6, v216
	v_max_f32_e32 v9, 0, v210
	v_max_f32_e32 v200, 0, v211
	v_max_f32_e32 v201, 0, v212
	v_max_f32_e32 v216, 0, v213
	v_fmac_f32_e32 v196, v6, v9
	v_fmac_f32_e32 v195, v6, v200
	v_fmac_f32_e32 v198, v6, v201
	v_fmac_f32_e32 v197, v6, v216
	s_waitcnt lgkmcnt(1)
	v_mfma_f32_16x16x32_bf16 v[206:209], v[26:29], v[238:241], 0
	v_mfma_f32_16x16x32_bf16 v[210:213], v[34:37], v[238:241], 0
	v_mfma_f32_16x16x32_bf16 v[206:209], v[30:33], v[242:245], v[206:209]
	v_mfma_f32_16x16x32_bf16 v[210:213], v[38:41], v[242:245], v[210:213]
	ds_read_b128 v[230:233], v154
	ds_read_b128 v[234:237], v153
	ds_read_b32 v6, v137 offset:704
	v_max_f32_e32 v9, 0, v246
	v_max_f32_e32 v200, 0, v247
	v_max_f32_e32 v201, 0, v248
	v_max_f32_e32 v216, 0, v249
	v_fmac_f32_e32 v192, v7, v9
	v_fmac_f32_e32 v191, v7, v200
	v_fmac_f32_e32 v194, v7, v201
	v_fmac_f32_e32 v193, v7, v216
	v_max_f32_e32 v9, 0, v250
	v_max_f32_e32 v200, 0, v251
	v_max_f32_e32 v201, 0, v252
	v_max_f32_e32 v216, 0, v253
	v_fmac_f32_e32 v196, v7, v9
	v_fmac_f32_e32 v195, v7, v200
	v_fmac_f32_e32 v198, v7, v201
	v_fmac_f32_e32 v197, v7, v216
	s_waitcnt lgkmcnt(1)
	v_mfma_f32_16x16x32_bf16 v[246:249], v[26:29], v[230:233], 0
	v_mfma_f32_16x16x32_bf16 v[250:253], v[34:37], v[230:233], 0
	v_mfma_f32_16x16x32_bf16 v[246:249], v[30:33], v[234:237], v[246:249]
	v_mfma_f32_16x16x32_bf16 v[250:253], v[38:41], v[234:237], v[250:253]
	ds_read_b128 v[238:241], v152
	ds_read_b128 v[242:245], v151
	ds_read_b32 v7, v137 offset:768
	v_max_f32_e32 v9, 0, v206
	v_max_f32_e32 v200, 0, v207
	v_max_f32_e32 v201, 0, v208
	v_max_f32_e32 v216, 0, v209
	v_fmac_f32_e32 v192, v217, v9
	v_fmac_f32_e32 v191, v217, v200
	v_fmac_f32_e32 v194, v217, v201
	v_fmac_f32_e32 v193, v217, v216
	v_max_f32_e32 v9, 0, v210
	v_max_f32_e32 v200, 0, v211
	v_max_f32_e32 v201, 0, v212
	v_max_f32_e32 v216, 0, v213
	v_fmac_f32_e32 v196, v217, v9
	v_fmac_f32_e32 v195, v217, v200
	v_fmac_f32_e32 v198, v217, v201
	v_fmac_f32_e32 v197, v217, v216
	s_waitcnt lgkmcnt(1)
	v_mfma_f32_16x16x32_bf16 v[206:209], v[26:29], v[238:241], 0
	v_mfma_f32_16x16x32_bf16 v[210:213], v[34:37], v[238:241], 0
	v_mfma_f32_16x16x32_bf16 v[206:209], v[30:33], v[242:245], v[206:209]
	v_mfma_f32_16x16x32_bf16 v[210:213], v[38:41], v[242:245], v[210:213]
	v_max_f32_e32 v9, 0, v246
	v_max_f32_e32 v200, 0, v247
	v_max_f32_e32 v201, 0, v248
	v_max_f32_e32 v216, 0, v249
	v_fmac_f32_e32 v192, v6, v9
	v_fmac_f32_e32 v191, v6, v200
	v_fmac_f32_e32 v194, v6, v201
	v_fmac_f32_e32 v193, v6, v216
	v_max_f32_e32 v9, 0, v250
	v_max_f32_e32 v200, 0, v251
	v_max_f32_e32 v201, 0, v252
	v_max_f32_e32 v216, 0, v253
	v_fmac_f32_e32 v196, v6, v9
	v_fmac_f32_e32 v195, v6, v200
	v_fmac_f32_e32 v198, v6, v201
	v_fmac_f32_e32 v197, v6, v216
	s_waitcnt lgkmcnt(0)
	v_max_f32_e32 v9, 0, v206
	v_max_f32_e32 v200, 0, v207
	v_max_f32_e32 v201, 0, v208
	v_max_f32_e32 v216, 0, v209
	v_fmac_f32_e32 v192, v7, v9
	v_fmac_f32_e32 v191, v7, v200
	v_fmac_f32_e32 v194, v7, v201
	v_fmac_f32_e32 v193, v7, v216
	v_max_f32_e32 v9, 0, v210
	v_max_f32_e32 v200, 0, v211
	v_max_f32_e32 v201, 0, v212
	v_max_f32_e32 v216, 0, v213
	v_fmac_f32_e32 v196, v7, v9
	v_fmac_f32_e32 v195, v7, v200
	v_fmac_f32_e32 v198, v7, v201
	v_fmac_f32_e32 v197, v7, v216
	v_ashrrev_i32_e32 v9, 31, v192
	v_bitop3_b32 v192, v9, v192, v8 bitop3:0x36
	v_ashrrev_i32_e32 v200, 31, v191
	v_bitop3_b32 v191, v200, v191, v8 bitop3:0x36
	v_ashrrev_i32_e32 v201, 31, v194
	v_bitop3_b32 v194, v201, v194, v8 bitop3:0x36
	v_ashrrev_i32_e32 v216, 31, v193
	v_bitop3_b32 v193, v216, v193, v8 bitop3:0x36
	v_ashrrev_i32_e32 v9, 31, v196
	v_bitop3_b32 v196, v9, v196, v8 bitop3:0x36
	v_ashrrev_i32_e32 v200, 31, v195
	v_bitop3_b32 v195, v200, v195, v8 bitop3:0x36
	v_ashrrev_i32_e32 v201, 31, v198
	v_bitop3_b32 v198, v201, v198, v8 bitop3:0x36
	v_ashrrev_i32_e32 v216, 31, v197
	v_bitop3_b32 v197, v216, v197, v8 bitop3:0x36
	v_lshrrev_b32_e32 v9, 24, v192
	v_lshl_add_u32 v9, v9, 6, v0
	ds_add_u32 v9, v205 offset:16384
	v_lshrrev_b32_e32 v200, 24, v191
	v_lshl_add_u32 v200, v200, 6, v0
	ds_add_u32 v200, v205 offset:16384
	v_lshrrev_b32_e32 v201, 24, v194
	v_lshl_add_u32 v201, v201, 6, v0
	ds_add_u32 v201, v205 offset:16384
	v_lshrrev_b32_e32 v216, 24, v193
	v_lshl_add_u32 v216, v216, 6, v0
	ds_add_u32 v216, v205 offset:16384
	v_lshrrev_b32_e32 v9, 24, v196
	v_lshl_add_u32 v9, v9, 6, v0
	ds_add_u32 v9, v205 offset:16384
	v_lshrrev_b32_e32 v200, 24, v195
	v_lshl_add_u32 v200, v200, 6, v0
	ds_add_u32 v200, v205 offset:16384
	v_lshrrev_b32_e32 v201, 24, v198
	v_lshl_add_u32 v201, v201, 6, v0
	ds_add_u32 v201, v205 offset:16384
	v_lshrrev_b32_e32 v216, 24, v197
	v_lshl_add_u32 v216, v216, 6, v0
	ds_add_u32 v216, v205 offset:16384
	ds_read_b128 v[230:233], v182
	ds_read_b128 v[234:237], v183
	ds_read_b32 v6, v137 offset:320
	s_waitcnt vmcnt(0)
	s_cmp_lt_i32 s4, 8
	s_cbranch_scc1 .Lp0_nopf_6
	v_add_co_u32_e32 v22, vcc, 0xf000, v22
	s_nop 1
	v_addc_co_u32_e32 v23, vcc, 0, v23, vcc
	global_load_dwordx4 v[26:29], v[22:23], off
	global_load_dwordx4 v[30:33], v[22:23], off offset:64
	global_load_dwordx4 v[34:37], v[22:23], off offset:2048
	global_load_dwordx4 v[38:41], v[22:23], off offset:2112
; #define LAS __attribute__((address_space(3)))
; __device__ __forceinline__ unsigned fkey(float f) { const unsigned u = __float_as_uint(f); return (u & 0x80000000u) ? ~u : (u | 0x80000000u); }
; #define SEL_HADD(idx_) __hip_atomic_fetch_add(&hist[(idx_)], 1u, __ATOMIC_RELAXED, __HIP_MEMORY_SCOPE_WORKGROUP)
; __device__ __forceinline__ void sel_unit(LAS char* lds, int b, int u, const bf16_t* QI, const bf16_t* KIDX, const float* WIDX, unsigned long long* MASK) {
;     ...
;             for (int kh = 0; kh < 2; ++kh) {
;             bf16x8 kf[2][2];
; #pragma unroll
;             for (int kb = 0; kb < 2; ++kb)
; #pragma unroll
;                 for (int ks = 0; ks < 2; ++ks) kf[kb][ks] = *(const bf16x8*)(KIDX + (rowbase + 64 * t + 32 * kh + 16 * kb + q16) * 64 + 32 * ks + 8 * kg);
; #pragma unroll
;             for (int kb = 0; kb < 2; ++kb) {
;                 f32x4 s = (f32x4){0.f, 0.f, 0.f, 0.f};
; #pragma unroll
;                 for (int hh = 0; hh < 8; ++hh) {
;                     f32x4 a = (f32x4){0.f, 0.f, 0.f, 0.f};
; #pragma unroll
;                     for (int ks = 0; ks < 2; ++ks) {
;                         const bf16x8 qv = *(const LAS bf16x8*)(lds + L_QI + q16 * 1024 + (((hh * 8 + 4 * ks + kg) ^ q16) << 4));
;                         a = __builtin_amdgcn_mfma_f32_16x16x32_bf16(kf[kb][ks], qv, a, 0, 0, 0);
;                     }
;                     const float wh = wl[hh * 16];
; #pragma unroll
;                     for (int i = 0; i < 4; ++i) s[i] += wh * fmaxf(a[i], 0.f);
;                 }
;                 u32x4 kk; kk.x = fkey(s[0]); kk.y = fkey(s[1]); kk.z = fkey(s[2]); kk.w = fkey(s[3]);
;                 sc[j][2 * kh + kb] = kk;
; #pragma unroll
;                 for (int i = 0; i < 4; ++i) SEL_HADD((kk[i] >> 24) * 16 + q16);
.Lp0_nopf_6:
	s_waitcnt lgkmcnt(1)
	v_mfma_f32_16x16x32_bf16 v[246:249], v[42:45], v[230:233], 0
	v_mfma_f32_16x16x32_bf16 v[250:253], v[50:53], v[230:233], 0
	v_mfma_f32_16x16x32_bf16 v[246:249], v[46:49], v[234:237], v[246:249]
	v_mfma_f32_16x16x32_bf16 v[250:253], v[2:5], v[234:237], v[250:253]
	ds_read_b128 v[238:241], v184
	ds_read_b128 v[242:245], v185
	ds_read_b32 v7, v137 offset:384
	s_waitcnt lgkmcnt(1)
	v_mfma_f32_16x16x32_bf16 v[206:209], v[42:45], v[238:241], 0
	v_mfma_f32_16x16x32_bf16 v[210:213], v[50:53], v[238:241], 0
	v_mfma_f32_16x16x32_bf16 v[206:209], v[46:49], v[242:245], v[206:209]
	v_mfma_f32_16x16x32_bf16 v[210:213], v[2:5], v[242:245], v[210:213]
	ds_read_b128 v[230:233], v179
	ds_read_b128 v[234:237], v180
	ds_read_b32 v217, v137 offset:448
	v_max_f32_e32 v9, 0, v246
	v_max_f32_e32 v200, 0, v247
	v_max_f32_e32 v201, 0, v248
	v_max_f32_e32 v216, 0, v249
	v_mul_f32_e32 v57, v6, v9
	v_mul_f32_e32 v56, v6, v200
	v_mul_f32_e32 v55, v6, v201
	v_mul_f32_e32 v54, v6, v216
	v_max_f32_e32 v9, 0, v250
	v_max_f32_e32 v200, 0, v251
	v_max_f32_e32 v201, 0, v252
	v_max_f32_e32 v216, 0, v253
	v_mul_f32_e32 v218, v6, v9
	v_mul_f32_e32 v199, v6, v200
	v_mul_f32_e32 v220, v6, v201
	v_mul_f32_e32 v219, v6, v216
	s_waitcnt lgkmcnt(1)
	v_mfma_f32_16x16x32_bf16 v[246:249], v[42:45], v[230:233], 0
	v_mfma_f32_16x16x32_bf16 v[250:253], v[50:53], v[230:233], 0
	v_mfma_f32_16x16x32_bf16 v[246:249], v[46:49], v[234:237], v[246:249]
	v_mfma_f32_16x16x32_bf16 v[250:253], v[2:5], v[234:237], v[250:253]
	ds_read_b128 v[238:241], v176
	ds_read_b128 v[242:245], v159
	ds_read_b32 v6, v137 offset:512
	v_max_f32_e32 v9, 0, v206
	v_max_f32_e32 v200, 0, v207
	v_max_f32_e32 v201, 0, v208
	v_max_f32_e32 v216, 0, v209
	v_fmac_f32_e32 v57, v7, v9
	v_fmac_f32_e32 v56, v7, v200
	v_fmac_f32_e32 v55, v7, v201
	v_fmac_f32_e32 v54, v7, v216
	v_max_f32_e32 v9, 0, v210
	v_max_f32_e32 v200, 0, v211
	v_max_f32_e32 v201, 0, v212
	v_max_f32_e32 v216, 0, v213
	v_fmac_f32_e32 v218, v7, v9
	v_fmac_f32_e32 v199, v7, v200
	v_fmac_f32_e32 v220, v7, v201
	v_fmac_f32_e32 v219, v7, v216
	s_waitcnt lgkmcnt(1)
	v_mfma_f32_16x16x32_bf16 v[206:209], v[42:45], v[238:241], 0
	v_mfma_f32_16x16x32_bf16 v[210:213], v[50:53], v[238:241], 0
	v_mfma_f32_16x16x32_bf16 v[206:209], v[46:49], v[242:245], v[206:209]
	v_mfma_f32_16x16x32_bf16 v[210:213], v[2:5], v[242:245], v[210:213]
	ds_read_b128 v[230:233], v158
	ds_read_b128 v[234:237], v157
	ds_read_b32 v7, v137 offset:576
	v_max_f32_e32 v9, 0, v246
	v_max_f32_e32 v200, 0, v247
	v_max_f32_e32 v201, 0, v248
	v_max_f32_e32 v216, 0, v249
	v_fmac_f32_e32 v57, v217, v9
	v_fmac_f32_e32 v56, v217, v200
	v_fmac_f32_e32 v55, v217, v201
	v_fmac_f32_e32 v54, v217, v216
	v_max_f32_e32 v9, 0, v250
	v_max_f32_e32 v200, 0, v251
	v_max_f32_e32 v201, 0, v252
	v_max_f32_e32 v216, 0, v253
	v_fmac_f32_e32 v218, v217, v9
	v_fmac_f32_e32 v199, v217, v200
	v_fmac_f32_e32 v220, v217, v201
	v_fmac_f32_e32 v219, v217, v216
	s_waitcnt lgkmcnt(1)
	v_mfma_f32_16x16x32_bf16 v[246:249], v[42:45], v[230:233], 0
	v_mfma_f32_16x16x32_bf16 v[250:253], v[50:53], v[230:233], 0
	v_mfma_f32_16x16x32_bf16 v[246:249], v[46:49], v[234:237], v[246:249]
	v_mfma_f32_16x16x32_bf16 v[250:253], v[2:5], v[234:237], v[250:253]
	ds_read_b128 v[238:241], v156
	ds_read_b128 v[242:245], v155
	ds_read_b32 v217, v137 offset:640
	v_max_f32_e32 v9, 0, v206
	v_max_f32_e32 v200, 0, v207
	v_max_f32_e32 v201, 0, v208
	v_max_f32_e32 v216, 0, v209
	v_fmac_f32_e32 v57, v6, v9
	v_fmac_f32_e32 v56, v6, v200
	v_fmac_f32_e32 v55, v6, v201
	v_fmac_f32_e32 v54, v6, v216
	v_max_f32_e32 v9, 0, v210
	v_max_f32_e32 v200, 0, v211
	v_max_f32_e32 v201, 0, v212
	v_max_f32_e32 v216, 0, v213
	v_fmac_f32_e32 v218, v6, v9
	v_fmac_f32_e32 v199, v6, v200
	v_fmac_f32_e32 v220, v6, v201
	v_fmac_f32_e32 v219, v6, v216
	s_waitcnt lgkmcnt(1)
	v_mfma_f32_16x16x32_bf16 v[206:209], v[42:45], v[238:241], 0
	v_mfma_f32_16x16x32_bf16 v[210:213], v[50:53], v[238:241], 0
	v_mfma_f32_16x16x32_bf16 v[206:209], v[46:49], v[242:245], v[206:209]
	v_mfma_f32_16x16x32_bf16 v[210:213], v[2:5], v[242:245], v[210:213]
	ds_read_b128 v[230:233], v154
	ds_read_b128 v[234:237], v153
	ds_read_b32 v6, v137 offset:704
	v_max_f32_e32 v9, 0, v246
	v_max_f32_e32 v200, 0, v247
	v_max_f32_e32 v201, 0, v248
	v_max_f32_e32 v216, 0, v249
	v_fmac_f32_e32 v57, v7, v9
	v_fmac_f32_e32 v56, v7, v200
	v_fmac_f32_e32 v55, v7, v201
	v_fmac_f32_e32 v54, v7, v216
	v_max_f32_e32 v9, 0, v250
	v_max_f32_e32 v200, 0, v251
	v_max_f32_e32 v201, 0, v252
	v_max_f32_e32 v216, 0, v253
	v_fmac_f32_e32 v218, v7, v9
	v_fmac_f32_e32 v199, v7, v200
	v_fmac_f32_e32 v220, v7, v201
	v_fmac_f32_e32 v219, v7, v216
	s_waitcnt lgkmcnt(1)
	v_mfma_f32_16x16x32_bf16 v[246:249], v[42:45], v[230:233], 0
	v_mfma_f32_16x16x32_bf16 v[250:253], v[50:53], v[230:233], 0
	v_mfma_f32_16x16x32_bf16 v[246:249], v[46:49], v[234:237], v[246:249]
	v_mfma_f32_16x16x32_bf16 v[250:253], v[2:5], v[234:237], v[250:253]
	ds_read_b128 v[238:241], v152
	ds_read_b128 v[242:245], v151
	ds_read_b32 v7, v137 offset:768
	v_max_f32_e32 v9, 0, v206
	v_max_f32_e32 v200, 0, v207
	v_max_f32_e32 v201, 0, v208
	v_max_f32_e32 v216, 0, v209
	v_fmac_f32_e32 v57, v217, v9
	v_fmac_f32_e32 v56, v217, v200
	v_fmac_f32_e32 v55, v217, v201
	v_fmac_f32_e32 v54, v217, v216
	v_max_f32_e32 v9, 0, v210
	v_max_f32_e32 v200, 0, v211
	v_max_f32_e32 v201, 0, v212
	v_max_f32_e32 v216, 0, v213
	v_fmac_f32_e32 v218, v217, v9
	v_fmac_f32_e32 v199, v217, v200
	v_fmac_f32_e32 v220, v217, v201
	v_fmac_f32_e32 v219, v217, v216
	s_waitcnt lgkmcnt(1)
; #define LAS __attribute__((address_space(3)))
; #define SEL_HADD(idx_) __hip_atomic_fetch_add(&hist[(idx_)], 1u, __ATOMIC_RELAXED, __HIP_MEMORY_SCOPE_WORKGROUP)
; __device__ __forceinline__ unsigned fkey(float f) { const unsigned u = __float_as_uint(f); return (u & 0x80000000u) ? ~u : (u | 0x80000000u); }
; __device__ __forceinline__ void sel_unit(LAS char* lds, int b, int u, const bf16_t* QI, const bf16_t* KIDX, const float* WIDX, unsigned long long* MASK) {
;     ...
;             for (int kb = 0; kb < 2; ++kb) {
;                 f32x4 s = (f32x4){0.f, 0.f, 0.f, 0.f};
; #pragma unroll
;                 for (int hh = 0; hh < 8; ++hh) {
;                     f32x4 a = (f32x4){0.f, 0.f, 0.f, 0.f};
; #pragma unroll
;                     for (int ks = 0; ks < 2; ++ks) {
;                         const bf16x8 qv = *(const LAS bf16x8*)(lds + L_QI + q16 * 1024 + (((hh * 8 + 4 * ks + kg) ^ q16) << 4));
;                         a = __builtin_amdgcn_mfma_f32_16x16x32_bf16(kf[kb][ks], qv, a, 0, 0, 0);
;                     }
;                     const float wh = wl[hh * 16];
; #pragma unroll
;                     for (int i = 0; i < 4; ++i) s[i] += wh * fmaxf(a[i], 0.f);
;                 }
;                 u32x4 kk; kk.x = fkey(s[0]); kk.y = fkey(s[1]); kk.z = fkey(s[2]); kk.w = fkey(s[3]);
;                 sc[j][2 * kh + kb] = kk;
; #pragma unroll
;                 for (int i = 0; i < 4; ++i) SEL_HADD((kk[i] >> 24) * 16 + q16);
	v_mfma_f32_16x16x32_bf16 v[206:209], v[42:45], v[238:241], 0
	v_mfma_f32_16x16x32_bf16 v[210:213], v[50:53], v[238:241], 0
	v_mfma_f32_16x16x32_bf16 v[206:209], v[46:49], v[242:245], v[206:209]
	v_mfma_f32_16x16x32_bf16 v[210:213], v[2:5], v[242:245], v[210:213]
	v_max_f32_e32 v9, 0, v246
	v_max_f32_e32 v200, 0, v247
	v_max_f32_e32 v201, 0, v248
	v_max_f32_e32 v216, 0, v249
	v_fmac_f32_e32 v57, v6, v9
	v_fmac_f32_e32 v56, v6, v200
	v_fmac_f32_e32 v55, v6, v201
	v_fmac_f32_e32 v54, v6, v216
	v_max_f32_e32 v9, 0, v250
	v_max_f32_e32 v200, 0, v251
	v_max_f32_e32 v201, 0, v252
	v_max_f32_e32 v216, 0, v253
	v_fmac_f32_e32 v218, v6, v9
	v_fmac_f32_e32 v199, v6, v200
	v_fmac_f32_e32 v220, v6, v201
	v_fmac_f32_e32 v219, v6, v216
	s_waitcnt lgkmcnt(0)
	v_max_f32_e32 v9, 0, v206
	v_max_f32_e32 v200, 0, v207
	v_max_f32_e32 v201, 0, v208
	v_max_f32_e32 v216, 0, v209
	v_fmac_f32_e32 v57, v7, v9
	v_fmac_f32_e32 v56, v7, v200
	v_fmac_f32_e32 v55, v7, v201
	v_fmac_f32_e32 v54, v7, v216
	v_max_f32_e32 v9, 0, v210
	v_max_f32_e32 v200, 0, v211
	v_max_f32_e32 v201, 0, v212
	v_max_f32_e32 v216, 0, v213
	v_fmac_f32_e32 v218, v7, v9
	v_fmac_f32_e32 v199, v7, v200
	v_fmac_f32_e32 v220, v7, v201
	v_fmac_f32_e32 v219, v7, v216
	v_ashrrev_i32_e32 v9, 31, v57
	v_bitop3_b32 v57, v9, v57, v8 bitop3:0x36
	v_ashrrev_i32_e32 v200, 31, v56
	v_bitop3_b32 v56, v200, v56, v8 bitop3:0x36
	v_ashrrev_i32_e32 v201, 31, v55
	v_bitop3_b32 v55, v201, v55, v8 bitop3:0x36
	v_ashrrev_i32_e32 v216, 31, v54
	v_bitop3_b32 v54, v216, v54, v8 bitop3:0x36
	v_ashrrev_i32_e32 v9, 31, v218
	v_bitop3_b32 v218, v9, v218, v8 bitop3:0x36
	v_ashrrev_i32_e32 v200, 31, v199
	v_bitop3_b32 v199, v200, v199, v8 bitop3:0x36
	v_ashrrev_i32_e32 v201, 31, v220
	v_bitop3_b32 v220, v201, v220, v8 bitop3:0x36
	v_ashrrev_i32_e32 v216, 31, v219
	v_bitop3_b32 v219, v216, v219, v8 bitop3:0x36
	v_lshrrev_b32_e32 v9, 24, v57
	v_lshl_add_u32 v9, v9, 6, v0
	ds_add_u32 v9, v205 offset:16384
	v_lshrrev_b32_e32 v200, 24, v56
	v_lshl_add_u32 v200, v200, 6, v0
	ds_add_u32 v200, v205 offset:16384
	v_lshrrev_b32_e32 v201, 24, v55
	v_lshl_add_u32 v201, v201, 6, v0
	ds_add_u32 v201, v205 offset:16384
	v_lshrrev_b32_e32 v216, 24, v54
	v_lshl_add_u32 v216, v216, 6, v0
	ds_add_u32 v216, v205 offset:16384
	v_lshrrev_b32_e32 v9, 24, v218
	v_lshl_add_u32 v9, v9, 6, v0
	ds_add_u32 v9, v205 offset:16384
	v_lshrrev_b32_e32 v200, 24, v199
	v_lshl_add_u32 v200, v200, 6, v0
	ds_add_u32 v200, v205 offset:16384
	v_lshrrev_b32_e32 v201, 24, v220
	v_lshl_add_u32 v201, v201, 6, v0
	ds_add_u32 v201, v205 offset:16384
	v_lshrrev_b32_e32 v216, 24, v219
	v_lshl_add_u32 v216, v216, 6, v0
	ds_add_u32 v216, v205 offset:16384
.LBB0_670:
	s_cmp_gt_i32 s4, 7
	s_cselect_b64 s[26:27], -1, 0
	s_cmp_lt_i32 s4, 8
	s_cbranch_scc1 .LBB0_672
	ds_read_b128 v[230:233], v182
	ds_read_b128 v[234:237], v183
	ds_read_b32 v6, v137 offset:320
	s_waitcnt vmcnt(0)
	v_add_co_u32_e32 v22, vcc, s96, v22
	s_nop 1
	v_addc_co_u32_e32 v23, vcc, 0, v23, vcc
	global_load_dwordx4 v[42:45], v[22:23], off
	global_load_dwordx4 v[46:49], v[22:23], off offset:64
	global_load_dwordx4 v[50:53], v[22:23], off offset:2048
	global_load_dwordx4 v[2:5], v[22:23], off offset:2112
	s_waitcnt lgkmcnt(1)
	v_mfma_f32_16x16x32_bf16 v[246:249], v[26:29], v[230:233], 0
	v_mfma_f32_16x16x32_bf16 v[250:253], v[34:37], v[230:233], 0
	v_mfma_f32_16x16x32_bf16 v[246:249], v[30:33], v[234:237], v[246:249]
	v_mfma_f32_16x16x32_bf16 v[250:253], v[38:41], v[234:237], v[250:253]
	ds_read_b128 v[238:241], v184
	ds_read_b128 v[242:245], v185
	ds_read_b32 v7, v137 offset:384
	s_waitcnt lgkmcnt(1)
	v_mfma_f32_16x16x32_bf16 v[206:209], v[26:29], v[238:241], 0
	v_mfma_f32_16x16x32_bf16 v[210:213], v[34:37], v[238:241], 0
	v_mfma_f32_16x16x32_bf16 v[206:209], v[30:33], v[242:245], v[206:209]
	v_mfma_f32_16x16x32_bf16 v[210:213], v[38:41], v[242:245], v[210:213]
	ds_read_b128 v[230:233], v179
	ds_read_b128 v[234:237], v180
	ds_read_b32 v217, v137 offset:448
	v_max_f32_e32 v9, 0, v246
	v_max_f32_e32 v200, 0, v247
	v_max_f32_e32 v201, 0, v248
	v_max_f32_e32 v216, 0, v249
	v_mul_f32_e32 v222, v6, v9
	v_mul_f32_e32 v221, v6, v200
	v_mul_f32_e32 v224, v6, v201
	v_mul_f32_e32 v223, v6, v216
	v_max_f32_e32 v9, 0, v250
	v_max_f32_e32 v200, 0, v251
	v_max_f32_e32 v201, 0, v252
	v_max_f32_e32 v216, 0, v253
	v_mul_f32_e32 v226, v6, v9
	v_mul_f32_e32 v225, v6, v200
	v_mul_f32_e32 v228, v6, v201
	v_mul_f32_e32 v227, v6, v216
	s_waitcnt lgkmcnt(1)
	v_mfma_f32_16x16x32_bf16 v[246:249], v[26:29], v[230:233], 0
	v_mfma_f32_16x16x32_bf16 v[250:253], v[34:37], v[230:233], 0
	v_mfma_f32_16x16x32_bf16 v[246:249], v[30:33], v[234:237], v[246:249]
	v_mfma_f32_16x16x32_bf16 v[250:253], v[38:41], v[234:237], v[250:253]
	ds_read_b128 v[238:241], v176
	ds_read_b128 v[242:245], v159
	ds_read_b32 v6, v137 offset:512
	v_max_f32_e32 v9, 0, v206
	v_max_f32_e32 v200, 0, v207
	v_max_f32_e32 v201, 0, v208
	v_max_f32_e32 v216, 0, v209
	v_fmac_f32_e32 v222, v7, v9
	v_fmac_f32_e32 v221, v7, v200
	v_fmac_f32_e32 v224, v7, v201
	v_fmac_f32_e32 v223, v7, v216
	v_max_f32_e32 v9, 0, v210
	v_max_f32_e32 v200, 0, v211
	v_max_f32_e32 v201, 0, v212
	v_max_f32_e32 v216, 0, v213
	v_fmac_f32_e32 v226, v7, v9
	v_fmac_f32_e32 v225, v7, v200
	v_fmac_f32_e32 v228, v7, v201
	v_fmac_f32_e32 v227, v7, v216
	s_waitcnt lgkmcnt(1)
; #define LAS __attribute__((address_space(3)))
; #define SEL_HADD(idx_) __hip_atomic_fetch_add(&hist[(idx_)], 1u, __ATOMIC_RELAXED, __HIP_MEMORY_SCOPE_WORKGROUP)
; __device__ __forceinline__ unsigned fkey(float f) { const unsigned u = __float_as_uint(f); return (u & 0x80000000u) ? ~u : (u | 0x80000000u); }
; __device__ __forceinline__ void sel_unit(LAS char* lds, int b, int u, const bf16_t* QI, const bf16_t* KIDX, const float* WIDX, unsigned long long* MASK) {
;     ...
;             for (int kb = 0; kb < 2; ++kb) {
;                 f32x4 s = (f32x4){0.f, 0.f, 0.f, 0.f};
; #pragma unroll
;                 for (int hh = 0; hh < 8; ++hh) {
;                     f32x4 a = (f32x4){0.f, 0.f, 0.f, 0.f};
; #pragma unroll
;                     for (int ks = 0; ks < 2; ++ks) {
;                         const bf16x8 qv = *(const LAS bf16x8*)(lds + L_QI + q16 * 1024 + (((hh * 8 + 4 * ks + kg) ^ q16) << 4));
;                         a = __builtin_amdgcn_mfma_f32_16x16x32_bf16(kf[kb][ks], qv, a, 0, 0, 0);
;                     }
;                     const float wh = wl[hh * 16];
; #pragma unroll
;                     for (int i = 0; i < 4; ++i) s[i] += wh * fmaxf(a[i], 0.f);
;                 }
;                 u32x4 kk; kk.x = fkey(s[0]); kk.y = fkey(s[1]); kk.z = fkey(s[2]); kk.w = fkey(s[3]);
;                 sc[j][2 * kh + kb] = kk;
; #pragma unroll
;                 for (int i = 0; i < 4; ++i) SEL_HADD((kk[i] >> 24) * 16 + q16);
	v_mfma_f32_16x16x32_bf16 v[206:209], v[26:29], v[238:241], 0
	v_mfma_f32_16x16x32_bf16 v[210:213], v[34:37], v[238:241], 0
	v_mfma_f32_16x16x32_bf16 v[206:209], v[30:33], v[242:245], v[206:209]
	v_mfma_f32_16x16x32_bf16 v[210:213], v[38:41], v[242:245], v[210:213]
	ds_read_b128 v[230:233], v158
	ds_read_b128 v[234:237], v157
	ds_read_b32 v7, v137 offset:576
	v_max_f32_e32 v9, 0, v246
	v_max_f32_e32 v200, 0, v247
	v_max_f32_e32 v201, 0, v248
	v_max_f32_e32 v216, 0, v249
	v_fmac_f32_e32 v222, v217, v9
	v_fmac_f32_e32 v221, v217, v200
	v_fmac_f32_e32 v224, v217, v201
	v_fmac_f32_e32 v223, v217, v216
	v_max_f32_e32 v9, 0, v250
	v_max_f32_e32 v200, 0, v251
	v_max_f32_e32 v201, 0, v252
	v_max_f32_e32 v216, 0, v253
	v_fmac_f32_e32 v226, v217, v9
	v_fmac_f32_e32 v225, v217, v200
	v_fmac_f32_e32 v228, v217, v201
	v_fmac_f32_e32 v227, v217, v216
	s_waitcnt lgkmcnt(1)
	v_mfma_f32_16x16x32_bf16 v[246:249], v[26:29], v[230:233], 0
	v_mfma_f32_16x16x32_bf16 v[250:253], v[34:37], v[230:233], 0
	v_mfma_f32_16x16x32_bf16 v[246:249], v[30:33], v[234:237], v[246:249]
	v_mfma_f32_16x16x32_bf16 v[250:253], v[38:41], v[234:237], v[250:253]
	ds_read_b128 v[238:241], v156
	ds_read_b128 v[242:245], v155
	ds_read_b32 v217, v137 offset:640
	v_max_f32_e32 v9, 0, v206
	v_max_f32_e32 v200, 0, v207
	v_max_f32_e32 v201, 0, v208
	v_max_f32_e32 v216, 0, v209
	v_fmac_f32_e32 v222, v6, v9
	v_fmac_f32_e32 v221, v6, v200
	v_fmac_f32_e32 v224, v6, v201
	v_fmac_f32_e32 v223, v6, v216
	v_max_f32_e32 v9, 0, v210
	v_max_f32_e32 v200, 0, v211
	v_max_f32_e32 v201, 0, v212
	v_max_f32_e32 v216, 0, v213
	v_fmac_f32_e32 v226, v6, v9
	v_fmac_f32_e32 v225, v6, v200
	v_fmac_f32_e32 v228, v6, v201
	v_fmac_f32_e32 v227, v6, v216
	s_waitcnt lgkmcnt(1)
	v_mfma_f32_16x16x32_bf16 v[206:209], v[26:29], v[238:241], 0
	v_mfma_f32_16x16x32_bf16 v[210:213], v[34:37], v[238:241], 0
	v_mfma_f32_16x16x32_bf16 v[206:209], v[30:33], v[242:245], v[206:209]
	v_mfma_f32_16x16x32_bf16 v[210:213], v[38:41], v[242:245], v[210:213]
	ds_read_b128 v[230:233], v154
	ds_read_b128 v[234:237], v153
	ds_read_b32 v6, v137 offset:704
	v_max_f32_e32 v9, 0, v246
	v_max_f32_e32 v200, 0, v247
	v_max_f32_e32 v201, 0, v248
	v_max_f32_e32 v216, 0, v249
	v_fmac_f32_e32 v222, v7, v9
	v_fmac_f32_e32 v221, v7, v200
	v_fmac_f32_e32 v224, v7, v201
	v_fmac_f32_e32 v223, v7, v216
	v_max_f32_e32 v9, 0, v250
	v_max_f32_e32 v200, 0, v251
	v_max_f32_e32 v201, 0, v252
	v_max_f32_e32 v216, 0, v253
	v_fmac_f32_e32 v226, v7, v9
	v_fmac_f32_e32 v225, v7, v200
	v_fmac_f32_e32 v228, v7, v201
	v_fmac_f32_e32 v227, v7, v216
	s_waitcnt lgkmcnt(1)
	v_mfma_f32_16x16x32_bf16 v[246:249], v[26:29], v[230:233], 0
	v_mfma_f32_16x16x32_bf16 v[250:253], v[34:37], v[230:233], 0
	v_mfma_f32_16x16x32_bf16 v[246:249], v[30:33], v[234:237], v[246:249]
	v_mfma_f32_16x16x32_bf16 v[250:253], v[38:41], v[234:237], v[250:253]
	ds_read_b128 v[238:241], v152
	ds_read_b128 v[242:245], v151
	ds_read_b32 v7, v137 offset:768
	v_max_f32_e32 v9, 0, v206
	v_max_f32_e32 v200, 0, v207
	v_max_f32_e32 v201, 0, v208
	v_max_f32_e32 v216, 0, v209
	v_fmac_f32_e32 v222, v217, v9
	v_fmac_f32_e32 v221, v217, v200
	v_fmac_f32_e32 v224, v217, v201
	v_fmac_f32_e32 v223, v217, v216
	v_max_f32_e32 v9, 0, v210
	v_max_f32_e32 v200, 0, v211
	v_max_f32_e32 v201, 0, v212
	v_max_f32_e32 v216, 0, v213
	v_fmac_f32_e32 v226, v217, v9
	v_fmac_f32_e32 v225, v217, v200
	v_fmac_f32_e32 v228, v217, v201
	v_fmac_f32_e32 v227, v217, v216
	s_waitcnt lgkmcnt(1)
	v_mfma_f32_16x16x32_bf16 v[206:209], v[26:29], v[238:241], 0
	v_mfma_f32_16x16x32_bf16 v[210:213], v[34:37], v[238:241], 0
	v_mfma_f32_16x16x32_bf16 v[206:209], v[30:33], v[242:245], v[206:209]
	v_mfma_f32_16x16x32_bf16 v[210:213], v[38:41], v[242:245], v[210:213]
	v_max_f32_e32 v9, 0, v246
	v_max_f32_e32 v200, 0, v247
	v_max_f32_e32 v201, 0, v248
	v_max_f32_e32 v216, 0, v249
	v_fmac_f32_e32 v222, v6, v9
	v_fmac_f32_e32 v221, v6, v200
	v_fmac_f32_e32 v224, v6, v201
	v_fmac_f32_e32 v223, v6, v216
	v_max_f32_e32 v9, 0, v250
	v_max_f32_e32 v200, 0, v251
	v_max_f32_e32 v201, 0, v252
	v_max_f32_e32 v216, 0, v253
	v_fmac_f32_e32 v226, v6, v9
	v_fmac_f32_e32 v225, v6, v200
	v_fmac_f32_e32 v228, v6, v201
	v_fmac_f32_e32 v227, v6, v216
	s_waitcnt lgkmcnt(0)
	v_max_f32_e32 v9, 0, v206
	v_max_f32_e32 v200, 0, v207
	v_max_f32_e32 v201, 0, v208
	v_max_f32_e32 v216, 0, v209
	v_fmac_f32_e32 v222, v7, v9
	v_fmac_f32_e32 v221, v7, v200
	v_fmac_f32_e32 v224, v7, v201
	v_fmac_f32_e32 v223, v7, v216
	v_max_f32_e32 v9, 0, v210
	v_max_f32_e32 v200, 0, v211
	v_max_f32_e32 v201, 0, v212
	v_max_f32_e32 v216, 0, v213
	v_fmac_f32_e32 v226, v7, v9
	v_fmac_f32_e32 v225, v7, v200
	v_fmac_f32_e32 v228, v7, v201
	v_fmac_f32_e32 v227, v7, v216
	v_ashrrev_i32_e32 v9, 31, v222
	v_bitop3_b32 v222, v9, v222, v8 bitop3:0x36
	v_ashrrev_i32_e32 v200, 31, v221
	v_bitop3_b32 v221, v200, v221, v8 bitop3:0x36
	v_ashrrev_i32_e32 v201, 31, v224
	v_bitop3_b32 v224, v201, v224, v8 bitop3:0x36
	v_ashrrev_i32_e32 v216, 31, v223
	v_bitop3_b32 v223, v216, v223, v8 bitop3:0x36
	v_ashrrev_i32_e32 v9, 31, v226
	v_bitop3_b32 v226, v9, v226, v8 bitop3:0x36
	v_ashrrev_i32_e32 v200, 31, v225
	v_bitop3_b32 v225, v200, v225, v8 bitop3:0x36
	v_ashrrev_i32_e32 v201, 31, v228
	v_bitop3_b32 v228, v201, v228, v8 bitop3:0x36
	v_ashrrev_i32_e32 v216, 31, v227
	v_bitop3_b32 v227, v216, v227, v8 bitop3:0x36
	v_lshrrev_b32_e32 v9, 24, v222
	v_lshl_add_u32 v9, v9, 6, v0
	ds_add_u32 v9, v205 offset:16384
	v_lshrrev_b32_e32 v200, 24, v221
	v_lshl_add_u32 v200, v200, 6, v0
	ds_add_u32 v200, v205 offset:16384
	v_lshrrev_b32_e32 v201, 24, v224
	v_lshl_add_u32 v201, v201, 6, v0
	ds_add_u32 v201, v205 offset:16384
	v_lshrrev_b32_e32 v216, 24, v223
	v_lshl_add_u32 v216, v216, 6, v0
	ds_add_u32 v216, v205 offset:16384
	v_lshrrev_b32_e32 v9, 24, v226
	v_lshl_add_u32 v9, v9, 6, v0
	ds_add_u32 v9, v205 offset:16384
	v_lshrrev_b32_e32 v200, 24, v225
	v_lshl_add_u32 v200, v200, 6, v0
	ds_add_u32 v200, v205 offset:16384
	v_lshrrev_b32_e32 v201, 24, v228
	v_lshl_add_u32 v201, v201, 6, v0
	ds_add_u32 v201, v205 offset:16384
	v_lshrrev_b32_e32 v216, 24, v227
	v_lshl_add_u32 v216, v216, 6, v0
	ds_add_u32 v216, v205 offset:16384
	ds_read_b128 v[230:233], v182
	ds_read_b128 v[234:237], v183
	ds_read_b32 v6, v137 offset:320
	s_waitcnt vmcnt(0)
; #define LAS __attribute__((address_space(3)))
; __device__ __forceinline__ void sel_unit(LAS char* lds, int b, int u, const bf16_t* QI, const bf16_t* KIDX, const float* WIDX, unsigned long long* MASK) {
;     ...
;             for (int kh = 0; kh < 2; ++kh) {
;             bf16x8 kf[2][2];
; #pragma unroll
;             for (int kb = 0; kb < 2; ++kb)
; #pragma unroll
;                 for (int ks = 0; ks < 2; ++ks) kf[kb][ks] = *(const bf16x8*)(KIDX + (rowbase + 64 * t + 32 * kh + 16 * kb + q16) * 64 + 32 * ks + 8 * kg);
; #pragma unroll
;             for (int kb = 0; kb < 2; ++kb) {
;                 f32x4 s = (f32x4){0.f, 0.f, 0.f, 0.f};
; #pragma unroll
;                 for (int hh = 0; hh < 8; ++hh) {
;                     f32x4 a = (f32x4){0.f, 0.f, 0.f, 0.f};
; #pragma unroll
;                     for (int ks = 0; ks < 2; ++ks) {
;                         const bf16x8 qv = *(const LAS bf16x8*)(lds + L_QI + q16 * 1024 + (((hh * 8 + 4 * ks + kg) ^ q16) << 4));
;                         a = __builtin_amdgcn_mfma_f32_16x16x32_bf16(kf[kb][ks], qv, a, 0, 0, 0);
;                     }
;                     const float wh = wl[hh * 16];
; #pragma unroll
;                     for (int i = 0; i < 4; ++i) s[i] += wh * fmaxf(a[i], 0.f);
	s_waitcnt lgkmcnt(1)
	v_mfma_f32_16x16x32_bf16 v[246:249], v[42:45], v[230:233], 0
	v_mfma_f32_16x16x32_bf16 v[250:253], v[50:53], v[230:233], 0
	v_mfma_f32_16x16x32_bf16 v[246:249], v[46:49], v[234:237], v[246:249]
	v_mfma_f32_16x16x32_bf16 v[250:253], v[2:5], v[234:237], v[250:253]
	ds_read_b128 v[238:241], v184
	ds_read_b128 v[242:245], v185
	ds_read_b32 v7, v137 offset:384
	s_waitcnt lgkmcnt(1)
	v_mfma_f32_16x16x32_bf16 v[206:209], v[42:45], v[238:241], 0
	v_mfma_f32_16x16x32_bf16 v[210:213], v[50:53], v[238:241], 0
	v_mfma_f32_16x16x32_bf16 v[206:209], v[46:49], v[242:245], v[206:209]
	v_mfma_f32_16x16x32_bf16 v[210:213], v[2:5], v[242:245], v[210:213]
	ds_read_b128 v[230:233], v179
	ds_read_b128 v[234:237], v180
	ds_read_b32 v217, v137 offset:448
	v_max_f32_e32 v9, 0, v246
	v_max_f32_e32 v200, 0, v247
	v_max_f32_e32 v201, 0, v248
	v_max_f32_e32 v216, 0, v249
	v_mul_f32_e32 v11, v6, v9
	v_mul_f32_e32 v10, v6, v200
	v_mul_f32_e32 v13, v6, v201
	v_mul_f32_e32 v12, v6, v216
	v_max_f32_e32 v9, 0, v250
	v_max_f32_e32 v200, 0, v251
	v_max_f32_e32 v201, 0, v252
	v_max_f32_e32 v216, 0, v253
	v_mul_f32_e32 v15, v6, v9
	v_mul_f32_e32 v14, v6, v200
	v_mul_f32_e32 v17, v6, v201
	v_mul_f32_e32 v16, v6, v216
	s_waitcnt lgkmcnt(1)
	v_mfma_f32_16x16x32_bf16 v[246:249], v[42:45], v[230:233], 0
	v_mfma_f32_16x16x32_bf16 v[250:253], v[50:53], v[230:233], 0
	v_mfma_f32_16x16x32_bf16 v[246:249], v[46:49], v[234:237], v[246:249]
	v_mfma_f32_16x16x32_bf16 v[250:253], v[2:5], v[234:237], v[250:253]
	ds_read_b128 v[238:241], v176
	ds_read_b128 v[242:245], v159
	ds_read_b32 v6, v137 offset:512
	v_max_f32_e32 v9, 0, v206
	v_max_f32_e32 v200, 0, v207
	v_max_f32_e32 v201, 0, v208
	v_max_f32_e32 v216, 0, v209
	v_fmac_f32_e32 v11, v7, v9
	v_fmac_f32_e32 v10, v7, v200
	v_fmac_f32_e32 v13, v7, v201
	v_fmac_f32_e32 v12, v7, v216
	v_max_f32_e32 v9, 0, v210
	v_max_f32_e32 v200, 0, v211
	v_max_f32_e32 v201, 0, v212
	v_max_f32_e32 v216, 0, v213
	v_fmac_f32_e32 v15, v7, v9
	v_fmac_f32_e32 v14, v7, v200
	v_fmac_f32_e32 v17, v7, v201
	v_fmac_f32_e32 v16, v7, v216
	s_waitcnt lgkmcnt(1)
	v_mfma_f32_16x16x32_bf16 v[206:209], v[42:45], v[238:241], 0
	v_mfma_f32_16x16x32_bf16 v[210:213], v[50:53], v[238:241], 0
	v_mfma_f32_16x16x32_bf16 v[206:209], v[46:49], v[242:245], v[206:209]
	v_mfma_f32_16x16x32_bf16 v[210:213], v[2:5], v[242:245], v[210:213]
	ds_read_b128 v[230:233], v158
	ds_read_b128 v[234:237], v157
	ds_read_b32 v7, v137 offset:576
	v_max_f32_e32 v9, 0, v246
	v_max_f32_e32 v200, 0, v247
	v_max_f32_e32 v201, 0, v248
	v_max_f32_e32 v216, 0, v249
	v_fmac_f32_e32 v11, v217, v9
	v_fmac_f32_e32 v10, v217, v200
	v_fmac_f32_e32 v13, v217, v201
	v_fmac_f32_e32 v12, v217, v216
	v_max_f32_e32 v9, 0, v250
	v_max_f32_e32 v200, 0, v251
	v_max_f32_e32 v201, 0, v252
	v_max_f32_e32 v216, 0, v253
	v_fmac_f32_e32 v15, v217, v9
	v_fmac_f32_e32 v14, v217, v200
	v_fmac_f32_e32 v17, v217, v201
	v_fmac_f32_e32 v16, v217, v216
	s_waitcnt lgkmcnt(1)
	v_mfma_f32_16x16x32_bf16 v[246:249], v[42:45], v[230:233], 0
	v_mfma_f32_16x16x32_bf16 v[250:253], v[50:53], v[230:233], 0
	v_mfma_f32_16x16x32_bf16 v[246:249], v[46:49], v[234:237], v[246:249]
	v_mfma_f32_16x16x32_bf16 v[250:253], v[2:5], v[234:237], v[250:253]
	ds_read_b128 v[238:241], v156
	ds_read_b128 v[242:245], v155
	ds_read_b32 v217, v137 offset:640
	v_max_f32_e32 v9, 0, v206
	v_max_f32_e32 v200, 0, v207
	v_max_f32_e32 v201, 0, v208
	v_max_f32_e32 v216, 0, v209
	v_fmac_f32_e32 v11, v6, v9
	v_fmac_f32_e32 v10, v6, v200
	v_fmac_f32_e32 v13, v6, v201
	v_fmac_f32_e32 v12, v6, v216
	v_max_f32_e32 v9, 0, v210
	v_max_f32_e32 v200, 0, v211
	v_max_f32_e32 v201, 0, v212
	v_max_f32_e32 v216, 0, v213
	v_fmac_f32_e32 v15, v6, v9
	v_fmac_f32_e32 v14, v6, v200
	v_fmac_f32_e32 v17, v6, v201
	v_fmac_f32_e32 v16, v6, v216
	s_waitcnt lgkmcnt(1)
; #define LAS __attribute__((address_space(3)))
; #define SEL_HADD(idx_) __hip_atomic_fetch_add(&hist[(idx_)], 1u, __ATOMIC_RELAXED, __HIP_MEMORY_SCOPE_WORKGROUP)
; __device__ __forceinline__ unsigned fkey(float f) { const unsigned u = __float_as_uint(f); return (u & 0x80000000u) ? ~u : (u | 0x80000000u); }
; __device__ __forceinline__ void sel_unit(LAS char* lds, int b, int u, const bf16_t* QI, const bf16_t* KIDX, const float* WIDX, unsigned long long* MASK) {
;     ...
;             for (int kb = 0; kb < 2; ++kb) {
;                 f32x4 s = (f32x4){0.f, 0.f, 0.f, 0.f};
; #pragma unroll
;                 for (int hh = 0; hh < 8; ++hh) {
;                     f32x4 a = (f32x4){0.f, 0.f, 0.f, 0.f};
; #pragma unroll
;                     for (int ks = 0; ks < 2; ++ks) {
;                         const bf16x8 qv = *(const LAS bf16x8*)(lds + L_QI + q16 * 1024 + (((hh * 8 + 4 * ks + kg) ^ q16) << 4));
;                         a = __builtin_amdgcn_mfma_f32_16x16x32_bf16(kf[kb][ks], qv, a, 0, 0, 0);
;                     }
;                     const float wh = wl[hh * 16];
; #pragma unroll
;                     for (int i = 0; i < 4; ++i) s[i] += wh * fmaxf(a[i], 0.f);
;                 }
;                 u32x4 kk; kk.x = fkey(s[0]); kk.y = fkey(s[1]); kk.z = fkey(s[2]); kk.w = fkey(s[3]);
;                 sc[j][2 * kh + kb] = kk;
; #pragma unroll
;                 for (int i = 0; i < 4; ++i) SEL_HADD((kk[i] >> 24) * 16 + q16);
	v_mfma_f32_16x16x32_bf16 v[206:209], v[42:45], v[238:241], 0
	v_mfma_f32_16x16x32_bf16 v[210:213], v[50:53], v[238:241], 0
	v_mfma_f32_16x16x32_bf16 v[206:209], v[46:49], v[242:245], v[206:209]
	v_mfma_f32_16x16x32_bf16 v[210:213], v[2:5], v[242:245], v[210:213]
	ds_read_b128 v[230:233], v154
	ds_read_b128 v[234:237], v153
	ds_read_b32 v6, v137 offset:704
	v_max_f32_e32 v9, 0, v246
	v_max_f32_e32 v200, 0, v247
	v_max_f32_e32 v201, 0, v248
	v_max_f32_e32 v216, 0, v249
	v_fmac_f32_e32 v11, v7, v9
	v_fmac_f32_e32 v10, v7, v200
	v_fmac_f32_e32 v13, v7, v201
	v_fmac_f32_e32 v12, v7, v216
	v_max_f32_e32 v9, 0, v250
	v_max_f32_e32 v200, 0, v251
	v_max_f32_e32 v201, 0, v252
	v_max_f32_e32 v216, 0, v253
	v_fmac_f32_e32 v15, v7, v9
	v_fmac_f32_e32 v14, v7, v200
	v_fmac_f32_e32 v17, v7, v201
	v_fmac_f32_e32 v16, v7, v216
	s_waitcnt lgkmcnt(1)
	v_mfma_f32_16x16x32_bf16 v[246:249], v[42:45], v[230:233], 0
	v_mfma_f32_16x16x32_bf16 v[250:253], v[50:53], v[230:233], 0
	v_mfma_f32_16x16x32_bf16 v[246:249], v[46:49], v[234:237], v[246:249]
	v_mfma_f32_16x16x32_bf16 v[250:253], v[2:5], v[234:237], v[250:253]
	ds_read_b128 v[238:241], v152
	ds_read_b128 v[242:245], v151
	ds_read_b32 v7, v137 offset:768
	v_max_f32_e32 v9, 0, v206
	v_max_f32_e32 v200, 0, v207
	v_max_f32_e32 v201, 0, v208
	v_max_f32_e32 v216, 0, v209
	v_fmac_f32_e32 v11, v217, v9
	v_fmac_f32_e32 v10, v217, v200
	v_fmac_f32_e32 v13, v217, v201
	v_fmac_f32_e32 v12, v217, v216
	v_max_f32_e32 v9, 0, v210
	v_max_f32_e32 v200, 0, v211
	v_max_f32_e32 v201, 0, v212
	v_max_f32_e32 v216, 0, v213
	v_fmac_f32_e32 v15, v217, v9
	v_fmac_f32_e32 v14, v217, v200
	v_fmac_f32_e32 v17, v217, v201
	v_fmac_f32_e32 v16, v217, v216
	s_waitcnt lgkmcnt(1)
	v_mfma_f32_16x16x32_bf16 v[206:209], v[42:45], v[238:241], 0
	v_mfma_f32_16x16x32_bf16 v[210:213], v[50:53], v[238:241], 0
	v_mfma_f32_16x16x32_bf16 v[206:209], v[46:49], v[242:245], v[206:209]
	v_mfma_f32_16x16x32_bf16 v[210:213], v[2:5], v[242:245], v[210:213]
	v_max_f32_e32 v9, 0, v246
	v_max_f32_e32 v200, 0, v247
	v_max_f32_e32 v201, 0, v248
	v_max_f32_e32 v216, 0, v249
	v_fmac_f32_e32 v11, v6, v9
	v_fmac_f32_e32 v10, v6, v200
	v_fmac_f32_e32 v13, v6, v201
	v_fmac_f32_e32 v12, v6, v216
	v_max_f32_e32 v9, 0, v250
	v_max_f32_e32 v200, 0, v251
	v_max_f32_e32 v201, 0, v252
	v_max_f32_e32 v216, 0, v253
	v_fmac_f32_e32 v15, v6, v9
	v_fmac_f32_e32 v14, v6, v200
	v_fmac_f32_e32 v17, v6, v201
	v_fmac_f32_e32 v16, v6, v216
	s_waitcnt lgkmcnt(0)
	v_max_f32_e32 v9, 0, v206
	v_max_f32_e32 v200, 0, v207
	v_max_f32_e32 v201, 0, v208
	v_max_f32_e32 v216, 0, v209
	v_fmac_f32_e32 v11, v7, v9
	v_fmac_f32_e32 v10, v7, v200
	v_fmac_f32_e32 v13, v7, v201
	v_fmac_f32_e32 v12, v7, v216
	v_max_f32_e32 v9, 0, v210
	v_max_f32_e32 v200, 0, v211
	v_max_f32_e32 v201, 0, v212
	v_max_f32_e32 v216, 0, v213
	v_fmac_f32_e32 v15, v7, v9
	v_fmac_f32_e32 v14, v7, v200
	v_fmac_f32_e32 v17, v7, v201
	v_fmac_f32_e32 v16, v7, v216
	v_ashrrev_i32_e32 v9, 31, v11
	v_bitop3_b32 v11, v9, v11, v8 bitop3:0x36
	v_ashrrev_i32_e32 v200, 31, v10
	v_bitop3_b32 v10, v200, v10, v8 bitop3:0x36
	v_ashrrev_i32_e32 v201, 31, v13
	v_bitop3_b32 v13, v201, v13, v8 bitop3:0x36
	v_ashrrev_i32_e32 v216, 31, v12
	v_bitop3_b32 v12, v216, v12, v8 bitop3:0x36
	v_ashrrev_i32_e32 v9, 31, v15
	v_bitop3_b32 v15, v9, v15, v8 bitop3:0x36
	v_ashrrev_i32_e32 v200, 31, v14
	v_bitop3_b32 v14, v200, v14, v8 bitop3:0x36
	v_ashrrev_i32_e32 v201, 31, v17
	v_bitop3_b32 v17, v201, v17, v8 bitop3:0x36
	v_ashrrev_i32_e32 v216, 31, v16
	v_bitop3_b32 v16, v216, v16, v8 bitop3:0x36
	v_lshrrev_b32_e32 v9, 24, v11
	v_lshl_add_u32 v9, v9, 6, v0
	ds_add_u32 v9, v205 offset:16384
	v_lshrrev_b32_e32 v200, 24, v10
	v_lshl_add_u32 v200, v200, 6, v0
	ds_add_u32 v200, v205 offset:16384
	v_lshrrev_b32_e32 v201, 24, v13
	v_lshl_add_u32 v201, v201, 6, v0
	ds_add_u32 v201, v205 offset:16384
	v_lshrrev_b32_e32 v216, 24, v12
	v_lshl_add_u32 v216, v216, 6, v0
	ds_add_u32 v216, v205 offset:16384
	v_lshrrev_b32_e32 v9, 24, v15
	v_lshl_add_u32 v9, v9, 6, v0
	ds_add_u32 v9, v205 offset:16384
	v_lshrrev_b32_e32 v200, 24, v14
	v_lshl_add_u32 v200, v200, 6, v0
	ds_add_u32 v200, v205 offset:16384
	v_lshrrev_b32_e32 v201, 24, v17
	v_lshl_add_u32 v201, v201, 6, v0
	ds_add_u32 v201, v205 offset:16384
	v_lshrrev_b32_e32 v216, 24, v16
	v_lshl_add_u32 v216, v216, 6, v0
	ds_add_u32 v216, v205 offset:16384
